# K-loop MFMA segments: removed mid-block s_setprio 0/1 pair and redundant post-barrier lgkmcnt(0) in all 14 GEMM loops (on top of v12)
# speedup vs baseline: 1.0020x; 1.0020x over previous
.LBB0_92:
	ds_read_b128 v[146:149], v143
	ds_read_b128 v[150:153], v143 offset:1024
	ds_read_b128 v[154:157], v143 offset:2048
	ds_read_b128 v[158:161], v143 offset:3072
	ds_read_b128 v[162:165], v144
	ds_read_b128 v[166:169], v144 offset:1024
	ds_read_b128 v[170:173], v144 offset:2048
	ds_read_b128 v[178:181], v144 offset:3072
	s_add_u32 s0, s28, 0xfff80080
	s_addc_u32 s1, s29, -1
	s_cmp_eq_u32 s68, 28
	s_cselect_b32 s35, s13, s1
	s_cselect_b32 s34, s63, s0
	s_cselect_b32 s31, s64, s67
	s_cselect_b32 s30, s65, s66
	v_lshl_add_u64 v[174:175], s[28:29], 0, v[136:137]
	s_add_i32 m0, s27, 0xc000
	ds_read_b128 v[182:185], v145
	ds_read_b128 v[186:189], v145 offset:1024
	ds_read_b128 v[190:193], v145 offset:2048
	ds_read_b128 v[194:197], v145 offset:3072
	ds_read_b128 v[198:201], v145 offset:4096
	ds_read_b128 v[206:209], v145 offset:5120
	ds_read_b128 v[210:213], v145 offset:6144
	ds_read_b128 v[214:217], v145 offset:7168
	global_load_lds_dwordx4 v[174:175], off
	v_lshl_add_u64 v[174:175], s[28:29], 0, v[138:139]
	s_add_i32 m0, s27, 0xe000
	s_nop 0
	global_load_lds_dwordx4 v[174:175], off
	s_waitcnt vmcnt(8)
	s_waitcnt lgkmcnt(0)
	s_barrier
	s_setprio 1
	v_mfma_f32_16x16x32_bf16 v[124:127], v[146:149], v[182:185], v[124:127]
	v_mfma_f32_16x16x32_bf16 v[120:123], v[154:157], v[182:185], v[120:123]
	v_mfma_f32_16x16x32_bf16 v[116:119], v[146:149], v[190:193], v[116:119]
	v_mfma_f32_16x16x32_bf16 v[108:111], v[154:157], v[190:193], v[108:111]
	v_mfma_f32_16x16x32_bf16 v[100:103], v[146:149], v[198:201], v[100:103]
	v_mfma_f32_16x16x32_bf16 v[92:95], v[154:157], v[198:201], v[92:95]
	v_mfma_f32_16x16x32_bf16 v[84:87], v[146:149], v[210:213], v[84:87]
	v_mfma_f32_16x16x32_bf16 v[76:79], v[154:157], v[210:213], v[76:79]
	v_mfma_f32_16x16x32_bf16 v[124:127], v[150:153], v[186:189], v[124:127]
	v_mfma_f32_16x16x32_bf16 v[120:123], v[158:161], v[186:189], v[120:123]
	v_mfma_f32_16x16x32_bf16 v[116:119], v[150:153], v[194:197], v[116:119]
	v_mfma_f32_16x16x32_bf16 v[108:111], v[158:161], v[194:197], v[108:111]
	v_mfma_f32_16x16x32_bf16 v[100:103], v[150:153], v[206:209], v[100:103]
	v_mfma_f32_16x16x32_bf16 v[92:95], v[158:161], v[206:209], v[92:95]
	v_mfma_f32_16x16x32_bf16 v[84:87], v[150:153], v[214:217], v[84:87]
	v_mfma_f32_16x16x32_bf16 v[76:79], v[158:161], v[214:217], v[76:79]
	v_mfma_f32_16x16x32_bf16 v[112:115], v[162:165], v[182:185], v[112:115]
	v_mfma_f32_16x16x32_bf16 v[104:107], v[170:173], v[182:185], v[104:107]
	v_mfma_f32_16x16x32_bf16 v[96:99], v[162:165], v[190:193], v[96:99]
	v_mfma_f32_16x16x32_bf16 v[88:91], v[170:173], v[190:193], v[88:91]
	v_mfma_f32_16x16x32_bf16 v[80:83], v[162:165], v[198:201], v[80:83]
	v_mfma_f32_16x16x32_bf16 v[72:75], v[170:173], v[198:201], v[72:75]
	v_mfma_f32_16x16x32_bf16 v[68:71], v[162:165], v[210:213], v[68:71]
	v_mfma_f32_16x16x32_bf16 v[64:67], v[170:173], v[210:213], v[64:67]
	v_mfma_f32_16x16x32_bf16 v[112:115], v[166:169], v[186:189], v[112:115]
	v_mfma_f32_16x16x32_bf16 v[104:107], v[178:181], v[186:189], v[104:107]
	v_mfma_f32_16x16x32_bf16 v[96:99], v[166:169], v[194:197], v[96:99]
	v_mfma_f32_16x16x32_bf16 v[88:91], v[178:181], v[194:197], v[88:91]
	v_mfma_f32_16x16x32_bf16 v[80:83], v[166:169], v[206:209], v[80:83]
	v_mfma_f32_16x16x32_bf16 v[72:75], v[178:181], v[206:209], v[72:75]
	v_mfma_f32_16x16x32_bf16 v[68:71], v[166:169], v[214:217], v[68:71]
	v_mfma_f32_16x16x32_bf16 v[64:67], v[178:181], v[214:217], v[64:67]
	s_setprio 0
	s_barrier
	s_add_i32 s0, s58, s48
	v_lshl_add_u64 v[174:175], s[30:31], 0, v[132:133]
	s_mov_b32 m0, s0
	ds_read_b128 v[182:185], v145 offset:16384
	ds_read_b128 v[186:189], v145 offset:17408
	ds_read_b128 v[190:193], v145 offset:18432
	ds_read_b128 v[194:197], v145 offset:19456
	ds_read_b128 v[198:201], v145 offset:20480
	ds_read_b128 v[206:209], v145 offset:21504
	ds_read_b128 v[210:213], v145 offset:22528
	ds_read_b128 v[214:217], v145 offset:23552
	global_load_lds_dwordx4 v[174:175], off
	s_add_i32 m0, s0, 0x2000
	s_add_u32 s0, s30, 0x80000
	v_lshl_add_u64 v[202:203], s[30:31], 0, v[128:129]
	s_addc_u32 s1, s31, 0
	s_add_i32 s2, s59, s48
	global_load_lds_dwordx4 v[202:203], off
	v_lshl_add_u64 v[218:219], s[0:1], 0, v[132:133]
	s_mov_b32 m0, s2
	v_lshl_add_u64 v[220:221], s[34:35], 0, v[130:131]
	global_load_lds_dwordx4 v[218:219], off
	v_lshl_add_u64 v[218:219], s[0:1], 0, v[128:129]
	s_add_i32 m0, s2, 0x2000
	s_nop 0
	global_load_lds_dwordx4 v[218:219], off
	v_lshl_add_u64 v[218:219], s[34:35], 0, v[134:135]
	s_mov_b32 m0, s27
	s_nop 0
	global_load_lds_dwordx4 v[218:219], off
	s_mov_b32 m0, s50
	s_nop 0
	global_load_lds_dwordx4 v[220:221], off
	s_waitcnt vmcnt(8)
	s_waitcnt lgkmcnt(0)
	s_barrier
	s_setprio 1
	v_mfma_f32_16x16x32_bf16 v[60:63], v[146:149], v[182:185], v[60:63]
	v_mfma_f32_16x16x32_bf16 v[56:59], v[154:157], v[182:185], v[56:59]
	v_mfma_f32_16x16x32_bf16 v[52:55], v[146:149], v[190:193], v[52:55]
	v_mfma_f32_16x16x32_bf16 v[44:47], v[154:157], v[190:193], v[44:47]
	v_mfma_f32_16x16x32_bf16 v[36:39], v[146:149], v[198:201], v[36:39]
	v_mfma_f32_16x16x32_bf16 v[28:31], v[154:157], v[198:201], v[28:31]
	v_mfma_f32_16x16x32_bf16 v[20:23], v[146:149], v[210:213], v[20:23]
	v_mfma_f32_16x16x32_bf16 v[12:15], v[154:157], v[210:213], v[12:15]
	v_mfma_f32_16x16x32_bf16 v[60:63], v[150:153], v[186:189], v[60:63]
	v_mfma_f32_16x16x32_bf16 v[56:59], v[158:161], v[186:189], v[56:59]
	v_mfma_f32_16x16x32_bf16 v[52:55], v[150:153], v[194:197], v[52:55]
	v_mfma_f32_16x16x32_bf16 v[44:47], v[158:161], v[194:197], v[44:47]
	v_mfma_f32_16x16x32_bf16 v[36:39], v[150:153], v[206:209], v[36:39]
	v_mfma_f32_16x16x32_bf16 v[28:31], v[158:161], v[206:209], v[28:31]
	v_mfma_f32_16x16x32_bf16 v[20:23], v[150:153], v[214:217], v[20:23]
	v_mfma_f32_16x16x32_bf16 v[12:15], v[158:161], v[214:217], v[12:15]
	v_mfma_f32_16x16x32_bf16 v[48:51], v[162:165], v[182:185], v[48:51]
	v_mfma_f32_16x16x32_bf16 v[40:43], v[170:173], v[182:185], v[40:43]
	v_mfma_f32_16x16x32_bf16 v[32:35], v[162:165], v[190:193], v[32:35]
	v_mfma_f32_16x16x32_bf16 v[24:27], v[170:173], v[190:193], v[24:27]
	v_mfma_f32_16x16x32_bf16 v[16:19], v[162:165], v[198:201], v[16:19]
	v_mfma_f32_16x16x32_bf16 v[8:11], v[170:173], v[198:201], v[8:11]
	v_mfma_f32_16x16x32_bf16 v[4:7], v[162:165], v[210:213], v[4:7]
	v_mfma_f32_16x16x32_bf16 v[0:3], v[170:173], v[210:213], v[0:3]
	v_mfma_f32_16x16x32_bf16 v[48:51], v[166:169], v[186:189], v[48:51]
	v_mfma_f32_16x16x32_bf16 v[40:43], v[178:181], v[186:189], v[40:43]
	v_mfma_f32_16x16x32_bf16 v[32:35], v[166:169], v[194:197], v[32:35]
	v_mfma_f32_16x16x32_bf16 v[24:27], v[178:181], v[194:197], v[24:27]
	v_mfma_f32_16x16x32_bf16 v[16:19], v[166:169], v[206:209], v[16:19]
	v_mfma_f32_16x16x32_bf16 v[8:11], v[178:181], v[206:209], v[8:11]
	v_mfma_f32_16x16x32_bf16 v[4:7], v[166:169], v[214:217], v[4:7]
	v_mfma_f32_16x16x32_bf16 v[0:3], v[178:181], v[214:217], v[0:3]
	s_setprio 0
	s_barrier
	s_add_i32 s2, 0, 0x18000
	s_add_i32 s38, 0, 0x1c000
	v_add_u32_e32 v158, s2, v142
	v_add_u32_e32 v177, s38, v142
	ds_read_b128 v[146:149], v158
	ds_read_b128 v[150:153], v158 offset:1024
	ds_read_b128 v[154:157], v158 offset:2048
	ds_read_b128 v[158:161], v158 offset:3072
	ds_read_b128 v[162:165], v177
	ds_read_b128 v[166:169], v177 offset:1024
	ds_read_b128 v[170:173], v177 offset:2048
	ds_read_b128 v[178:181], v177 offset:3072
	s_add_u32 s0, s34, 0x80000
	s_addc_u32 s1, s35, 0
	s_mov_b32 m0, s51
	v_lshl_add_u64 v[222:223], s[0:1], 0, v[134:135]
	ds_read_b128 v[182:185], v145 offset:32768
	ds_read_b128 v[186:189], v145 offset:33792
	ds_read_b128 v[190:193], v145 offset:34816
	ds_read_b128 v[194:197], v145 offset:35840
	ds_read_b128 v[198:201], v145 offset:36864
	ds_read_b128 v[206:209], v145 offset:37888
	ds_read_b128 v[210:213], v145 offset:38912
	ds_read_b128 v[214:217], v145 offset:39936
	global_load_lds_dwordx4 v[222:223], off
	v_lshl_add_u64 v[222:223], s[0:1], 0, v[130:131]
	s_mov_b32 m0, s52
	s_nop 0
	global_load_lds_dwordx4 v[222:223], off
	s_waitcnt vmcnt(8)
	s_waitcnt lgkmcnt(0)
	s_barrier
	s_setprio 1
	v_mfma_f32_16x16x32_bf16 v[124:127], v[146:149], v[182:185], v[124:127]
	v_mfma_f32_16x16x32_bf16 v[120:123], v[154:157], v[182:185], v[120:123]
	v_mfma_f32_16x16x32_bf16 v[116:119], v[146:149], v[190:193], v[116:119]
	v_mfma_f32_16x16x32_bf16 v[108:111], v[154:157], v[190:193], v[108:111]
	v_mfma_f32_16x16x32_bf16 v[100:103], v[146:149], v[198:201], v[100:103]
	v_mfma_f32_16x16x32_bf16 v[92:95], v[154:157], v[198:201], v[92:95]
	v_mfma_f32_16x16x32_bf16 v[84:87], v[146:149], v[210:213], v[84:87]
	v_mfma_f32_16x16x32_bf16 v[76:79], v[154:157], v[210:213], v[76:79]
	v_mfma_f32_16x16x32_bf16 v[124:127], v[150:153], v[186:189], v[124:127]
	v_mfma_f32_16x16x32_bf16 v[120:123], v[158:161], v[186:189], v[120:123]
	v_mfma_f32_16x16x32_bf16 v[116:119], v[150:153], v[194:197], v[116:119]
	v_mfma_f32_16x16x32_bf16 v[108:111], v[158:161], v[194:197], v[108:111]
	v_mfma_f32_16x16x32_bf16 v[100:103], v[150:153], v[206:209], v[100:103]
	v_mfma_f32_16x16x32_bf16 v[92:95], v[158:161], v[206:209], v[92:95]
	v_mfma_f32_16x16x32_bf16 v[84:87], v[150:153], v[214:217], v[84:87]
	v_mfma_f32_16x16x32_bf16 v[76:79], v[158:161], v[214:217], v[76:79]
	v_mfma_f32_16x16x32_bf16 v[112:115], v[162:165], v[182:185], v[112:115]
	v_mfma_f32_16x16x32_bf16 v[104:107], v[170:173], v[182:185], v[104:107]
	v_mfma_f32_16x16x32_bf16 v[96:99], v[162:165], v[190:193], v[96:99]
	v_mfma_f32_16x16x32_bf16 v[88:91], v[170:173], v[190:193], v[88:91]
	v_mfma_f32_16x16x32_bf16 v[80:83], v[162:165], v[198:201], v[80:83]
	v_mfma_f32_16x16x32_bf16 v[72:75], v[170:173], v[198:201], v[72:75]
	v_mfma_f32_16x16x32_bf16 v[68:71], v[162:165], v[210:213], v[68:71]
	v_mfma_f32_16x16x32_bf16 v[64:67], v[170:173], v[210:213], v[64:67]
	v_mfma_f32_16x16x32_bf16 v[112:115], v[166:169], v[186:189], v[112:115]
	v_mfma_f32_16x16x32_bf16 v[104:107], v[178:181], v[186:189], v[104:107]
	v_mfma_f32_16x16x32_bf16 v[96:99], v[166:169], v[194:197], v[96:99]
	v_mfma_f32_16x16x32_bf16 v[88:91], v[178:181], v[194:197], v[88:91]
	v_mfma_f32_16x16x32_bf16 v[80:83], v[166:169], v[206:209], v[80:83]
	v_mfma_f32_16x16x32_bf16 v[72:75], v[178:181], v[206:209], v[72:75]
	v_mfma_f32_16x16x32_bf16 v[68:71], v[166:169], v[214:217], v[68:71]
	v_mfma_f32_16x16x32_bf16 v[64:67], v[178:181], v[214:217], v[64:67]
	s_setprio 0
	s_barrier
	s_add_i32 s0, s2, s48
	v_lshl_add_u64 v[174:175], v[174:175], 0, s[8:9]
	s_mov_b32 m0, s0
	ds_read_b128 v[182:185], v145 offset:49152
	ds_read_b128 v[186:189], v145 offset:50176
	ds_read_b128 v[190:193], v145 offset:51200
	ds_read_b128 v[194:197], v145 offset:52224
	ds_read_b128 v[198:201], v145 offset:53248
	ds_read_b128 v[206:209], v145 offset:54272
	ds_read_b128 v[210:213], v145 offset:55296
	ds_read_b128 v[214:217], v145 offset:56320
	global_load_lds_dwordx4 v[174:175], off
	s_add_i32 m0, s0, 0x2000
	s_add_u32 s0, s30, 0x80080
	v_lshl_add_u64 v[174:175], v[202:203], 0, s[8:9]
	s_addc_u32 s1, s31, 0
	s_add_i32 s2, s38, s48
	global_load_lds_dwordx4 v[174:175], off
	v_lshl_add_u64 v[174:175], s[0:1], 0, v[132:133]
	s_mov_b32 m0, s2
	s_nop 0
	global_load_lds_dwordx4 v[174:175], off
	v_lshl_add_u64 v[174:175], s[0:1], 0, v[128:129]
	s_add_i32 m0, s2, 0x2000
	s_nop 0
	global_load_lds_dwordx4 v[174:175], off
	v_lshl_add_u64 v[174:175], v[218:219], 0, s[8:9]
	s_mov_b32 m0, s55
	s_nop 0
	global_load_lds_dwordx4 v[174:175], off
	v_lshl_add_u64 v[174:175], v[220:221], 0, s[8:9]
	s_mov_b32 m0, s56
	s_nop 0
	global_load_lds_dwordx4 v[174:175], off
	s_waitcnt vmcnt(8)
	s_waitcnt lgkmcnt(0)
	s_barrier
	s_setprio 1
	v_mfma_f32_16x16x32_bf16 v[60:63], v[146:149], v[182:185], v[60:63]
	v_mfma_f32_16x16x32_bf16 v[56:59], v[154:157], v[182:185], v[56:59]
	v_mfma_f32_16x16x32_bf16 v[52:55], v[146:149], v[190:193], v[52:55]
	v_mfma_f32_16x16x32_bf16 v[44:47], v[154:157], v[190:193], v[44:47]
	v_mfma_f32_16x16x32_bf16 v[36:39], v[146:149], v[198:201], v[36:39]
	v_mfma_f32_16x16x32_bf16 v[28:31], v[154:157], v[198:201], v[28:31]
	v_mfma_f32_16x16x32_bf16 v[20:23], v[146:149], v[210:213], v[20:23]
	v_mfma_f32_16x16x32_bf16 v[12:15], v[154:157], v[210:213], v[12:15]
	v_mfma_f32_16x16x32_bf16 v[60:63], v[150:153], v[186:189], v[60:63]
	v_mfma_f32_16x16x32_bf16 v[56:59], v[158:161], v[186:189], v[56:59]
	v_mfma_f32_16x16x32_bf16 v[52:55], v[150:153], v[194:197], v[52:55]
	v_mfma_f32_16x16x32_bf16 v[44:47], v[158:161], v[194:197], v[44:47]
	v_mfma_f32_16x16x32_bf16 v[36:39], v[150:153], v[206:209], v[36:39]
	v_mfma_f32_16x16x32_bf16 v[28:31], v[158:161], v[206:209], v[28:31]
	v_mfma_f32_16x16x32_bf16 v[20:23], v[150:153], v[214:217], v[20:23]
	v_mfma_f32_16x16x32_bf16 v[12:15], v[158:161], v[214:217], v[12:15]
	v_mfma_f32_16x16x32_bf16 v[48:51], v[162:165], v[182:185], v[48:51]
	v_mfma_f32_16x16x32_bf16 v[40:43], v[170:173], v[182:185], v[40:43]
	v_mfma_f32_16x16x32_bf16 v[32:35], v[162:165], v[190:193], v[32:35]
	v_mfma_f32_16x16x32_bf16 v[24:27], v[170:173], v[190:193], v[24:27]
	v_mfma_f32_16x16x32_bf16 v[16:19], v[162:165], v[198:201], v[16:19]
	v_mfma_f32_16x16x32_bf16 v[8:11], v[170:173], v[198:201], v[8:11]
	v_mfma_f32_16x16x32_bf16 v[4:7], v[162:165], v[210:213], v[4:7]
	v_mfma_f32_16x16x32_bf16 v[0:3], v[170:173], v[210:213], v[0:3]
	v_mfma_f32_16x16x32_bf16 v[48:51], v[166:169], v[186:189], v[48:51]
	v_mfma_f32_16x16x32_bf16 v[40:43], v[178:181], v[186:189], v[40:43]
	v_mfma_f32_16x16x32_bf16 v[32:35], v[166:169], v[194:197], v[32:35]
	v_mfma_f32_16x16x32_bf16 v[24:27], v[178:181], v[194:197], v[24:27]
	v_mfma_f32_16x16x32_bf16 v[16:19], v[166:169], v[206:209], v[16:19]
	v_mfma_f32_16x16x32_bf16 v[8:11], v[178:181], v[206:209], v[8:11]
	v_mfma_f32_16x16x32_bf16 v[4:7], v[166:169], v[214:217], v[4:7]
	v_mfma_f32_16x16x32_bf16 v[0:3], v[178:181], v[214:217], v[0:3]
	s_setprio 0
	s_barrier
	s_add_i32 s68, s68, 2
	s_add_u32 s28, s28, 0x100
	s_addc_u32 s29, s29, 0
	s_add_u32 s66, s66, 0x100
	s_addc_u32 s67, s67, 0
	s_cmp_gt_u32 s68, 29
	s_cbranch_scc0 .LBB0_92
	s_and_b64 vcc, exec, s[10:11]
	s_cbranch_vccz .LBB0_95
	s_barrier

.LBB0_300:
	ds_read_b128 v[128:131], v157
	ds_read_b128 v[132:135], v157 offset:1024
	ds_read_b128 v[136:139], v157 offset:2048
	ds_read_b128 v[140:143], v157 offset:3072
	ds_read_b128 v[160:163], v158
	ds_read_b128 v[164:167], v158 offset:1024
	ds_read_b128 v[168:171], v158 offset:2048
	ds_read_b128 v[172:175], v158 offset:3072
	s_add_u32 s0, s62, 0xfff80080
	s_addc_u32 s1, s63, -1
	s_cmp_eq_u32 s89, 28
	s_cselect_b32 s67, s14, s1
	s_cselect_b32 s66, s49, s0
	s_cselect_b32 s65, s61, s88
	s_cselect_b32 s64, s68, s69
	v_lshl_add_u64 v[152:153], s[62:63], 0, v[148:149]
	s_add_i32 m0, s72, 0xc000
	ds_read_b128 v[178:181], v159
	ds_read_b128 v[182:185], v159 offset:1024
	ds_read_b128 v[186:189], v159 offset:2048
	ds_read_b128 v[190:193], v159 offset:3072
	ds_read_b128 v[194:197], v159 offset:4096
	ds_read_b128 v[198:201], v159 offset:5120
	ds_read_b128 v[206:209], v159 offset:6144
	ds_read_b128 v[210:213], v159 offset:7168
	global_load_lds_dwordx4 v[152:153], off
	v_lshl_add_u64 v[152:153], s[62:63], 0, v[150:151]
	s_add_i32 m0, s72, 0xe000
	s_nop 0
	global_load_lds_dwordx4 v[152:153], off
	s_waitcnt vmcnt(8)
	s_waitcnt lgkmcnt(0)
	s_barrier
	s_setprio 1
	v_mfma_f32_16x16x32_bf16 v[124:127], v[128:131], v[178:181], v[124:127]
	v_mfma_f32_16x16x32_bf16 v[120:123], v[136:139], v[178:181], v[120:123]
	v_mfma_f32_16x16x32_bf16 v[112:115], v[128:131], v[186:189], v[112:115]
	v_mfma_f32_16x16x32_bf16 v[108:111], v[136:139], v[186:189], v[108:111]
	v_mfma_f32_16x16x32_bf16 v[96:99], v[128:131], v[194:197], v[96:99]
	v_mfma_f32_16x16x32_bf16 v[92:95], v[136:139], v[194:197], v[92:95]
	v_mfma_f32_16x16x32_bf16 v[80:83], v[128:131], v[206:209], v[80:83]
	v_mfma_f32_16x16x32_bf16 v[76:79], v[136:139], v[206:209], v[76:79]
	v_mfma_f32_16x16x32_bf16 v[124:127], v[132:135], v[182:185], v[124:127]
	v_mfma_f32_16x16x32_bf16 v[120:123], v[140:143], v[182:185], v[120:123]
	v_mfma_f32_16x16x32_bf16 v[112:115], v[132:135], v[190:193], v[112:115]
	v_mfma_f32_16x16x32_bf16 v[108:111], v[140:143], v[190:193], v[108:111]
	v_mfma_f32_16x16x32_bf16 v[96:99], v[132:135], v[198:201], v[96:99]
	v_mfma_f32_16x16x32_bf16 v[92:95], v[140:143], v[198:201], v[92:95]
	v_mfma_f32_16x16x32_bf16 v[80:83], v[132:135], v[210:213], v[80:83]
	v_mfma_f32_16x16x32_bf16 v[76:79], v[140:143], v[210:213], v[76:79]
	v_mfma_f32_16x16x32_bf16 v[116:119], v[160:163], v[178:181], v[116:119]
	v_mfma_f32_16x16x32_bf16 v[104:107], v[168:171], v[178:181], v[104:107]
	v_mfma_f32_16x16x32_bf16 v[100:103], v[160:163], v[186:189], v[100:103]
	v_mfma_f32_16x16x32_bf16 v[88:91], v[168:171], v[186:189], v[88:91]
	v_mfma_f32_16x16x32_bf16 v[84:87], v[160:163], v[194:197], v[84:87]
	v_mfma_f32_16x16x32_bf16 v[72:75], v[168:171], v[194:197], v[72:75]
	v_mfma_f32_16x16x32_bf16 v[68:71], v[160:163], v[206:209], v[68:71]
	v_mfma_f32_16x16x32_bf16 v[64:67], v[168:171], v[206:209], v[64:67]
	v_mfma_f32_16x16x32_bf16 v[116:119], v[164:167], v[182:185], v[116:119]
	v_mfma_f32_16x16x32_bf16 v[104:107], v[172:175], v[182:185], v[104:107]
	v_mfma_f32_16x16x32_bf16 v[100:103], v[164:167], v[190:193], v[100:103]
	v_mfma_f32_16x16x32_bf16 v[88:91], v[172:175], v[190:193], v[88:91]
	v_mfma_f32_16x16x32_bf16 v[84:87], v[164:167], v[198:201], v[84:87]
	v_mfma_f32_16x16x32_bf16 v[72:75], v[172:175], v[198:201], v[72:75]
	v_mfma_f32_16x16x32_bf16 v[68:71], v[164:167], v[210:213], v[68:71]
	v_mfma_f32_16x16x32_bf16 v[64:67], v[172:175], v[210:213], v[64:67]
	s_setprio 0
	s_barrier
	s_add_i32 s0, s83, s71
	v_lshl_add_u64 v[152:153], s[64:65], 0, v[146:147]
	s_mov_b32 m0, s0
	ds_read_b128 v[178:181], v159 offset:16384
	ds_read_b128 v[182:185], v159 offset:17408
	ds_read_b128 v[186:189], v159 offset:18432
	ds_read_b128 v[190:193], v159 offset:19456
	ds_read_b128 v[194:197], v159 offset:20480
	ds_read_b128 v[198:201], v159 offset:21504
	ds_read_b128 v[206:209], v159 offset:22528
	ds_read_b128 v[210:213], v159 offset:23552
	global_load_lds_dwordx4 v[152:153], off
	s_add_i32 m0, s0, 0x2000
	s_add_u32 s0, s64, 0x80000
	v_lshl_add_u64 v[202:203], s[64:65], 0, v[144:145]
	s_addc_u32 s1, s65, 0
	s_add_i32 s2, s84, s71
	global_load_lds_dwordx4 v[202:203], off
	v_lshl_add_u64 v[214:215], s[0:1], 0, v[146:147]
	s_mov_b32 m0, s2
	v_lshl_add_u64 v[216:217], s[66:67], 0, v[144:145]
	global_load_lds_dwordx4 v[214:215], off
	v_lshl_add_u64 v[214:215], s[0:1], 0, v[144:145]
	s_add_i32 m0, s2, 0x2000
	s_nop 0
	global_load_lds_dwordx4 v[214:215], off
	v_lshl_add_u64 v[214:215], s[66:67], 0, v[146:147]
	s_mov_b32 m0, s72
	s_nop 0
	global_load_lds_dwordx4 v[214:215], off
	s_mov_b32 m0, s73
	s_nop 0
	global_load_lds_dwordx4 v[216:217], off
	s_waitcnt vmcnt(8)
	s_waitcnt lgkmcnt(0)
	s_barrier
	s_setprio 1
	v_mfma_f32_16x16x32_bf16 v[60:63], v[128:131], v[178:181], v[60:63]
	v_mfma_f32_16x16x32_bf16 v[56:59], v[136:139], v[178:181], v[56:59]
	v_mfma_f32_16x16x32_bf16 v[48:51], v[128:131], v[186:189], v[48:51]
	v_mfma_f32_16x16x32_bf16 v[44:47], v[136:139], v[186:189], v[44:47]
	v_mfma_f32_16x16x32_bf16 v[32:35], v[128:131], v[194:197], v[32:35]
	v_mfma_f32_16x16x32_bf16 v[28:31], v[136:139], v[194:197], v[28:31]
	v_mfma_f32_16x16x32_bf16 v[16:19], v[128:131], v[206:209], v[16:19]
	v_mfma_f32_16x16x32_bf16 v[12:15], v[136:139], v[206:209], v[12:15]
	v_mfma_f32_16x16x32_bf16 v[60:63], v[132:135], v[182:185], v[60:63]
	v_mfma_f32_16x16x32_bf16 v[56:59], v[140:143], v[182:185], v[56:59]
	v_mfma_f32_16x16x32_bf16 v[48:51], v[132:135], v[190:193], v[48:51]
	v_mfma_f32_16x16x32_bf16 v[44:47], v[140:143], v[190:193], v[44:47]
	v_mfma_f32_16x16x32_bf16 v[32:35], v[132:135], v[198:201], v[32:35]
	v_mfma_f32_16x16x32_bf16 v[28:31], v[140:143], v[198:201], v[28:31]
	v_mfma_f32_16x16x32_bf16 v[16:19], v[132:135], v[210:213], v[16:19]
	v_mfma_f32_16x16x32_bf16 v[12:15], v[140:143], v[210:213], v[12:15]
	v_mfma_f32_16x16x32_bf16 v[52:55], v[160:163], v[178:181], v[52:55]
	v_mfma_f32_16x16x32_bf16 v[40:43], v[168:171], v[178:181], v[40:43]
	v_mfma_f32_16x16x32_bf16 v[36:39], v[160:163], v[186:189], v[36:39]
	v_mfma_f32_16x16x32_bf16 v[24:27], v[168:171], v[186:189], v[24:27]
	v_mfma_f32_16x16x32_bf16 v[20:23], v[160:163], v[194:197], v[20:23]
	v_mfma_f32_16x16x32_bf16 v[8:11], v[168:171], v[194:197], v[8:11]
	v_mfma_f32_16x16x32_bf16 v[4:7], v[160:163], v[206:209], v[4:7]
	v_mfma_f32_16x16x32_bf16 v[0:3], v[168:171], v[206:209], v[0:3]
	v_mfma_f32_16x16x32_bf16 v[52:55], v[164:167], v[182:185], v[52:55]
	v_mfma_f32_16x16x32_bf16 v[40:43], v[172:175], v[182:185], v[40:43]
	v_mfma_f32_16x16x32_bf16 v[36:39], v[164:167], v[190:193], v[36:39]
	v_mfma_f32_16x16x32_bf16 v[24:27], v[172:175], v[190:193], v[24:27]
	v_mfma_f32_16x16x32_bf16 v[20:23], v[164:167], v[198:201], v[20:23]
	v_mfma_f32_16x16x32_bf16 v[8:11], v[172:175], v[198:201], v[8:11]
	v_mfma_f32_16x16x32_bf16 v[4:7], v[164:167], v[210:213], v[4:7]
	v_mfma_f32_16x16x32_bf16 v[0:3], v[172:175], v[210:213], v[0:3]
	s_setprio 0
	s_barrier
	s_add_i32 s2, 0, 0x18000
	s_add_i32 s3, 0, 0x1c000
	v_add_u32_e32 v140, s2, v156
	v_add_u32_e32 v172, s3, v156
	ds_read_b128 v[128:131], v140
	ds_read_b128 v[132:135], v140 offset:1024
	ds_read_b128 v[136:139], v140 offset:2048
	ds_read_b128 v[140:143], v140 offset:3072
	ds_read_b128 v[160:163], v172
	ds_read_b128 v[164:167], v172 offset:1024
	ds_read_b128 v[168:171], v172 offset:2048
	ds_read_b128 v[172:175], v172 offset:3072
	s_add_u32 s0, s66, 0x80000
	s_addc_u32 s1, s67, 0
	s_mov_b32 m0, s74
	v_lshl_add_u64 v[218:219], s[0:1], 0, v[146:147]
	ds_read_b128 v[178:181], v159 offset:32768
	ds_read_b128 v[182:185], v159 offset:33792
	ds_read_b128 v[186:189], v159 offset:34816
	ds_read_b128 v[190:193], v159 offset:35840
	ds_read_b128 v[194:197], v159 offset:36864
	ds_read_b128 v[198:201], v159 offset:37888
	ds_read_b128 v[206:209], v159 offset:38912
	ds_read_b128 v[210:213], v159 offset:39936
	global_load_lds_dwordx4 v[218:219], off
	v_lshl_add_u64 v[218:219], s[0:1], 0, v[144:145]
	s_mov_b32 m0, s75
	s_nop 0
	global_load_lds_dwordx4 v[218:219], off
	s_waitcnt vmcnt(8)
	s_waitcnt lgkmcnt(0)
	s_barrier
	s_setprio 1
	v_mfma_f32_16x16x32_bf16 v[124:127], v[128:131], v[178:181], v[124:127]
	v_mfma_f32_16x16x32_bf16 v[120:123], v[136:139], v[178:181], v[120:123]
	v_mfma_f32_16x16x32_bf16 v[112:115], v[128:131], v[186:189], v[112:115]
	v_mfma_f32_16x16x32_bf16 v[108:111], v[136:139], v[186:189], v[108:111]
	v_mfma_f32_16x16x32_bf16 v[96:99], v[128:131], v[194:197], v[96:99]
	v_mfma_f32_16x16x32_bf16 v[92:95], v[136:139], v[194:197], v[92:95]
	v_mfma_f32_16x16x32_bf16 v[80:83], v[128:131], v[206:209], v[80:83]
	v_mfma_f32_16x16x32_bf16 v[76:79], v[136:139], v[206:209], v[76:79]
	v_mfma_f32_16x16x32_bf16 v[124:127], v[132:135], v[182:185], v[124:127]
	v_mfma_f32_16x16x32_bf16 v[120:123], v[140:143], v[182:185], v[120:123]
	v_mfma_f32_16x16x32_bf16 v[112:115], v[132:135], v[190:193], v[112:115]
	v_mfma_f32_16x16x32_bf16 v[108:111], v[140:143], v[190:193], v[108:111]
	v_mfma_f32_16x16x32_bf16 v[96:99], v[132:135], v[198:201], v[96:99]
	v_mfma_f32_16x16x32_bf16 v[92:95], v[140:143], v[198:201], v[92:95]
	v_mfma_f32_16x16x32_bf16 v[80:83], v[132:135], v[210:213], v[80:83]
	v_mfma_f32_16x16x32_bf16 v[76:79], v[140:143], v[210:213], v[76:79]
	v_mfma_f32_16x16x32_bf16 v[116:119], v[160:163], v[178:181], v[116:119]
	v_mfma_f32_16x16x32_bf16 v[104:107], v[168:171], v[178:181], v[104:107]
	v_mfma_f32_16x16x32_bf16 v[100:103], v[160:163], v[186:189], v[100:103]
	v_mfma_f32_16x16x32_bf16 v[88:91], v[168:171], v[186:189], v[88:91]
	v_mfma_f32_16x16x32_bf16 v[84:87], v[160:163], v[194:197], v[84:87]
	v_mfma_f32_16x16x32_bf16 v[72:75], v[168:171], v[194:197], v[72:75]
	v_mfma_f32_16x16x32_bf16 v[68:71], v[160:163], v[206:209], v[68:71]
	v_mfma_f32_16x16x32_bf16 v[64:67], v[168:171], v[206:209], v[64:67]
	v_mfma_f32_16x16x32_bf16 v[116:119], v[164:167], v[182:185], v[116:119]
	v_mfma_f32_16x16x32_bf16 v[104:107], v[172:175], v[182:185], v[104:107]
	v_mfma_f32_16x16x32_bf16 v[100:103], v[164:167], v[190:193], v[100:103]
	v_mfma_f32_16x16x32_bf16 v[88:91], v[172:175], v[190:193], v[88:91]
	v_mfma_f32_16x16x32_bf16 v[84:87], v[164:167], v[198:201], v[84:87]
	v_mfma_f32_16x16x32_bf16 v[72:75], v[172:175], v[198:201], v[72:75]
	v_mfma_f32_16x16x32_bf16 v[68:71], v[164:167], v[210:213], v[68:71]
	v_mfma_f32_16x16x32_bf16 v[64:67], v[172:175], v[210:213], v[64:67]
	s_setprio 0
	s_barrier
	s_add_i32 s0, s2, s71
	v_lshl_add_u64 v[152:153], v[152:153], 0, s[12:13]
	s_mov_b32 m0, s0
	ds_read_b128 v[178:181], v159 offset:49152
	ds_read_b128 v[182:185], v159 offset:50176
	ds_read_b128 v[186:189], v159 offset:51200
	ds_read_b128 v[190:193], v159 offset:52224
	ds_read_b128 v[194:197], v159 offset:53248
	ds_read_b128 v[198:201], v159 offset:54272
	ds_read_b128 v[206:209], v159 offset:55296
	ds_read_b128 v[210:213], v159 offset:56320
	global_load_lds_dwordx4 v[152:153], off
	s_add_i32 m0, s0, 0x2000
	s_add_u32 s0, s64, 0x80080
	v_lshl_add_u64 v[152:153], v[202:203], 0, s[12:13]
	s_addc_u32 s1, s65, 0
	s_add_i32 s2, s3, s71
	global_load_lds_dwordx4 v[152:153], off
	v_lshl_add_u64 v[152:153], s[0:1], 0, v[146:147]
	s_mov_b32 m0, s2
	s_nop 0
	global_load_lds_dwordx4 v[152:153], off
	v_lshl_add_u64 v[152:153], s[0:1], 0, v[144:145]
	s_add_i32 m0, s2, 0x2000
	s_nop 0
	global_load_lds_dwordx4 v[152:153], off
	v_lshl_add_u64 v[152:153], v[214:215], 0, s[12:13]
	s_mov_b32 m0, s81
	s_nop 0
	global_load_lds_dwordx4 v[152:153], off
	v_lshl_add_u64 v[152:153], v[216:217], 0, s[12:13]
	s_mov_b32 m0, s82
	s_nop 0
	global_load_lds_dwordx4 v[152:153], off
	s_waitcnt vmcnt(8)
	s_waitcnt lgkmcnt(0)
	s_barrier
	s_setprio 1
	v_mfma_f32_16x16x32_bf16 v[60:63], v[128:131], v[178:181], v[60:63]
	v_mfma_f32_16x16x32_bf16 v[56:59], v[136:139], v[178:181], v[56:59]
	v_mfma_f32_16x16x32_bf16 v[48:51], v[128:131], v[186:189], v[48:51]
	v_mfma_f32_16x16x32_bf16 v[44:47], v[136:139], v[186:189], v[44:47]
	v_mfma_f32_16x16x32_bf16 v[32:35], v[128:131], v[194:197], v[32:35]
	v_mfma_f32_16x16x32_bf16 v[28:31], v[136:139], v[194:197], v[28:31]
	v_mfma_f32_16x16x32_bf16 v[16:19], v[128:131], v[206:209], v[16:19]
	v_mfma_f32_16x16x32_bf16 v[12:15], v[136:139], v[206:209], v[12:15]
	v_mfma_f32_16x16x32_bf16 v[60:63], v[132:135], v[182:185], v[60:63]
	v_mfma_f32_16x16x32_bf16 v[56:59], v[140:143], v[182:185], v[56:59]
	v_mfma_f32_16x16x32_bf16 v[48:51], v[132:135], v[190:193], v[48:51]
	v_mfma_f32_16x16x32_bf16 v[44:47], v[140:143], v[190:193], v[44:47]
	v_mfma_f32_16x16x32_bf16 v[32:35], v[132:135], v[198:201], v[32:35]
	v_mfma_f32_16x16x32_bf16 v[28:31], v[140:143], v[198:201], v[28:31]
	v_mfma_f32_16x16x32_bf16 v[16:19], v[132:135], v[210:213], v[16:19]
	v_mfma_f32_16x16x32_bf16 v[12:15], v[140:143], v[210:213], v[12:15]
	v_mfma_f32_16x16x32_bf16 v[52:55], v[160:163], v[178:181], v[52:55]
	v_mfma_f32_16x16x32_bf16 v[40:43], v[168:171], v[178:181], v[40:43]
	v_mfma_f32_16x16x32_bf16 v[36:39], v[160:163], v[186:189], v[36:39]
	v_mfma_f32_16x16x32_bf16 v[24:27], v[168:171], v[186:189], v[24:27]
	v_mfma_f32_16x16x32_bf16 v[20:23], v[160:163], v[194:197], v[20:23]
	v_mfma_f32_16x16x32_bf16 v[8:11], v[168:171], v[194:197], v[8:11]
	v_mfma_f32_16x16x32_bf16 v[4:7], v[160:163], v[206:209], v[4:7]
	v_mfma_f32_16x16x32_bf16 v[0:3], v[168:171], v[206:209], v[0:3]
	v_mfma_f32_16x16x32_bf16 v[52:55], v[164:167], v[182:185], v[52:55]
	v_mfma_f32_16x16x32_bf16 v[40:43], v[172:175], v[182:185], v[40:43]
	v_mfma_f32_16x16x32_bf16 v[36:39], v[164:167], v[190:193], v[36:39]
	v_mfma_f32_16x16x32_bf16 v[24:27], v[172:175], v[190:193], v[24:27]
	v_mfma_f32_16x16x32_bf16 v[20:23], v[164:167], v[198:201], v[20:23]
	v_mfma_f32_16x16x32_bf16 v[8:11], v[172:175], v[198:201], v[8:11]
	v_mfma_f32_16x16x32_bf16 v[4:7], v[164:167], v[210:213], v[4:7]
	v_mfma_f32_16x16x32_bf16 v[0:3], v[172:175], v[210:213], v[0:3]
	s_setprio 0
	s_barrier
	s_add_i32 s89, s89, 2
	s_add_u32 s62, s62, 0x100
	s_addc_u32 s63, s63, 0
	s_add_u32 s69, s69, 0x100
	s_addc_u32 s88, s88, 0
	s_cmp_gt_u32 s89, 29
	s_cbranch_scc0 .LBB0_300
	s_and_b64 vcc, exec, s[16:17]
	s_cbranch_vccz .LBB0_303
	s_barrier

.LBB0_399:
	ds_read_b128 v[128:131], v207
	ds_read_b128 v[132:135], v207 offset:1024
	ds_read_b128 v[136:139], v207 offset:2048
	ds_read_b128 v[140:143], v207 offset:3072
	ds_read_b128 v[144:147], v208
	ds_read_b128 v[148:151], v208 offset:1024
	ds_read_b128 v[152:155], v208 offset:2048
	ds_read_b128 v[156:159], v208 offset:3072
	s_add_u32 s0, s4, 0xfff80080
	s_addc_u32 s1, s5, -1
	s_cmp_eq_u32 vcc_hi, 28
	s_cselect_b32 s11, s7, s1
	s_cselect_b32 s10, s12, s0
	s_cselect_b32 s9, s13, vcc_lo
	s_cselect_b32 s8, s15, s65
	v_lshl_add_u64 v[202:203], s[4:5], 0, v[186:187]
	s_add_i32 m0, s81, 0xc000
	ds_read_b128 v[160:163], v209
	ds_read_b128 v[164:167], v209 offset:1024
	ds_read_b128 v[168:171], v209 offset:2048
	ds_read_b128 v[172:175], v209 offset:3072
	ds_read_b128 v[190:193], v209 offset:4096
	ds_read_b128 v[194:197], v209 offset:5120
	ds_read_b128 v[198:201], v209 offset:6144
	ds_read_b128 v[210:213], v209 offset:7168
	global_load_lds_dwordx4 v[202:203], off
	v_lshl_add_u64 v[202:203], s[4:5], 0, v[188:189]
	s_add_i32 m0, s81, 0xe000
	s_nop 0
	global_load_lds_dwordx4 v[202:203], off
	s_waitcnt vmcnt(8)
	s_waitcnt lgkmcnt(0)
	s_barrier
	s_setprio 1
	v_mfma_f32_16x16x32_bf16 v[124:127], v[128:131], v[160:163], v[124:127]
	v_mfma_f32_16x16x32_bf16 v[56:59], v[136:139], v[160:163], v[56:59]
	v_mfma_f32_16x16x32_bf16 v[116:119], v[128:131], v[168:171], v[116:119]
	v_mfma_f32_16x16x32_bf16 v[52:55], v[136:139], v[168:171], v[52:55]
	v_mfma_f32_16x16x32_bf16 v[108:111], v[128:131], v[190:193], v[108:111]
	v_mfma_f32_16x16x32_bf16 v[44:47], v[136:139], v[190:193], v[44:47]
	v_mfma_f32_16x16x32_bf16 v[104:107], v[128:131], v[198:201], v[104:107]
	v_mfma_f32_16x16x32_bf16 v[32:35], v[136:139], v[198:201], v[32:35]
	v_mfma_f32_16x16x32_bf16 v[124:127], v[132:135], v[164:167], v[124:127]
	v_mfma_f32_16x16x32_bf16 v[56:59], v[140:143], v[164:167], v[56:59]
	v_mfma_f32_16x16x32_bf16 v[116:119], v[132:135], v[172:175], v[116:119]
	v_mfma_f32_16x16x32_bf16 v[52:55], v[140:143], v[172:175], v[52:55]
	v_mfma_f32_16x16x32_bf16 v[108:111], v[132:135], v[194:197], v[108:111]
	v_mfma_f32_16x16x32_bf16 v[44:47], v[140:143], v[194:197], v[44:47]
	v_mfma_f32_16x16x32_bf16 v[104:107], v[132:135], v[210:213], v[104:107]
	v_mfma_f32_16x16x32_bf16 v[32:35], v[140:143], v[210:213], v[32:35]
	v_mfma_f32_16x16x32_bf16 v[120:123], v[144:147], v[160:163], v[120:123]
	v_mfma_f32_16x16x32_bf16 v[60:63], v[152:155], v[160:163], v[60:63]
	v_mfma_f32_16x16x32_bf16 v[112:115], v[144:147], v[168:171], v[112:115]
	v_mfma_f32_16x16x32_bf16 v[48:51], v[152:155], v[168:171], v[48:51]
	v_mfma_f32_16x16x32_bf16 v[100:103], v[144:147], v[190:193], v[100:103]
	v_mfma_f32_16x16x32_bf16 v[40:43], v[152:155], v[190:193], v[40:43]
	v_mfma_f32_16x16x32_bf16 v[96:99], v[144:147], v[198:201], v[96:99]
	v_mfma_f32_16x16x32_bf16 v[36:39], v[152:155], v[198:201], v[36:39]
	v_mfma_f32_16x16x32_bf16 v[120:123], v[148:151], v[164:167], v[120:123]
	v_mfma_f32_16x16x32_bf16 v[60:63], v[156:159], v[164:167], v[60:63]
	v_mfma_f32_16x16x32_bf16 v[112:115], v[148:151], v[172:175], v[112:115]
	v_mfma_f32_16x16x32_bf16 v[48:51], v[156:159], v[172:175], v[48:51]
	v_mfma_f32_16x16x32_bf16 v[100:103], v[148:151], v[194:197], v[100:103]
	v_mfma_f32_16x16x32_bf16 v[40:43], v[156:159], v[194:197], v[40:43]
	v_mfma_f32_16x16x32_bf16 v[96:99], v[148:151], v[210:213], v[96:99]
	v_mfma_f32_16x16x32_bf16 v[36:39], v[156:159], v[210:213], v[36:39]
	s_setprio 0
	s_barrier
	s_add_i32 s0, s95, s80
	v_lshl_add_u64 v[202:203], s[8:9], 0, v[180:181]
	s_mov_b32 m0, s0
	ds_read_b128 v[160:163], v209 offset:16384
	ds_read_b128 v[164:167], v209 offset:17408
	ds_read_b128 v[168:171], v209 offset:18432
	ds_read_b128 v[172:175], v209 offset:19456
	ds_read_b128 v[190:193], v209 offset:20480
	ds_read_b128 v[194:197], v209 offset:21504
	ds_read_b128 v[198:201], v209 offset:22528
	ds_read_b128 v[210:213], v209 offset:23552
	global_load_lds_dwordx4 v[202:203], off
	s_add_i32 m0, s0, 0x2000
	s_add_u32 s0, s8, 0x80000
	v_lshl_add_u64 v[214:215], s[8:9], 0, v[184:185]
	s_addc_u32 s1, s9, 0
	s_add_i32 s2, s96, s80
	global_load_lds_dwordx4 v[214:215], off
	v_lshl_add_u64 v[216:217], s[0:1], 0, v[180:181]
	s_mov_b32 m0, s2
	v_lshl_add_u64 v[218:219], s[10:11], 0, v[182:183]
	global_load_lds_dwordx4 v[216:217], off
	v_lshl_add_u64 v[216:217], s[0:1], 0, v[184:185]
	s_add_i32 m0, s2, 0x2000
	s_nop 0
	global_load_lds_dwordx4 v[216:217], off
	v_lshl_add_u64 v[216:217], s[10:11], 0, v[178:179]
	s_mov_b32 m0, s81
	s_nop 0
	global_load_lds_dwordx4 v[216:217], off
	s_mov_b32 m0, s82
	s_nop 0
	global_load_lds_dwordx4 v[218:219], off
	s_waitcnt vmcnt(8)
	s_waitcnt lgkmcnt(0)
	s_barrier
	s_setprio 1
	v_mfma_f32_16x16x32_bf16 v[92:95], v[128:131], v[160:163], v[92:95]
	v_mfma_f32_16x16x32_bf16 v[24:27], v[136:139], v[160:163], v[24:27]
	v_mfma_f32_16x16x32_bf16 v[84:87], v[128:131], v[168:171], v[84:87]
	v_mfma_f32_16x16x32_bf16 v[20:23], v[136:139], v[168:171], v[20:23]
	v_mfma_f32_16x16x32_bf16 v[76:79], v[128:131], v[190:193], v[76:79]
	v_mfma_f32_16x16x32_bf16 v[12:15], v[136:139], v[190:193], v[12:15]
	v_mfma_f32_16x16x32_bf16 v[72:75], v[128:131], v[198:201], v[72:75]
	v_mfma_f32_16x16x32_bf16 v[0:3], v[136:139], v[198:201], v[0:3]
	v_mfma_f32_16x16x32_bf16 v[92:95], v[132:135], v[164:167], v[92:95]
	v_mfma_f32_16x16x32_bf16 v[24:27], v[140:143], v[164:167], v[24:27]
	v_mfma_f32_16x16x32_bf16 v[84:87], v[132:135], v[172:175], v[84:87]
	v_mfma_f32_16x16x32_bf16 v[20:23], v[140:143], v[172:175], v[20:23]
	v_mfma_f32_16x16x32_bf16 v[76:79], v[132:135], v[194:197], v[76:79]
	v_mfma_f32_16x16x32_bf16 v[12:15], v[140:143], v[194:197], v[12:15]
	v_mfma_f32_16x16x32_bf16 v[72:75], v[132:135], v[210:213], v[72:75]
	v_mfma_f32_16x16x32_bf16 v[0:3], v[140:143], v[210:213], v[0:3]
	v_mfma_f32_16x16x32_bf16 v[88:91], v[144:147], v[160:163], v[88:91]
	v_mfma_f32_16x16x32_bf16 v[28:31], v[152:155], v[160:163], v[28:31]
	v_mfma_f32_16x16x32_bf16 v[80:83], v[144:147], v[168:171], v[80:83]
	v_mfma_f32_16x16x32_bf16 v[16:19], v[152:155], v[168:171], v[16:19]
	v_mfma_f32_16x16x32_bf16 v[68:71], v[144:147], v[190:193], v[68:71]
	v_mfma_f32_16x16x32_bf16 v[8:11], v[152:155], v[190:193], v[8:11]
	v_mfma_f32_16x16x32_bf16 v[64:67], v[144:147], v[198:201], v[64:67]
	v_mfma_f32_16x16x32_bf16 v[4:7], v[152:155], v[198:201], v[4:7]
	v_mfma_f32_16x16x32_bf16 v[88:91], v[148:151], v[164:167], v[88:91]
	v_mfma_f32_16x16x32_bf16 v[28:31], v[156:159], v[164:167], v[28:31]
	v_mfma_f32_16x16x32_bf16 v[80:83], v[148:151], v[172:175], v[80:83]
	v_mfma_f32_16x16x32_bf16 v[16:19], v[156:159], v[172:175], v[16:19]
	v_mfma_f32_16x16x32_bf16 v[68:71], v[148:151], v[194:197], v[68:71]
	v_mfma_f32_16x16x32_bf16 v[8:11], v[156:159], v[194:197], v[8:11]
	v_mfma_f32_16x16x32_bf16 v[64:67], v[148:151], v[210:213], v[64:67]
	v_mfma_f32_16x16x32_bf16 v[4:7], v[156:159], v[210:213], v[4:7]
	s_setprio 0
	s_barrier
	s_add_i32 s2, 0, 0x18000
	s_add_i32 s3, 0, 0x1c000
	v_add_u32_e32 v140, s2, v206
	v_add_u32_e32 v156, s3, v206
	ds_read_b128 v[128:131], v140
	ds_read_b128 v[132:135], v140 offset:1024
	ds_read_b128 v[136:139], v140 offset:2048
	ds_read_b128 v[140:143], v140 offset:3072
	ds_read_b128 v[144:147], v156
	ds_read_b128 v[148:151], v156 offset:1024
	ds_read_b128 v[152:155], v156 offset:2048
	ds_read_b128 v[156:159], v156 offset:3072
	s_add_u32 s0, s10, 0x80000
	s_addc_u32 s1, s11, 0
	s_mov_b32 m0, s83
	v_lshl_add_u64 v[220:221], s[0:1], 0, v[178:179]
	ds_read_b128 v[160:163], v209 offset:32768
	ds_read_b128 v[164:167], v209 offset:33792
	ds_read_b128 v[168:171], v209 offset:34816
	ds_read_b128 v[172:175], v209 offset:35840
	ds_read_b128 v[190:193], v209 offset:36864
	ds_read_b128 v[194:197], v209 offset:37888
	ds_read_b128 v[198:201], v209 offset:38912
	ds_read_b128 v[210:213], v209 offset:39936
	global_load_lds_dwordx4 v[220:221], off
	v_lshl_add_u64 v[220:221], s[0:1], 0, v[182:183]
	s_mov_b32 m0, s84
	s_nop 0
	global_load_lds_dwordx4 v[220:221], off
	s_waitcnt vmcnt(8)
	s_waitcnt lgkmcnt(0)
	s_barrier
	s_setprio 1
	v_mfma_f32_16x16x32_bf16 v[124:127], v[128:131], v[160:163], v[124:127]
	v_mfma_f32_16x16x32_bf16 v[56:59], v[136:139], v[160:163], v[56:59]
	v_mfma_f32_16x16x32_bf16 v[116:119], v[128:131], v[168:171], v[116:119]
	v_mfma_f32_16x16x32_bf16 v[52:55], v[136:139], v[168:171], v[52:55]
	v_mfma_f32_16x16x32_bf16 v[108:111], v[128:131], v[190:193], v[108:111]
	v_mfma_f32_16x16x32_bf16 v[44:47], v[136:139], v[190:193], v[44:47]
	v_mfma_f32_16x16x32_bf16 v[104:107], v[128:131], v[198:201], v[104:107]
	v_mfma_f32_16x16x32_bf16 v[32:35], v[136:139], v[198:201], v[32:35]
	v_mfma_f32_16x16x32_bf16 v[124:127], v[132:135], v[164:167], v[124:127]
	v_mfma_f32_16x16x32_bf16 v[56:59], v[140:143], v[164:167], v[56:59]
	v_mfma_f32_16x16x32_bf16 v[116:119], v[132:135], v[172:175], v[116:119]
	v_mfma_f32_16x16x32_bf16 v[52:55], v[140:143], v[172:175], v[52:55]
	v_mfma_f32_16x16x32_bf16 v[108:111], v[132:135], v[194:197], v[108:111]
	v_mfma_f32_16x16x32_bf16 v[44:47], v[140:143], v[194:197], v[44:47]
	v_mfma_f32_16x16x32_bf16 v[104:107], v[132:135], v[210:213], v[104:107]
	v_mfma_f32_16x16x32_bf16 v[32:35], v[140:143], v[210:213], v[32:35]
	v_mfma_f32_16x16x32_bf16 v[120:123], v[144:147], v[160:163], v[120:123]
	v_mfma_f32_16x16x32_bf16 v[60:63], v[152:155], v[160:163], v[60:63]
	v_mfma_f32_16x16x32_bf16 v[112:115], v[144:147], v[168:171], v[112:115]
	v_mfma_f32_16x16x32_bf16 v[48:51], v[152:155], v[168:171], v[48:51]
	v_mfma_f32_16x16x32_bf16 v[100:103], v[144:147], v[190:193], v[100:103]
	v_mfma_f32_16x16x32_bf16 v[40:43], v[152:155], v[190:193], v[40:43]
	v_mfma_f32_16x16x32_bf16 v[96:99], v[144:147], v[198:201], v[96:99]
	v_mfma_f32_16x16x32_bf16 v[36:39], v[152:155], v[198:201], v[36:39]
	v_mfma_f32_16x16x32_bf16 v[120:123], v[148:151], v[164:167], v[120:123]
	v_mfma_f32_16x16x32_bf16 v[60:63], v[156:159], v[164:167], v[60:63]
	v_mfma_f32_16x16x32_bf16 v[112:115], v[148:151], v[172:175], v[112:115]
	v_mfma_f32_16x16x32_bf16 v[48:51], v[156:159], v[172:175], v[48:51]
	v_mfma_f32_16x16x32_bf16 v[100:103], v[148:151], v[194:197], v[100:103]
	v_mfma_f32_16x16x32_bf16 v[40:43], v[156:159], v[194:197], v[40:43]
	v_mfma_f32_16x16x32_bf16 v[96:99], v[148:151], v[210:213], v[96:99]
	v_mfma_f32_16x16x32_bf16 v[36:39], v[156:159], v[210:213], v[36:39]
	s_setprio 0
	s_barrier
	s_add_i32 s0, s2, s80
	v_lshl_add_u64 v[202:203], v[202:203], 0, s[24:25]
	s_mov_b32 m0, s0
	ds_read_b128 v[160:163], v209 offset:49152
	ds_read_b128 v[164:167], v209 offset:50176
	ds_read_b128 v[168:171], v209 offset:51200
	ds_read_b128 v[172:175], v209 offset:52224
	ds_read_b128 v[190:193], v209 offset:53248
	ds_read_b128 v[194:197], v209 offset:54272
	ds_read_b128 v[198:201], v209 offset:55296
	ds_read_b128 v[210:213], v209 offset:56320
	global_load_lds_dwordx4 v[202:203], off
	s_add_i32 m0, s0, 0x2000
	s_add_u32 s0, s8, 0x80080
	v_lshl_add_u64 v[202:203], v[214:215], 0, s[24:25]
	s_addc_u32 s1, s9, 0
	s_add_i32 s2, s3, s80
	global_load_lds_dwordx4 v[202:203], off
	v_lshl_add_u64 v[202:203], s[0:1], 0, v[180:181]
	s_mov_b32 m0, s2
	s_nop 0
	global_load_lds_dwordx4 v[202:203], off
	v_lshl_add_u64 v[202:203], s[0:1], 0, v[184:185]
	s_add_i32 m0, s2, 0x2000
	s_nop 0
	global_load_lds_dwordx4 v[202:203], off
	v_lshl_add_u64 v[202:203], v[216:217], 0, s[24:25]
	s_mov_b32 m0, s90
	s_nop 0
	global_load_lds_dwordx4 v[202:203], off
	v_lshl_add_u64 v[202:203], v[218:219], 0, s[24:25]
	s_mov_b32 m0, s91
	s_nop 0
	global_load_lds_dwordx4 v[202:203], off
	s_waitcnt vmcnt(8)
	s_waitcnt lgkmcnt(0)
	s_barrier
	s_setprio 1
	v_mfma_f32_16x16x32_bf16 v[92:95], v[128:131], v[160:163], v[92:95]
	v_mfma_f32_16x16x32_bf16 v[24:27], v[136:139], v[160:163], v[24:27]
	v_mfma_f32_16x16x32_bf16 v[84:87], v[128:131], v[168:171], v[84:87]
	v_mfma_f32_16x16x32_bf16 v[20:23], v[136:139], v[168:171], v[20:23]
	v_mfma_f32_16x16x32_bf16 v[76:79], v[128:131], v[190:193], v[76:79]
	v_mfma_f32_16x16x32_bf16 v[12:15], v[136:139], v[190:193], v[12:15]
	v_mfma_f32_16x16x32_bf16 v[72:75], v[128:131], v[198:201], v[72:75]
	v_mfma_f32_16x16x32_bf16 v[0:3], v[136:139], v[198:201], v[0:3]
	v_mfma_f32_16x16x32_bf16 v[92:95], v[132:135], v[164:167], v[92:95]
	v_mfma_f32_16x16x32_bf16 v[24:27], v[140:143], v[164:167], v[24:27]
	v_mfma_f32_16x16x32_bf16 v[84:87], v[132:135], v[172:175], v[84:87]
	v_mfma_f32_16x16x32_bf16 v[20:23], v[140:143], v[172:175], v[20:23]
	v_mfma_f32_16x16x32_bf16 v[76:79], v[132:135], v[194:197], v[76:79]
	v_mfma_f32_16x16x32_bf16 v[12:15], v[140:143], v[194:197], v[12:15]
	v_mfma_f32_16x16x32_bf16 v[72:75], v[132:135], v[210:213], v[72:75]
	v_mfma_f32_16x16x32_bf16 v[0:3], v[140:143], v[210:213], v[0:3]
	v_mfma_f32_16x16x32_bf16 v[88:91], v[144:147], v[160:163], v[88:91]
	v_mfma_f32_16x16x32_bf16 v[28:31], v[152:155], v[160:163], v[28:31]
	v_mfma_f32_16x16x32_bf16 v[80:83], v[144:147], v[168:171], v[80:83]
	v_mfma_f32_16x16x32_bf16 v[16:19], v[152:155], v[168:171], v[16:19]
	v_mfma_f32_16x16x32_bf16 v[68:71], v[144:147], v[190:193], v[68:71]
	v_mfma_f32_16x16x32_bf16 v[8:11], v[152:155], v[190:193], v[8:11]
	v_mfma_f32_16x16x32_bf16 v[64:67], v[144:147], v[198:201], v[64:67]
	v_mfma_f32_16x16x32_bf16 v[4:7], v[152:155], v[198:201], v[4:7]
	v_mfma_f32_16x16x32_bf16 v[88:91], v[148:151], v[164:167], v[88:91]
	v_mfma_f32_16x16x32_bf16 v[28:31], v[156:159], v[164:167], v[28:31]
	v_mfma_f32_16x16x32_bf16 v[80:83], v[148:151], v[172:175], v[80:83]
	v_mfma_f32_16x16x32_bf16 v[16:19], v[156:159], v[172:175], v[16:19]
	v_mfma_f32_16x16x32_bf16 v[68:71], v[148:151], v[194:197], v[68:71]
	v_mfma_f32_16x16x32_bf16 v[8:11], v[156:159], v[194:197], v[8:11]
	v_mfma_f32_16x16x32_bf16 v[64:67], v[148:151], v[210:213], v[64:67]
	v_mfma_f32_16x16x32_bf16 v[4:7], v[156:159], v[210:213], v[4:7]
	s_setprio 0
	s_barrier
	s_add_i32 vcc_hi, vcc_hi, 2
	s_add_u32 s4, s4, 0x100
	s_addc_u32 s5, s5, 0
	s_add_u32 s65, s65, 0x100
	s_addc_u32 vcc_lo, vcc_lo, 0
	s_cmp_gt_u32 vcc_hi, 29
	s_cbranch_scc0 .LBB0_399
	s_and_b64 vcc, exec, s[26:27]
	s_cbranch_vccz .LBB0_402
	s_barrier

.LBB0_541:
	ds_read_b128 v[128:131], v157
	ds_read_b128 v[132:135], v157 offset:1024
	ds_read_b128 v[136:139], v157 offset:2048
	ds_read_b128 v[140:143], v157 offset:3072
	ds_read_b128 v[160:163], v158
	ds_read_b128 v[164:167], v158 offset:1024
	ds_read_b128 v[168:171], v158 offset:2048
	ds_read_b128 v[172:175], v158 offset:3072
	s_add_u32 s58, s56, 0x100
	s_addc_u32 s59, s57, 0
	s_cmpk_eq_i32 s89, 0x54
	s_cselect_b32 s63, s12, s59
	s_cselect_b32 s62, s55, s58
	s_cselect_b32 s61, s85, s88
	s_cselect_b32 s60, s86, s87
	v_lshl_add_u64 v[152:153], s[56:57], 0, v[148:149]
	s_add_i32 m0, s66, 0xc000
	ds_read_b128 v[178:181], v159
	ds_read_b128 v[182:185], v159 offset:1024
	ds_read_b128 v[186:189], v159 offset:2048
	ds_read_b128 v[190:193], v159 offset:3072
	ds_read_b128 v[194:197], v159 offset:4096
	ds_read_b128 v[206:209], v159 offset:5120
	ds_read_b128 v[210:213], v159 offset:6144
	ds_read_b128 v[214:217], v159 offset:7168
	global_load_lds_dwordx4 v[152:153], off
	v_lshl_add_u64 v[152:153], s[56:57], 0, v[150:151]
	s_add_i32 m0, s66, 0xe000
	s_nop 0
	global_load_lds_dwordx4 v[152:153], off
	s_waitcnt vmcnt(8)
	s_waitcnt lgkmcnt(0)
	s_barrier
	s_setprio 1
	v_mfma_f32_16x16x32_bf16 v[124:127], v[128:131], v[178:181], v[124:127]
	v_mfma_f32_16x16x32_bf16 v[120:123], v[136:139], v[178:181], v[120:123]
	v_mfma_f32_16x16x32_bf16 v[112:115], v[128:131], v[186:189], v[112:115]
	v_mfma_f32_16x16x32_bf16 v[108:111], v[136:139], v[186:189], v[108:111]
	v_mfma_f32_16x16x32_bf16 v[96:99], v[128:131], v[194:197], v[96:99]
	v_mfma_f32_16x16x32_bf16 v[92:95], v[136:139], v[194:197], v[92:95]
	v_mfma_f32_16x16x32_bf16 v[80:83], v[128:131], v[210:213], v[80:83]
	v_mfma_f32_16x16x32_bf16 v[76:79], v[136:139], v[210:213], v[76:79]
	v_mfma_f32_16x16x32_bf16 v[124:127], v[132:135], v[182:185], v[124:127]
	v_mfma_f32_16x16x32_bf16 v[120:123], v[140:143], v[182:185], v[120:123]
	v_mfma_f32_16x16x32_bf16 v[112:115], v[132:135], v[190:193], v[112:115]
	v_mfma_f32_16x16x32_bf16 v[108:111], v[140:143], v[190:193], v[108:111]
	v_mfma_f32_16x16x32_bf16 v[96:99], v[132:135], v[206:209], v[96:99]
	v_mfma_f32_16x16x32_bf16 v[92:95], v[140:143], v[206:209], v[92:95]
	v_mfma_f32_16x16x32_bf16 v[80:83], v[132:135], v[214:217], v[80:83]
	v_mfma_f32_16x16x32_bf16 v[76:79], v[140:143], v[214:217], v[76:79]
	v_mfma_f32_16x16x32_bf16 v[116:119], v[160:163], v[178:181], v[116:119]
	v_mfma_f32_16x16x32_bf16 v[104:107], v[168:171], v[178:181], v[104:107]
	v_mfma_f32_16x16x32_bf16 v[100:103], v[160:163], v[186:189], v[100:103]
	v_mfma_f32_16x16x32_bf16 v[88:91], v[168:171], v[186:189], v[88:91]
	v_mfma_f32_16x16x32_bf16 v[84:87], v[160:163], v[194:197], v[84:87]
	v_mfma_f32_16x16x32_bf16 v[72:75], v[168:171], v[194:197], v[72:75]
	v_mfma_f32_16x16x32_bf16 v[68:71], v[160:163], v[210:213], v[68:71]
	v_mfma_f32_16x16x32_bf16 v[64:67], v[168:171], v[210:213], v[64:67]
	v_mfma_f32_16x16x32_bf16 v[116:119], v[164:167], v[182:185], v[116:119]
	v_mfma_f32_16x16x32_bf16 v[104:107], v[172:175], v[182:185], v[104:107]
	v_mfma_f32_16x16x32_bf16 v[100:103], v[164:167], v[190:193], v[100:103]
	v_mfma_f32_16x16x32_bf16 v[88:91], v[172:175], v[190:193], v[88:91]
	v_mfma_f32_16x16x32_bf16 v[84:87], v[164:167], v[206:209], v[84:87]
	v_mfma_f32_16x16x32_bf16 v[72:75], v[172:175], v[206:209], v[72:75]
	v_mfma_f32_16x16x32_bf16 v[68:71], v[164:167], v[214:217], v[68:71]
	v_mfma_f32_16x16x32_bf16 v[64:67], v[172:175], v[214:217], v[64:67]
	s_setprio 0
	s_barrier
	s_add_i32 s0, s79, s65
	v_lshl_add_u64 v[152:153], s[60:61], 0, v[146:147]
	s_mov_b32 m0, s0
	ds_read_b128 v[178:181], v159 offset:16384
	ds_read_b128 v[182:185], v159 offset:17408
	ds_read_b128 v[186:189], v159 offset:18432
	ds_read_b128 v[190:193], v159 offset:19456
	ds_read_b128 v[194:197], v159 offset:20480
	ds_read_b128 v[206:209], v159 offset:21504
	ds_read_b128 v[210:213], v159 offset:22528
	ds_read_b128 v[214:217], v159 offset:23552
	global_load_lds_dwordx4 v[152:153], off
	s_add_i32 m0, s0, 0x2000
	s_add_u32 s0, s60, 0x160000
	v_lshl_add_u64 v[198:199], s[60:61], 0, v[144:145]
	s_addc_u32 s1, s61, 0
	s_add_i32 s2, s80, s65
	global_load_lds_dwordx4 v[198:199], off
	v_lshl_add_u64 v[202:203], s[0:1], 0, v[146:147]
	s_mov_b32 m0, s2
	v_lshl_add_u64 v[218:219], s[62:63], 0, v[144:145]
	global_load_lds_dwordx4 v[202:203], off
	v_lshl_add_u64 v[202:203], s[0:1], 0, v[144:145]
	s_add_i32 m0, s2, 0x2000
	s_nop 0
	global_load_lds_dwordx4 v[202:203], off
	v_lshl_add_u64 v[202:203], s[62:63], 0, v[146:147]
	s_mov_b32 m0, s66
	s_nop 0
	global_load_lds_dwordx4 v[202:203], off
	s_mov_b32 m0, s67
	s_nop 0
	global_load_lds_dwordx4 v[218:219], off
	s_waitcnt vmcnt(8)
	s_waitcnt lgkmcnt(0)
	s_barrier
	s_setprio 1
	v_mfma_f32_16x16x32_bf16 v[60:63], v[128:131], v[178:181], v[60:63]
	v_mfma_f32_16x16x32_bf16 v[56:59], v[136:139], v[178:181], v[56:59]
	v_mfma_f32_16x16x32_bf16 v[48:51], v[128:131], v[186:189], v[48:51]
	v_mfma_f32_16x16x32_bf16 v[44:47], v[136:139], v[186:189], v[44:47]
	v_mfma_f32_16x16x32_bf16 v[32:35], v[128:131], v[194:197], v[32:35]
	v_mfma_f32_16x16x32_bf16 v[28:31], v[136:139], v[194:197], v[28:31]
	v_mfma_f32_16x16x32_bf16 v[16:19], v[128:131], v[210:213], v[16:19]
	v_mfma_f32_16x16x32_bf16 v[12:15], v[136:139], v[210:213], v[12:15]
	v_mfma_f32_16x16x32_bf16 v[60:63], v[132:135], v[182:185], v[60:63]
	v_mfma_f32_16x16x32_bf16 v[56:59], v[140:143], v[182:185], v[56:59]
	v_mfma_f32_16x16x32_bf16 v[48:51], v[132:135], v[190:193], v[48:51]
	v_mfma_f32_16x16x32_bf16 v[44:47], v[140:143], v[190:193], v[44:47]
	v_mfma_f32_16x16x32_bf16 v[32:35], v[132:135], v[206:209], v[32:35]
	v_mfma_f32_16x16x32_bf16 v[28:31], v[140:143], v[206:209], v[28:31]
	v_mfma_f32_16x16x32_bf16 v[16:19], v[132:135], v[214:217], v[16:19]
	v_mfma_f32_16x16x32_bf16 v[12:15], v[140:143], v[214:217], v[12:15]
	v_mfma_f32_16x16x32_bf16 v[52:55], v[160:163], v[178:181], v[52:55]
	v_mfma_f32_16x16x32_bf16 v[40:43], v[168:171], v[178:181], v[40:43]
	v_mfma_f32_16x16x32_bf16 v[36:39], v[160:163], v[186:189], v[36:39]
	v_mfma_f32_16x16x32_bf16 v[24:27], v[168:171], v[186:189], v[24:27]
	v_mfma_f32_16x16x32_bf16 v[20:23], v[160:163], v[194:197], v[20:23]
	v_mfma_f32_16x16x32_bf16 v[8:11], v[168:171], v[194:197], v[8:11]
	v_mfma_f32_16x16x32_bf16 v[4:7], v[160:163], v[210:213], v[4:7]
	v_mfma_f32_16x16x32_bf16 v[0:3], v[168:171], v[210:213], v[0:3]
	v_mfma_f32_16x16x32_bf16 v[52:55], v[164:167], v[182:185], v[52:55]
	v_mfma_f32_16x16x32_bf16 v[40:43], v[172:175], v[182:185], v[40:43]
	v_mfma_f32_16x16x32_bf16 v[36:39], v[164:167], v[190:193], v[36:39]
	v_mfma_f32_16x16x32_bf16 v[24:27], v[172:175], v[190:193], v[24:27]
	v_mfma_f32_16x16x32_bf16 v[20:23], v[164:167], v[206:209], v[20:23]
	v_mfma_f32_16x16x32_bf16 v[8:11], v[172:175], v[206:209], v[8:11]
	v_mfma_f32_16x16x32_bf16 v[4:7], v[164:167], v[214:217], v[4:7]
	v_mfma_f32_16x16x32_bf16 v[0:3], v[172:175], v[214:217], v[0:3]
	s_setprio 0
	s_barrier
	s_add_i32 s2, 0, 0x18000
	s_add_i32 s3, 0, 0x1c000
	v_add_u32_e32 v140, s2, v156
	v_add_u32_e32 v172, s3, v156
	ds_read_b128 v[128:131], v140
	ds_read_b128 v[132:135], v140 offset:1024
	ds_read_b128 v[136:139], v140 offset:2048
	ds_read_b128 v[140:143], v140 offset:3072
	ds_read_b128 v[160:163], v172
	ds_read_b128 v[164:167], v172 offset:1024
	ds_read_b128 v[168:171], v172 offset:2048
	ds_read_b128 v[172:175], v172 offset:3072
	s_add_u32 s0, s62, 0x160000
	s_addc_u32 s1, s63, 0
	s_mov_b32 m0, s68
	v_lshl_add_u64 v[220:221], s[0:1], 0, v[146:147]
	ds_read_b128 v[178:181], v159 offset:32768
	ds_read_b128 v[182:185], v159 offset:33792
	ds_read_b128 v[186:189], v159 offset:34816
	ds_read_b128 v[190:193], v159 offset:35840
	ds_read_b128 v[194:197], v159 offset:36864
	ds_read_b128 v[206:209], v159 offset:37888
	ds_read_b128 v[210:213], v159 offset:38912
	ds_read_b128 v[214:217], v159 offset:39936
	global_load_lds_dwordx4 v[220:221], off
	v_lshl_add_u64 v[220:221], s[0:1], 0, v[144:145]
	s_mov_b32 m0, s69
	s_nop 0
	global_load_lds_dwordx4 v[220:221], off
	s_waitcnt vmcnt(8)
	s_waitcnt lgkmcnt(0)
	s_barrier
	s_setprio 1
	v_mfma_f32_16x16x32_bf16 v[124:127], v[128:131], v[178:181], v[124:127]
	v_mfma_f32_16x16x32_bf16 v[120:123], v[136:139], v[178:181], v[120:123]
	v_mfma_f32_16x16x32_bf16 v[112:115], v[128:131], v[186:189], v[112:115]
	v_mfma_f32_16x16x32_bf16 v[108:111], v[136:139], v[186:189], v[108:111]
	v_mfma_f32_16x16x32_bf16 v[96:99], v[128:131], v[194:197], v[96:99]
	v_mfma_f32_16x16x32_bf16 v[92:95], v[136:139], v[194:197], v[92:95]
	v_mfma_f32_16x16x32_bf16 v[80:83], v[128:131], v[210:213], v[80:83]
	v_mfma_f32_16x16x32_bf16 v[76:79], v[136:139], v[210:213], v[76:79]
	v_mfma_f32_16x16x32_bf16 v[124:127], v[132:135], v[182:185], v[124:127]
	v_mfma_f32_16x16x32_bf16 v[120:123], v[140:143], v[182:185], v[120:123]
	v_mfma_f32_16x16x32_bf16 v[112:115], v[132:135], v[190:193], v[112:115]
	v_mfma_f32_16x16x32_bf16 v[108:111], v[140:143], v[190:193], v[108:111]
	v_mfma_f32_16x16x32_bf16 v[96:99], v[132:135], v[206:209], v[96:99]
	v_mfma_f32_16x16x32_bf16 v[92:95], v[140:143], v[206:209], v[92:95]
	v_mfma_f32_16x16x32_bf16 v[80:83], v[132:135], v[214:217], v[80:83]
	v_mfma_f32_16x16x32_bf16 v[76:79], v[140:143], v[214:217], v[76:79]
	v_mfma_f32_16x16x32_bf16 v[116:119], v[160:163], v[178:181], v[116:119]
	v_mfma_f32_16x16x32_bf16 v[104:107], v[168:171], v[178:181], v[104:107]
	v_mfma_f32_16x16x32_bf16 v[100:103], v[160:163], v[186:189], v[100:103]
	v_mfma_f32_16x16x32_bf16 v[88:91], v[168:171], v[186:189], v[88:91]
	v_mfma_f32_16x16x32_bf16 v[84:87], v[160:163], v[194:197], v[84:87]
	v_mfma_f32_16x16x32_bf16 v[72:75], v[168:171], v[194:197], v[72:75]
	v_mfma_f32_16x16x32_bf16 v[68:71], v[160:163], v[210:213], v[68:71]
	v_mfma_f32_16x16x32_bf16 v[64:67], v[168:171], v[210:213], v[64:67]
	v_mfma_f32_16x16x32_bf16 v[116:119], v[164:167], v[182:185], v[116:119]
	v_mfma_f32_16x16x32_bf16 v[104:107], v[172:175], v[182:185], v[104:107]
	v_mfma_f32_16x16x32_bf16 v[100:103], v[164:167], v[190:193], v[100:103]
	v_mfma_f32_16x16x32_bf16 v[88:91], v[172:175], v[190:193], v[88:91]
	v_mfma_f32_16x16x32_bf16 v[84:87], v[164:167], v[206:209], v[84:87]
	v_mfma_f32_16x16x32_bf16 v[72:75], v[172:175], v[206:209], v[72:75]
	v_mfma_f32_16x16x32_bf16 v[68:71], v[164:167], v[214:217], v[68:71]
	v_mfma_f32_16x16x32_bf16 v[64:67], v[172:175], v[214:217], v[64:67]
	s_setprio 0
	s_barrier
	s_add_i32 s0, s2, s65
	v_lshl_add_u64 v[152:153], v[152:153], 0, s[10:11]
	s_mov_b32 m0, s0
	ds_read_b128 v[178:181], v159 offset:49152
	ds_read_b128 v[182:185], v159 offset:50176
	ds_read_b128 v[186:189], v159 offset:51200
	ds_read_b128 v[190:193], v159 offset:52224
	ds_read_b128 v[194:197], v159 offset:53248
	ds_read_b128 v[206:209], v159 offset:54272
	ds_read_b128 v[210:213], v159 offset:55296
	ds_read_b128 v[214:217], v159 offset:56320
	global_load_lds_dwordx4 v[152:153], off
	s_add_i32 m0, s0, 0x2000
	s_add_u32 s0, s60, 0x160080
	v_lshl_add_u64 v[152:153], v[198:199], 0, s[10:11]
	s_addc_u32 s1, s61, 0
	s_add_i32 s2, s3, s65
	global_load_lds_dwordx4 v[152:153], off
	v_lshl_add_u64 v[152:153], s[0:1], 0, v[146:147]
	s_mov_b32 m0, s2
	s_nop 0
	global_load_lds_dwordx4 v[152:153], off
	v_lshl_add_u64 v[152:153], s[0:1], 0, v[144:145]
	s_add_i32 m0, s2, 0x2000
	s_nop 0
	global_load_lds_dwordx4 v[152:153], off
	v_lshl_add_u64 v[152:153], v[202:203], 0, s[10:11]
	s_mov_b32 m0, s77
	s_nop 0
	global_load_lds_dwordx4 v[152:153], off
	v_lshl_add_u64 v[152:153], v[218:219], 0, s[10:11]
	s_mov_b32 m0, s78
	s_nop 0
	global_load_lds_dwordx4 v[152:153], off
	s_waitcnt vmcnt(8)
	s_waitcnt lgkmcnt(0)
	s_barrier
	s_setprio 1
	v_mfma_f32_16x16x32_bf16 v[60:63], v[128:131], v[178:181], v[60:63]
	v_mfma_f32_16x16x32_bf16 v[56:59], v[136:139], v[178:181], v[56:59]
	v_mfma_f32_16x16x32_bf16 v[48:51], v[128:131], v[186:189], v[48:51]
	v_mfma_f32_16x16x32_bf16 v[44:47], v[136:139], v[186:189], v[44:47]
	v_mfma_f32_16x16x32_bf16 v[32:35], v[128:131], v[194:197], v[32:35]
	v_mfma_f32_16x16x32_bf16 v[28:31], v[136:139], v[194:197], v[28:31]
	v_mfma_f32_16x16x32_bf16 v[16:19], v[128:131], v[210:213], v[16:19]
	v_mfma_f32_16x16x32_bf16 v[12:15], v[136:139], v[210:213], v[12:15]
	v_mfma_f32_16x16x32_bf16 v[60:63], v[132:135], v[182:185], v[60:63]
	v_mfma_f32_16x16x32_bf16 v[56:59], v[140:143], v[182:185], v[56:59]
	v_mfma_f32_16x16x32_bf16 v[48:51], v[132:135], v[190:193], v[48:51]
	v_mfma_f32_16x16x32_bf16 v[44:47], v[140:143], v[190:193], v[44:47]
	v_mfma_f32_16x16x32_bf16 v[32:35], v[132:135], v[206:209], v[32:35]
	v_mfma_f32_16x16x32_bf16 v[28:31], v[140:143], v[206:209], v[28:31]
	v_mfma_f32_16x16x32_bf16 v[16:19], v[132:135], v[214:217], v[16:19]
	v_mfma_f32_16x16x32_bf16 v[12:15], v[140:143], v[214:217], v[12:15]
	v_mfma_f32_16x16x32_bf16 v[52:55], v[160:163], v[178:181], v[52:55]
	v_mfma_f32_16x16x32_bf16 v[40:43], v[168:171], v[178:181], v[40:43]
	v_mfma_f32_16x16x32_bf16 v[36:39], v[160:163], v[186:189], v[36:39]
	v_mfma_f32_16x16x32_bf16 v[24:27], v[168:171], v[186:189], v[24:27]
	v_mfma_f32_16x16x32_bf16 v[20:23], v[160:163], v[194:197], v[20:23]
	v_mfma_f32_16x16x32_bf16 v[8:11], v[168:171], v[194:197], v[8:11]
	v_mfma_f32_16x16x32_bf16 v[4:7], v[160:163], v[210:213], v[4:7]
	v_mfma_f32_16x16x32_bf16 v[0:3], v[168:171], v[210:213], v[0:3]
	v_mfma_f32_16x16x32_bf16 v[52:55], v[164:167], v[182:185], v[52:55]
	v_mfma_f32_16x16x32_bf16 v[40:43], v[172:175], v[182:185], v[40:43]
	v_mfma_f32_16x16x32_bf16 v[36:39], v[164:167], v[190:193], v[36:39]
	v_mfma_f32_16x16x32_bf16 v[24:27], v[172:175], v[190:193], v[24:27]
	v_mfma_f32_16x16x32_bf16 v[20:23], v[164:167], v[206:209], v[20:23]
	v_mfma_f32_16x16x32_bf16 v[8:11], v[172:175], v[206:209], v[8:11]
	v_mfma_f32_16x16x32_bf16 v[4:7], v[164:167], v[214:217], v[4:7]
	v_mfma_f32_16x16x32_bf16 v[0:3], v[172:175], v[214:217], v[0:3]
	s_setprio 0
	s_barrier
	s_add_i32 s89, s89, 2
	s_add_u32 s87, s87, 0x100
	s_addc_u32 s88, s88, 0
	s_cmpk_gt_u32 s89, 0x55
	s_mov_b64 s[56:57], s[58:59]
	s_cbranch_scc0 .LBB0_541
	s_and_b64 vcc, exec, s[14:15]
	s_cbranch_vccz .LBB0_544
	s_barrier

.LBB0_666:
	ds_read_b128 v[140:143], v147
	ds_read_b128 v[150:153], v147 offset:1024
	ds_read_b128 v[154:157], v147 offset:2048
	ds_read_b128 v[158:161], v147 offset:3072
	ds_read_b128 v[162:165], v148
	ds_read_b128 v[166:169], v148 offset:1024
	ds_read_b128 v[170:173], v148 offset:2048
	ds_read_b128 v[178:181], v148 offset:3072
	s_add_u32 s0, s28, 0xfff80080
	s_addc_u32 s1, s29, -1
	s_cmp_eq_u32 s71, 28
	s_cselect_b32 s35, s15, s1
	s_cselect_b32 s34, s66, s0
	s_cselect_b32 s31, s67, s70
	s_cselect_b32 s30, s68, s69
	v_lshl_add_u64 v[174:175], s[28:29], 0, v[136:137]
	s_add_i32 m0, s27, 0xc000
	ds_read_b128 v[182:185], v149
	ds_read_b128 v[186:189], v149 offset:1024
	ds_read_b128 v[190:193], v149 offset:2048
	ds_read_b128 v[194:197], v149 offset:3072
	ds_read_b128 v[206:209], v149 offset:4096
	ds_read_b128 v[210:213], v149 offset:5120
	ds_read_b128 v[214:217], v149 offset:6144
	ds_read_b128 v[218:221], v149 offset:7168
	global_load_lds_dwordx4 v[174:175], off
	v_lshl_add_u64 v[174:175], s[28:29], 0, v[138:139]
	s_add_i32 m0, s27, 0xe000
	s_nop 0
	global_load_lds_dwordx4 v[174:175], off
	s_waitcnt vmcnt(8)
	s_waitcnt lgkmcnt(0)
	s_barrier
	s_setprio 1
	v_mfma_f32_16x16x32_bf16 v[124:127], v[140:143], v[182:185], v[124:127]
	v_mfma_f32_16x16x32_bf16 v[120:123], v[154:157], v[182:185], v[120:123]
	v_mfma_f32_16x16x32_bf16 v[116:119], v[140:143], v[190:193], v[116:119]
	v_mfma_f32_16x16x32_bf16 v[108:111], v[154:157], v[190:193], v[108:111]
	v_mfma_f32_16x16x32_bf16 v[100:103], v[140:143], v[206:209], v[100:103]
	v_mfma_f32_16x16x32_bf16 v[92:95], v[154:157], v[206:209], v[92:95]
	v_mfma_f32_16x16x32_bf16 v[84:87], v[140:143], v[214:217], v[84:87]
	v_mfma_f32_16x16x32_bf16 v[76:79], v[154:157], v[214:217], v[76:79]
	v_mfma_f32_16x16x32_bf16 v[124:127], v[150:153], v[186:189], v[124:127]
	v_mfma_f32_16x16x32_bf16 v[120:123], v[158:161], v[186:189], v[120:123]
	v_mfma_f32_16x16x32_bf16 v[116:119], v[150:153], v[194:197], v[116:119]
	v_mfma_f32_16x16x32_bf16 v[108:111], v[158:161], v[194:197], v[108:111]
	v_mfma_f32_16x16x32_bf16 v[100:103], v[150:153], v[210:213], v[100:103]
	v_mfma_f32_16x16x32_bf16 v[92:95], v[158:161], v[210:213], v[92:95]
	v_mfma_f32_16x16x32_bf16 v[84:87], v[150:153], v[218:221], v[84:87]
	v_mfma_f32_16x16x32_bf16 v[76:79], v[158:161], v[218:221], v[76:79]
	v_mfma_f32_16x16x32_bf16 v[112:115], v[162:165], v[182:185], v[112:115]
	v_mfma_f32_16x16x32_bf16 v[104:107], v[170:173], v[182:185], v[104:107]
	v_mfma_f32_16x16x32_bf16 v[96:99], v[162:165], v[190:193], v[96:99]
	v_mfma_f32_16x16x32_bf16 v[88:91], v[170:173], v[190:193], v[88:91]
	v_mfma_f32_16x16x32_bf16 v[80:83], v[162:165], v[206:209], v[80:83]
	v_mfma_f32_16x16x32_bf16 v[72:75], v[170:173], v[206:209], v[72:75]
	v_mfma_f32_16x16x32_bf16 v[68:71], v[162:165], v[214:217], v[68:71]
	v_mfma_f32_16x16x32_bf16 v[64:67], v[170:173], v[214:217], v[64:67]
	v_mfma_f32_16x16x32_bf16 v[112:115], v[166:169], v[186:189], v[112:115]
	v_mfma_f32_16x16x32_bf16 v[104:107], v[178:181], v[186:189], v[104:107]
	v_mfma_f32_16x16x32_bf16 v[96:99], v[166:169], v[194:197], v[96:99]
	v_mfma_f32_16x16x32_bf16 v[88:91], v[178:181], v[194:197], v[88:91]
	v_mfma_f32_16x16x32_bf16 v[80:83], v[166:169], v[210:213], v[80:83]
	v_mfma_f32_16x16x32_bf16 v[72:75], v[178:181], v[210:213], v[72:75]
	v_mfma_f32_16x16x32_bf16 v[68:71], v[166:169], v[218:221], v[68:71]
	v_mfma_f32_16x16x32_bf16 v[64:67], v[178:181], v[218:221], v[64:67]
	s_setprio 0
	s_barrier
	s_add_i32 s0, s62, s53
	v_lshl_add_u64 v[174:175], s[30:31], 0, v[132:133]
	s_mov_b32 m0, s0
	ds_read_b128 v[182:185], v149 offset:16384
	ds_read_b128 v[186:189], v149 offset:17408
	ds_read_b128 v[190:193], v149 offset:18432
	ds_read_b128 v[194:197], v149 offset:19456
	ds_read_b128 v[206:209], v149 offset:20480
	ds_read_b128 v[210:213], v149 offset:21504
	ds_read_b128 v[214:217], v149 offset:22528
	ds_read_b128 v[218:221], v149 offset:23552
	global_load_lds_dwordx4 v[174:175], off
	s_add_i32 m0, s0, 0x2000
	s_add_u32 s0, s30, 0x80000
	v_lshl_add_u64 v[198:199], s[30:31], 0, v[128:129]
	s_addc_u32 s1, s31, 0
	s_add_i32 s2, s63, s53
	global_load_lds_dwordx4 v[198:199], off
	v_lshl_add_u64 v[202:203], s[0:1], 0, v[132:133]
	s_mov_b32 m0, s2
	v_lshl_add_u64 v[222:223], s[34:35], 0, v[130:131]
	global_load_lds_dwordx4 v[202:203], off
	v_lshl_add_u64 v[202:203], s[0:1], 0, v[128:129]
	s_add_i32 m0, s2, 0x2000
	s_nop 0
	global_load_lds_dwordx4 v[202:203], off
	v_lshl_add_u64 v[202:203], s[34:35], 0, v[134:135]
	s_mov_b32 m0, s27
	s_nop 0
	global_load_lds_dwordx4 v[202:203], off
	s_mov_b32 m0, s55
	s_nop 0
	global_load_lds_dwordx4 v[222:223], off
	s_waitcnt vmcnt(8)
	s_waitcnt lgkmcnt(0)
	s_barrier
	s_setprio 1
	v_mfma_f32_16x16x32_bf16 v[60:63], v[140:143], v[182:185], v[60:63]
	v_mfma_f32_16x16x32_bf16 v[56:59], v[154:157], v[182:185], v[56:59]
	v_mfma_f32_16x16x32_bf16 v[52:55], v[140:143], v[190:193], v[52:55]
	v_mfma_f32_16x16x32_bf16 v[44:47], v[154:157], v[190:193], v[44:47]
	v_mfma_f32_16x16x32_bf16 v[36:39], v[140:143], v[206:209], v[36:39]
	v_mfma_f32_16x16x32_bf16 v[28:31], v[154:157], v[206:209], v[28:31]
	v_mfma_f32_16x16x32_bf16 v[20:23], v[140:143], v[214:217], v[20:23]
	v_mfma_f32_16x16x32_bf16 v[12:15], v[154:157], v[214:217], v[12:15]
	v_mfma_f32_16x16x32_bf16 v[60:63], v[150:153], v[186:189], v[60:63]
	v_mfma_f32_16x16x32_bf16 v[56:59], v[158:161], v[186:189], v[56:59]
	v_mfma_f32_16x16x32_bf16 v[52:55], v[150:153], v[194:197], v[52:55]
	v_mfma_f32_16x16x32_bf16 v[44:47], v[158:161], v[194:197], v[44:47]
	v_mfma_f32_16x16x32_bf16 v[36:39], v[150:153], v[210:213], v[36:39]
	v_mfma_f32_16x16x32_bf16 v[28:31], v[158:161], v[210:213], v[28:31]
	v_mfma_f32_16x16x32_bf16 v[20:23], v[150:153], v[218:221], v[20:23]
	v_mfma_f32_16x16x32_bf16 v[12:15], v[158:161], v[218:221], v[12:15]
	v_mfma_f32_16x16x32_bf16 v[48:51], v[162:165], v[182:185], v[48:51]
	v_mfma_f32_16x16x32_bf16 v[40:43], v[170:173], v[182:185], v[40:43]
	v_mfma_f32_16x16x32_bf16 v[32:35], v[162:165], v[190:193], v[32:35]
	v_mfma_f32_16x16x32_bf16 v[24:27], v[170:173], v[190:193], v[24:27]
	v_mfma_f32_16x16x32_bf16 v[16:19], v[162:165], v[206:209], v[16:19]
	v_mfma_f32_16x16x32_bf16 v[8:11], v[170:173], v[206:209], v[8:11]
	v_mfma_f32_16x16x32_bf16 v[4:7], v[162:165], v[214:217], v[4:7]
	v_mfma_f32_16x16x32_bf16 v[0:3], v[170:173], v[214:217], v[0:3]
	v_mfma_f32_16x16x32_bf16 v[48:51], v[166:169], v[186:189], v[48:51]
	v_mfma_f32_16x16x32_bf16 v[40:43], v[178:181], v[186:189], v[40:43]
	v_mfma_f32_16x16x32_bf16 v[32:35], v[166:169], v[194:197], v[32:35]
	v_mfma_f32_16x16x32_bf16 v[24:27], v[178:181], v[194:197], v[24:27]
	v_mfma_f32_16x16x32_bf16 v[16:19], v[166:169], v[210:213], v[16:19]
	v_mfma_f32_16x16x32_bf16 v[8:11], v[178:181], v[210:213], v[8:11]
	v_mfma_f32_16x16x32_bf16 v[4:7], v[166:169], v[218:221], v[4:7]
	v_mfma_f32_16x16x32_bf16 v[0:3], v[178:181], v[218:221], v[0:3]
	s_setprio 0
	s_barrier
	s_add_i32 s2, 0, 0x18000
	s_add_i32 s3, 0, 0x1c000
	v_add_u32_e32 v158, s2, v146
	v_add_u32_e32 v177, s3, v146
	ds_read_b128 v[140:143], v158
	ds_read_b128 v[150:153], v158 offset:1024
	ds_read_b128 v[154:157], v158 offset:2048
	ds_read_b128 v[158:161], v158 offset:3072
	ds_read_b128 v[162:165], v177
	ds_read_b128 v[166:169], v177 offset:1024
	ds_read_b128 v[170:173], v177 offset:2048
	ds_read_b128 v[178:181], v177 offset:3072
	s_add_u32 s0, s34, 0x80000
	s_addc_u32 s1, s35, 0
	s_mov_b32 m0, s56
	v_lshl_add_u64 v[224:225], s[0:1], 0, v[134:135]
	ds_read_b128 v[182:185], v149 offset:32768
	ds_read_b128 v[186:189], v149 offset:33792
	ds_read_b128 v[190:193], v149 offset:34816
	ds_read_b128 v[194:197], v149 offset:35840
	ds_read_b128 v[206:209], v149 offset:36864
	ds_read_b128 v[210:213], v149 offset:37888
	ds_read_b128 v[214:217], v149 offset:38912
	ds_read_b128 v[218:221], v149 offset:39936
	global_load_lds_dwordx4 v[224:225], off
	v_lshl_add_u64 v[224:225], s[0:1], 0, v[130:131]
	s_mov_b32 m0, s57
	s_nop 0
	global_load_lds_dwordx4 v[224:225], off
	s_waitcnt vmcnt(8)
	s_waitcnt lgkmcnt(0)
	s_barrier
	s_setprio 1
	v_mfma_f32_16x16x32_bf16 v[124:127], v[140:143], v[182:185], v[124:127]
	v_mfma_f32_16x16x32_bf16 v[120:123], v[154:157], v[182:185], v[120:123]
	v_mfma_f32_16x16x32_bf16 v[116:119], v[140:143], v[190:193], v[116:119]
	v_mfma_f32_16x16x32_bf16 v[108:111], v[154:157], v[190:193], v[108:111]
	v_mfma_f32_16x16x32_bf16 v[100:103], v[140:143], v[206:209], v[100:103]
	v_mfma_f32_16x16x32_bf16 v[92:95], v[154:157], v[206:209], v[92:95]
	v_mfma_f32_16x16x32_bf16 v[84:87], v[140:143], v[214:217], v[84:87]
	v_mfma_f32_16x16x32_bf16 v[76:79], v[154:157], v[214:217], v[76:79]
	v_mfma_f32_16x16x32_bf16 v[124:127], v[150:153], v[186:189], v[124:127]
	v_mfma_f32_16x16x32_bf16 v[120:123], v[158:161], v[186:189], v[120:123]
	v_mfma_f32_16x16x32_bf16 v[116:119], v[150:153], v[194:197], v[116:119]
	v_mfma_f32_16x16x32_bf16 v[108:111], v[158:161], v[194:197], v[108:111]
	v_mfma_f32_16x16x32_bf16 v[100:103], v[150:153], v[210:213], v[100:103]
	v_mfma_f32_16x16x32_bf16 v[92:95], v[158:161], v[210:213], v[92:95]
	v_mfma_f32_16x16x32_bf16 v[84:87], v[150:153], v[218:221], v[84:87]
	v_mfma_f32_16x16x32_bf16 v[76:79], v[158:161], v[218:221], v[76:79]
	v_mfma_f32_16x16x32_bf16 v[112:115], v[162:165], v[182:185], v[112:115]
	v_mfma_f32_16x16x32_bf16 v[104:107], v[170:173], v[182:185], v[104:107]
	v_mfma_f32_16x16x32_bf16 v[96:99], v[162:165], v[190:193], v[96:99]
	v_mfma_f32_16x16x32_bf16 v[88:91], v[170:173], v[190:193], v[88:91]
	v_mfma_f32_16x16x32_bf16 v[80:83], v[162:165], v[206:209], v[80:83]
	v_mfma_f32_16x16x32_bf16 v[72:75], v[170:173], v[206:209], v[72:75]
	v_mfma_f32_16x16x32_bf16 v[68:71], v[162:165], v[214:217], v[68:71]
	v_mfma_f32_16x16x32_bf16 v[64:67], v[170:173], v[214:217], v[64:67]
	v_mfma_f32_16x16x32_bf16 v[112:115], v[166:169], v[186:189], v[112:115]
	v_mfma_f32_16x16x32_bf16 v[104:107], v[178:181], v[186:189], v[104:107]
	v_mfma_f32_16x16x32_bf16 v[96:99], v[166:169], v[194:197], v[96:99]
	v_mfma_f32_16x16x32_bf16 v[88:91], v[178:181], v[194:197], v[88:91]
	v_mfma_f32_16x16x32_bf16 v[80:83], v[166:169], v[210:213], v[80:83]
	v_mfma_f32_16x16x32_bf16 v[72:75], v[178:181], v[210:213], v[72:75]
	v_mfma_f32_16x16x32_bf16 v[68:71], v[166:169], v[218:221], v[68:71]
	v_mfma_f32_16x16x32_bf16 v[64:67], v[178:181], v[218:221], v[64:67]
	s_setprio 0
	s_barrier
	s_add_i32 s0, s2, s53
	v_lshl_add_u64 v[174:175], v[174:175], 0, s[8:9]
	s_mov_b32 m0, s0
	ds_read_b128 v[182:185], v149 offset:49152
	ds_read_b128 v[186:189], v149 offset:50176
	ds_read_b128 v[190:193], v149 offset:51200
	ds_read_b128 v[194:197], v149 offset:52224
	ds_read_b128 v[206:209], v149 offset:53248
	ds_read_b128 v[210:213], v149 offset:54272
	ds_read_b128 v[214:217], v149 offset:55296
	ds_read_b128 v[218:221], v149 offset:56320
	global_load_lds_dwordx4 v[174:175], off
	s_add_i32 m0, s0, 0x2000
	s_add_u32 s0, s30, 0x80080
	v_lshl_add_u64 v[174:175], v[198:199], 0, s[8:9]
	s_addc_u32 s1, s31, 0
	s_add_i32 s2, s3, s53
	global_load_lds_dwordx4 v[174:175], off
	v_lshl_add_u64 v[174:175], s[0:1], 0, v[132:133]
	s_mov_b32 m0, s2
	s_nop 0
	global_load_lds_dwordx4 v[174:175], off
	v_lshl_add_u64 v[174:175], s[0:1], 0, v[128:129]
	s_add_i32 m0, s2, 0x2000
	s_nop 0
	global_load_lds_dwordx4 v[174:175], off
	v_lshl_add_u64 v[174:175], v[202:203], 0, s[8:9]
	s_mov_b32 m0, s60
	s_nop 0
	global_load_lds_dwordx4 v[174:175], off
	v_lshl_add_u64 v[174:175], v[222:223], 0, s[8:9]
	s_mov_b32 m0, s61
	s_nop 0
	global_load_lds_dwordx4 v[174:175], off
	s_waitcnt vmcnt(8)
	s_waitcnt lgkmcnt(0)
	s_barrier
	s_setprio 1
	v_mfma_f32_16x16x32_bf16 v[60:63], v[140:143], v[182:185], v[60:63]
	v_mfma_f32_16x16x32_bf16 v[56:59], v[154:157], v[182:185], v[56:59]
	v_mfma_f32_16x16x32_bf16 v[52:55], v[140:143], v[190:193], v[52:55]
	v_mfma_f32_16x16x32_bf16 v[44:47], v[154:157], v[190:193], v[44:47]
	v_mfma_f32_16x16x32_bf16 v[36:39], v[140:143], v[206:209], v[36:39]
	v_mfma_f32_16x16x32_bf16 v[28:31], v[154:157], v[206:209], v[28:31]
	v_mfma_f32_16x16x32_bf16 v[20:23], v[140:143], v[214:217], v[20:23]
	v_mfma_f32_16x16x32_bf16 v[12:15], v[154:157], v[214:217], v[12:15]
	v_mfma_f32_16x16x32_bf16 v[60:63], v[150:153], v[186:189], v[60:63]
	v_mfma_f32_16x16x32_bf16 v[56:59], v[158:161], v[186:189], v[56:59]
	v_mfma_f32_16x16x32_bf16 v[52:55], v[150:153], v[194:197], v[52:55]
	v_mfma_f32_16x16x32_bf16 v[44:47], v[158:161], v[194:197], v[44:47]
	v_mfma_f32_16x16x32_bf16 v[36:39], v[150:153], v[210:213], v[36:39]
	v_mfma_f32_16x16x32_bf16 v[28:31], v[158:161], v[210:213], v[28:31]
	v_mfma_f32_16x16x32_bf16 v[20:23], v[150:153], v[218:221], v[20:23]
	v_mfma_f32_16x16x32_bf16 v[12:15], v[158:161], v[218:221], v[12:15]
	v_mfma_f32_16x16x32_bf16 v[48:51], v[162:165], v[182:185], v[48:51]
	v_mfma_f32_16x16x32_bf16 v[40:43], v[170:173], v[182:185], v[40:43]
	v_mfma_f32_16x16x32_bf16 v[32:35], v[162:165], v[190:193], v[32:35]
	v_mfma_f32_16x16x32_bf16 v[24:27], v[170:173], v[190:193], v[24:27]
	v_mfma_f32_16x16x32_bf16 v[16:19], v[162:165], v[206:209], v[16:19]
	v_mfma_f32_16x16x32_bf16 v[8:11], v[170:173], v[206:209], v[8:11]
	v_mfma_f32_16x16x32_bf16 v[4:7], v[162:165], v[214:217], v[4:7]
	v_mfma_f32_16x16x32_bf16 v[0:3], v[170:173], v[214:217], v[0:3]
	v_mfma_f32_16x16x32_bf16 v[48:51], v[166:169], v[186:189], v[48:51]
	v_mfma_f32_16x16x32_bf16 v[40:43], v[178:181], v[186:189], v[40:43]
	v_mfma_f32_16x16x32_bf16 v[32:35], v[166:169], v[194:197], v[32:35]
	v_mfma_f32_16x16x32_bf16 v[24:27], v[178:181], v[194:197], v[24:27]
	v_mfma_f32_16x16x32_bf16 v[16:19], v[166:169], v[210:213], v[16:19]
	v_mfma_f32_16x16x32_bf16 v[8:11], v[178:181], v[210:213], v[8:11]
	v_mfma_f32_16x16x32_bf16 v[4:7], v[166:169], v[218:221], v[4:7]
	v_mfma_f32_16x16x32_bf16 v[0:3], v[178:181], v[218:221], v[0:3]
	s_setprio 0
	s_barrier
	s_add_i32 s71, s71, 2
	s_add_u32 s28, s28, 0x100
	s_addc_u32 s29, s29, 0
	s_add_u32 s69, s69, 0x100
	s_addc_u32 s70, s70, 0
	s_cmp_gt_u32 s71, 29
	s_cbranch_scc0 .LBB0_666
	s_and_b64 vcc, exec, s[12:13]
	s_cbranch_vccz .LBB0_669
	s_barrier

.LBB0_828:
	s_add_u32 s2, s58, s62
	s_addc_u32 s3, s59, s63
	s_add_u32 s9, s2, 0x100
	s_addc_u32 s38, s3, 0
	s_and_b64 s[0:1], s[60:61], exec
	v_cndmask_b32_e64 v137, 0, 1, s[64:65]
	s_cselect_b32 s65, s23, s38
	s_cselect_b32 s64, s12, s9
	s_add_u32 s0, s56, s62
	s_addc_u32 s1, s57, s63
	s_add_u32 s9, s0, 0x100
	s_addc_u32 s38, s1, 0
	s_and_b64 s[0:1], s[60:61], exec
	s_cselect_b32 s67, s13, s38
	s_cselect_b32 s66, s8, s9
	s_add_u32 s70, s2, 0x80080
	ds_read_b128 v[138:141], v145
	ds_read_b128 v[150:153], v145 offset:1024
	ds_read_b128 v[154:157], v145 offset:2048
	ds_read_b128 v[158:161], v145 offset:3072
	ds_read_b128 v[162:165], v146
	ds_read_b128 v[166:169], v146 offset:1024
	ds_read_b128 v[170:173], v146 offset:2048
	ds_read_b128 v[178:181], v146 offset:3072
	s_addc_u32 s71, s3, 0
	s_add_i32 s39, s87, s79
	s_add_i32 m0, s74, 0xc000
	s_add_i32 s53, s74, 0xe000
	s_add_i32 s50, s39, 0x2000
	s_add_u32 s68, s66, 0x80000
	s_addc_u32 s69, s67, 0
	s_add_i32 s51, s88, s79
	s_add_i32 s38, s51, 0x2000
	s_add_i32 s1, 0, 0x18000
	s_add_i32 s9, 0, 0x1c000
	s_add_u32 s62, s64, 0x80000
	s_addc_u32 s63, s65, 0
	s_add_i32 s3, s1, s79
	s_add_i32 s76, s3, 0x2000
	s_add_u32 s60, s66, 0x80080
	s_addc_u32 s61, s67, 0
	s_add_i32 s2, s9, s79
	s_add_i32 s0, s2, 0x2000
	v_cmp_ne_u32_e32 vcc, 1, v137
	v_lshl_add_u64 v[174:175], s[70:71], 0, v[128:129]
	ds_read_b128 v[182:185], v147
	ds_read_b128 v[186:189], v147 offset:1024
	ds_read_b128 v[190:193], v147 offset:2048
	ds_read_b128 v[194:197], v147 offset:3072
	ds_read_b128 v[206:209], v147 offset:4096
	ds_read_b128 v[210:213], v147 offset:5120
	ds_read_b128 v[214:217], v147 offset:6144
	ds_read_b128 v[218:221], v147 offset:7168
	global_load_lds_dwordx4 v[174:175], off
	v_lshl_add_u64 v[174:175], s[70:71], 0, v[132:133]
	s_mov_b32 m0, s53
	s_nop 0
	global_load_lds_dwordx4 v[174:175], off
	s_waitcnt vmcnt(8)
	s_waitcnt lgkmcnt(0)
	s_barrier
	s_setprio 1
	v_mfma_f32_16x16x32_bf16 v[124:127], v[138:141], v[182:185], v[124:127]
	v_mfma_f32_16x16x32_bf16 v[120:123], v[154:157], v[182:185], v[120:123]
	v_mfma_f32_16x16x32_bf16 v[108:111], v[138:141], v[190:193], v[108:111]
	v_mfma_f32_16x16x32_bf16 v[104:107], v[154:157], v[190:193], v[104:107]
	v_mfma_f32_16x16x32_bf16 v[92:95], v[138:141], v[206:209], v[92:95]
	v_mfma_f32_16x16x32_bf16 v[88:91], v[154:157], v[206:209], v[88:91]
	v_mfma_f32_16x16x32_bf16 v[76:79], v[138:141], v[214:217], v[76:79]
	v_mfma_f32_16x16x32_bf16 v[72:75], v[154:157], v[214:217], v[72:75]
	v_mfma_f32_16x16x32_bf16 v[124:127], v[150:153], v[186:189], v[124:127]
	v_mfma_f32_16x16x32_bf16 v[120:123], v[158:161], v[186:189], v[120:123]
	v_mfma_f32_16x16x32_bf16 v[108:111], v[150:153], v[194:197], v[108:111]
	v_mfma_f32_16x16x32_bf16 v[104:107], v[158:161], v[194:197], v[104:107]
	v_mfma_f32_16x16x32_bf16 v[92:95], v[150:153], v[210:213], v[92:95]
	v_mfma_f32_16x16x32_bf16 v[88:91], v[158:161], v[210:213], v[88:91]
	v_mfma_f32_16x16x32_bf16 v[76:79], v[150:153], v[218:221], v[76:79]
	v_mfma_f32_16x16x32_bf16 v[72:75], v[158:161], v[218:221], v[72:75]
	v_mfma_f32_16x16x32_bf16 v[116:119], v[162:165], v[182:185], v[116:119]
	v_mfma_f32_16x16x32_bf16 v[112:115], v[170:173], v[182:185], v[112:115]
	v_mfma_f32_16x16x32_bf16 v[100:103], v[162:165], v[190:193], v[100:103]
	v_mfma_f32_16x16x32_bf16 v[96:99], v[170:173], v[190:193], v[96:99]
	v_mfma_f32_16x16x32_bf16 v[84:87], v[162:165], v[206:209], v[84:87]
	v_mfma_f32_16x16x32_bf16 v[80:83], v[170:173], v[206:209], v[80:83]
	v_mfma_f32_16x16x32_bf16 v[68:71], v[162:165], v[214:217], v[68:71]
	v_mfma_f32_16x16x32_bf16 v[64:67], v[170:173], v[214:217], v[64:67]
	v_mfma_f32_16x16x32_bf16 v[116:119], v[166:169], v[186:189], v[116:119]
	v_mfma_f32_16x16x32_bf16 v[112:115], v[178:181], v[186:189], v[112:115]
	v_mfma_f32_16x16x32_bf16 v[100:103], v[166:169], v[194:197], v[100:103]
	v_mfma_f32_16x16x32_bf16 v[96:99], v[178:181], v[194:197], v[96:99]
	v_mfma_f32_16x16x32_bf16 v[84:87], v[166:169], v[210:213], v[84:87]
	v_mfma_f32_16x16x32_bf16 v[80:83], v[178:181], v[210:213], v[80:83]
	v_mfma_f32_16x16x32_bf16 v[68:71], v[166:169], v[218:221], v[68:71]
	v_mfma_f32_16x16x32_bf16 v[64:67], v[178:181], v[218:221], v[64:67]
	s_setprio 0
	s_barrier
	s_mov_b32 m0, s39
	v_lshl_add_u64 v[174:175], s[66:67], 0, v[130:131]
	ds_read_b128 v[182:185], v147 offset:16384
	ds_read_b128 v[186:189], v147 offset:17408
	ds_read_b128 v[190:193], v147 offset:18432
	ds_read_b128 v[194:197], v147 offset:19456
	ds_read_b128 v[206:209], v147 offset:20480
	ds_read_b128 v[210:213], v147 offset:21504
	ds_read_b128 v[214:217], v147 offset:22528
	ds_read_b128 v[218:221], v147 offset:23552
	global_load_lds_dwordx4 v[174:175], off
	v_lshl_add_u64 v[198:199], s[66:67], 0, v[134:135]
	s_mov_b32 m0, s50
	v_lshl_add_u64 v[202:203], s[68:69], 0, v[130:131]
	global_load_lds_dwordx4 v[198:199], off
	s_mov_b32 m0, s51
	v_lshl_add_u64 v[222:223], s[64:65], 0, v[132:133]
	global_load_lds_dwordx4 v[202:203], off
	v_lshl_add_u64 v[202:203], s[68:69], 0, v[134:135]
	s_mov_b32 m0, s38
	s_nop 0
	global_load_lds_dwordx4 v[202:203], off
	v_lshl_add_u64 v[202:203], s[64:65], 0, v[128:129]
	s_mov_b32 m0, s74
	s_nop 0
	global_load_lds_dwordx4 v[202:203], off
	s_mov_b32 m0, s55
	s_nop 0
	global_load_lds_dwordx4 v[222:223], off
	s_waitcnt vmcnt(8)
	s_waitcnt lgkmcnt(0)
	s_barrier
	s_setprio 1
	v_mfma_f32_16x16x32_bf16 v[60:63], v[138:141], v[182:185], v[60:63]
	v_mfma_f32_16x16x32_bf16 v[56:59], v[154:157], v[182:185], v[56:59]
	v_mfma_f32_16x16x32_bf16 v[44:47], v[138:141], v[190:193], v[44:47]
	v_mfma_f32_16x16x32_bf16 v[40:43], v[154:157], v[190:193], v[40:43]
	v_mfma_f32_16x16x32_bf16 v[28:31], v[138:141], v[206:209], v[28:31]
	v_mfma_f32_16x16x32_bf16 v[24:27], v[154:157], v[206:209], v[24:27]
	v_mfma_f32_16x16x32_bf16 v[12:15], v[138:141], v[214:217], v[12:15]
	v_mfma_f32_16x16x32_bf16 v[8:11], v[154:157], v[214:217], v[8:11]
	v_mfma_f32_16x16x32_bf16 v[60:63], v[150:153], v[186:189], v[60:63]
	v_mfma_f32_16x16x32_bf16 v[56:59], v[158:161], v[186:189], v[56:59]
	v_mfma_f32_16x16x32_bf16 v[44:47], v[150:153], v[194:197], v[44:47]
	v_mfma_f32_16x16x32_bf16 v[40:43], v[158:161], v[194:197], v[40:43]
	v_mfma_f32_16x16x32_bf16 v[28:31], v[150:153], v[210:213], v[28:31]
	v_mfma_f32_16x16x32_bf16 v[24:27], v[158:161], v[210:213], v[24:27]
	v_mfma_f32_16x16x32_bf16 v[12:15], v[150:153], v[218:221], v[12:15]
	v_mfma_f32_16x16x32_bf16 v[8:11], v[158:161], v[218:221], v[8:11]
	v_mfma_f32_16x16x32_bf16 v[52:55], v[162:165], v[182:185], v[52:55]
	v_mfma_f32_16x16x32_bf16 v[48:51], v[170:173], v[182:185], v[48:51]
	v_mfma_f32_16x16x32_bf16 v[36:39], v[162:165], v[190:193], v[36:39]
	v_mfma_f32_16x16x32_bf16 v[32:35], v[170:173], v[190:193], v[32:35]
	v_mfma_f32_16x16x32_bf16 v[20:23], v[162:165], v[206:209], v[20:23]
	v_mfma_f32_16x16x32_bf16 v[16:19], v[170:173], v[206:209], v[16:19]
	v_mfma_f32_16x16x32_bf16 v[4:7], v[162:165], v[214:217], v[4:7]
	v_mfma_f32_16x16x32_bf16 v[0:3], v[170:173], v[214:217], v[0:3]
	v_mfma_f32_16x16x32_bf16 v[52:55], v[166:169], v[186:189], v[52:55]
	v_mfma_f32_16x16x32_bf16 v[48:51], v[178:181], v[186:189], v[48:51]
	v_mfma_f32_16x16x32_bf16 v[36:39], v[166:169], v[194:197], v[36:39]
	v_mfma_f32_16x16x32_bf16 v[32:35], v[178:181], v[194:197], v[32:35]
	v_mfma_f32_16x16x32_bf16 v[20:23], v[166:169], v[210:213], v[20:23]
	v_mfma_f32_16x16x32_bf16 v[16:19], v[178:181], v[210:213], v[16:19]
	v_mfma_f32_16x16x32_bf16 v[4:7], v[166:169], v[218:221], v[4:7]
	v_mfma_f32_16x16x32_bf16 v[0:3], v[178:181], v[218:221], v[0:3]
	s_setprio 0
	s_barrier
	v_add_u32_e32 v137, s1, v144
	ds_read_b128 v[138:141], v137
	ds_read_b128 v[150:153], v137 offset:1024
	ds_read_b128 v[154:157], v137 offset:2048
	ds_read_b128 v[158:161], v137 offset:3072
	v_add_u32_e32 v137, s9, v144
	ds_read_b128 v[162:165], v137
	ds_read_b128 v[166:169], v137 offset:1024
	ds_read_b128 v[170:173], v137 offset:2048
	ds_read_b128 v[178:181], v137 offset:3072
	s_mov_b32 m0, s80
	v_lshl_add_u64 v[224:225], s[62:63], 0, v[128:129]
	ds_read_b128 v[182:185], v147 offset:32768
	ds_read_b128 v[186:189], v147 offset:33792
	ds_read_b128 v[190:193], v147 offset:34816
	ds_read_b128 v[194:197], v147 offset:35840
	ds_read_b128 v[206:209], v147 offset:36864
	ds_read_b128 v[210:213], v147 offset:37888
	ds_read_b128 v[214:217], v147 offset:38912
	ds_read_b128 v[218:221], v147 offset:39936
	global_load_lds_dwordx4 v[224:225], off
	v_lshl_add_u64 v[224:225], s[62:63], 0, v[132:133]
	s_mov_b32 m0, s81
	s_nop 0
	global_load_lds_dwordx4 v[224:225], off
	s_waitcnt vmcnt(8)
	s_waitcnt lgkmcnt(0)
	s_barrier
	s_setprio 1
	v_mfma_f32_16x16x32_bf16 v[124:127], v[138:141], v[182:185], v[124:127]
	v_mfma_f32_16x16x32_bf16 v[120:123], v[154:157], v[182:185], v[120:123]
	v_mfma_f32_16x16x32_bf16 v[108:111], v[138:141], v[190:193], v[108:111]
	v_mfma_f32_16x16x32_bf16 v[104:107], v[154:157], v[190:193], v[104:107]
	v_mfma_f32_16x16x32_bf16 v[92:95], v[138:141], v[206:209], v[92:95]
	v_mfma_f32_16x16x32_bf16 v[88:91], v[154:157], v[206:209], v[88:91]
	v_mfma_f32_16x16x32_bf16 v[76:79], v[138:141], v[214:217], v[76:79]
	v_mfma_f32_16x16x32_bf16 v[72:75], v[154:157], v[214:217], v[72:75]
	v_mfma_f32_16x16x32_bf16 v[124:127], v[150:153], v[186:189], v[124:127]
	v_mfma_f32_16x16x32_bf16 v[120:123], v[158:161], v[186:189], v[120:123]
	v_mfma_f32_16x16x32_bf16 v[108:111], v[150:153], v[194:197], v[108:111]
	v_mfma_f32_16x16x32_bf16 v[104:107], v[158:161], v[194:197], v[104:107]
	v_mfma_f32_16x16x32_bf16 v[92:95], v[150:153], v[210:213], v[92:95]
	v_mfma_f32_16x16x32_bf16 v[88:91], v[158:161], v[210:213], v[88:91]
	v_mfma_f32_16x16x32_bf16 v[76:79], v[150:153], v[218:221], v[76:79]
	v_mfma_f32_16x16x32_bf16 v[72:75], v[158:161], v[218:221], v[72:75]
	v_mfma_f32_16x16x32_bf16 v[116:119], v[162:165], v[182:185], v[116:119]
	v_mfma_f32_16x16x32_bf16 v[112:115], v[170:173], v[182:185], v[112:115]
	v_mfma_f32_16x16x32_bf16 v[100:103], v[162:165], v[190:193], v[100:103]
	v_mfma_f32_16x16x32_bf16 v[96:99], v[170:173], v[190:193], v[96:99]
	v_mfma_f32_16x16x32_bf16 v[84:87], v[162:165], v[206:209], v[84:87]
	v_mfma_f32_16x16x32_bf16 v[80:83], v[170:173], v[206:209], v[80:83]
	v_mfma_f32_16x16x32_bf16 v[68:71], v[162:165], v[214:217], v[68:71]
	v_mfma_f32_16x16x32_bf16 v[64:67], v[170:173], v[214:217], v[64:67]
	v_mfma_f32_16x16x32_bf16 v[116:119], v[166:169], v[186:189], v[116:119]
	v_mfma_f32_16x16x32_bf16 v[112:115], v[178:181], v[186:189], v[112:115]
	v_mfma_f32_16x16x32_bf16 v[100:103], v[166:169], v[194:197], v[100:103]
	v_mfma_f32_16x16x32_bf16 v[96:99], v[178:181], v[194:197], v[96:99]
	v_mfma_f32_16x16x32_bf16 v[84:87], v[166:169], v[210:213], v[84:87]
	v_mfma_f32_16x16x32_bf16 v[80:83], v[178:181], v[210:213], v[80:83]
	v_mfma_f32_16x16x32_bf16 v[68:71], v[166:169], v[218:221], v[68:71]
	v_mfma_f32_16x16x32_bf16 v[64:67], v[178:181], v[218:221], v[64:67]
	s_setprio 0
	s_barrier
	s_mov_b32 m0, s3
	v_lshl_add_u64 v[174:175], v[174:175], 0, s[16:17]
	ds_read_b128 v[182:185], v147 offset:49152
	ds_read_b128 v[186:189], v147 offset:50176
	ds_read_b128 v[190:193], v147 offset:51200
	ds_read_b128 v[194:197], v147 offset:52224
	ds_read_b128 v[206:209], v147 offset:53248
	ds_read_b128 v[210:213], v147 offset:54272
	ds_read_b128 v[214:217], v147 offset:55296
	ds_read_b128 v[218:221], v147 offset:56320
	global_load_lds_dwordx4 v[174:175], off
	v_lshl_add_u64 v[174:175], v[198:199], 0, s[16:17]
	s_mov_b32 m0, s76
	s_nop 0
	global_load_lds_dwordx4 v[174:175], off
	v_lshl_add_u64 v[174:175], s[60:61], 0, v[130:131]
	s_mov_b32 m0, s2
	s_nop 0
	global_load_lds_dwordx4 v[174:175], off
	v_lshl_add_u64 v[174:175], s[60:61], 0, v[134:135]
	s_mov_b32 m0, s0
	s_nop 0
	global_load_lds_dwordx4 v[174:175], off
	v_lshl_add_u64 v[174:175], v[202:203], 0, s[16:17]
	s_mov_b32 m0, s85
	s_nop 0
	global_load_lds_dwordx4 v[174:175], off
	v_lshl_add_u64 v[174:175], v[222:223], 0, s[16:17]
	s_mov_b32 m0, s86
	s_nop 0
	global_load_lds_dwordx4 v[174:175], off
	s_waitcnt vmcnt(8)
	s_waitcnt lgkmcnt(0)
	s_barrier
	s_setprio 1
	v_mfma_f32_16x16x32_bf16 v[60:63], v[138:141], v[182:185], v[60:63]
	v_mfma_f32_16x16x32_bf16 v[56:59], v[154:157], v[182:185], v[56:59]
	v_mfma_f32_16x16x32_bf16 v[44:47], v[138:141], v[190:193], v[44:47]
	v_mfma_f32_16x16x32_bf16 v[40:43], v[154:157], v[190:193], v[40:43]
	v_mfma_f32_16x16x32_bf16 v[28:31], v[138:141], v[206:209], v[28:31]
	v_mfma_f32_16x16x32_bf16 v[24:27], v[154:157], v[206:209], v[24:27]
	v_mfma_f32_16x16x32_bf16 v[12:15], v[138:141], v[214:217], v[12:15]
	v_mfma_f32_16x16x32_bf16 v[8:11], v[154:157], v[214:217], v[8:11]
	v_mfma_f32_16x16x32_bf16 v[60:63], v[150:153], v[186:189], v[60:63]
	v_mfma_f32_16x16x32_bf16 v[56:59], v[158:161], v[186:189], v[56:59]
	v_mfma_f32_16x16x32_bf16 v[44:47], v[150:153], v[194:197], v[44:47]
	v_mfma_f32_16x16x32_bf16 v[40:43], v[158:161], v[194:197], v[40:43]
	v_mfma_f32_16x16x32_bf16 v[28:31], v[150:153], v[210:213], v[28:31]
	v_mfma_f32_16x16x32_bf16 v[24:27], v[158:161], v[210:213], v[24:27]
	v_mfma_f32_16x16x32_bf16 v[12:15], v[150:153], v[218:221], v[12:15]
	v_mfma_f32_16x16x32_bf16 v[8:11], v[158:161], v[218:221], v[8:11]
	v_mfma_f32_16x16x32_bf16 v[52:55], v[162:165], v[182:185], v[52:55]
	v_mfma_f32_16x16x32_bf16 v[48:51], v[170:173], v[182:185], v[48:51]
	v_mfma_f32_16x16x32_bf16 v[36:39], v[162:165], v[190:193], v[36:39]
	v_mfma_f32_16x16x32_bf16 v[32:35], v[170:173], v[190:193], v[32:35]
	v_mfma_f32_16x16x32_bf16 v[20:23], v[162:165], v[206:209], v[20:23]
	v_mfma_f32_16x16x32_bf16 v[16:19], v[170:173], v[206:209], v[16:19]
	v_mfma_f32_16x16x32_bf16 v[4:7], v[162:165], v[214:217], v[4:7]
	v_mfma_f32_16x16x32_bf16 v[0:3], v[170:173], v[214:217], v[0:3]
	v_mfma_f32_16x16x32_bf16 v[52:55], v[166:169], v[186:189], v[52:55]
	v_mfma_f32_16x16x32_bf16 v[48:51], v[178:181], v[186:189], v[48:51]
	v_mfma_f32_16x16x32_bf16 v[36:39], v[166:169], v[194:197], v[36:39]
	v_mfma_f32_16x16x32_bf16 v[32:35], v[178:181], v[194:197], v[32:35]
	v_mfma_f32_16x16x32_bf16 v[20:23], v[166:169], v[210:213], v[20:23]
	v_mfma_f32_16x16x32_bf16 v[16:19], v[178:181], v[210:213], v[16:19]
	v_mfma_f32_16x16x32_bf16 v[4:7], v[166:169], v[218:221], v[4:7]
	v_mfma_f32_16x16x32_bf16 v[0:3], v[178:181], v[218:221], v[0:3]
	s_setprio 0
	s_barrier
	s_mov_b64 s[64:65], 0
	s_mov_b64 s[60:61], -1
	s_mov_b64 s[62:63], 0x100
	s_cbranch_vccz .LBB0_828
	s_and_b64 vcc, exec, s[18:19]
	s_cbranch_vccz .LBB0_831
	s_barrier

.LBB0_849:
	s_add_u32 s2, s30, s52
	s_addc_u32 s3, s31, s53
	s_add_u32 s9, s2, 0x100
	s_addc_u32 s38, s3, 0
	s_and_b64 s[0:1], s[34:35], exec
	v_cndmask_b32_e64 v137, 0, 1, s[54:55]
	s_cselect_b32 s55, s27, s38
	s_cselect_b32 s54, s89, s9
	s_add_u32 s0, s28, s52
	s_addc_u32 s1, s29, s53
	s_add_u32 s9, s0, 0x100
	s_addc_u32 s38, s1, 0
	s_and_b64 s[0:1], s[34:35], exec
	s_cselect_b32 s57, s90, s38
	s_cselect_b32 s56, s8, s9
	s_add_u32 s60, s2, 0x80080
	ds_read_b128 v[138:141], v147
	ds_read_b128 v[152:155], v147 offset:1024
	ds_read_b128 v[156:159], v147 offset:2048
	ds_read_b128 v[160:163], v147 offset:3072
	ds_read_b128 v[164:167], v148
	ds_read_b128 v[168:171], v148 offset:1024
	ds_read_b128 v[172:175], v148 offset:2048
	ds_read_b128 v[178:181], v148 offset:3072
	s_addc_u32 s61, s3, 0
	s_add_i32 s39, s79, s36
	s_add_i32 m0, s63, 0xc000
	s_add_i32 s74, s63, 0xe000
	s_add_i32 s50, s39, 0x2000
	s_add_u32 s58, s56, 0x80000
	s_addc_u32 s59, s57, 0
	s_add_i32 s38, s80, s36
	s_add_i32 s51, s38, 0x2000
	s_add_i32 s76, 0, 0x18000
	s_add_i32 s0, 0, 0x1c000
	s_add_u32 s52, s54, 0x80000
	s_addc_u32 s53, s55, 0
	s_add_i32 s3, s76, s36
	s_add_i32 s1, s3, 0x2000
	s_add_u32 s34, s56, 0x80080
	s_addc_u32 s35, s57, 0
	s_add_i32 s2, s0, s36
	s_add_i32 s9, s2, 0x2000
	v_cmp_ne_u32_e32 vcc, 1, v137
	v_lshl_add_u64 v[142:143], s[60:61], 0, v[134:135]
	ds_read_b128 v[182:185], v149
	ds_read_b128 v[186:189], v149 offset:1024
	ds_read_b128 v[190:193], v149 offset:2048
	ds_read_b128 v[194:197], v149 offset:3072
	ds_read_b128 v[206:209], v149 offset:4096
	ds_read_b128 v[210:213], v149 offset:5120
	ds_read_b128 v[214:217], v149 offset:6144
	ds_read_b128 v[218:221], v149 offset:7168
	global_load_lds_dwordx4 v[142:143], off
	v_lshl_add_u64 v[142:143], s[60:61], 0, v[130:131]
	s_mov_b32 m0, s74
	s_nop 0
	global_load_lds_dwordx4 v[142:143], off
	s_waitcnt vmcnt(8)
	s_waitcnt lgkmcnt(0)
	s_barrier
	s_setprio 1
	v_mfma_f32_16x16x32_bf16 v[124:127], v[138:141], v[182:185], v[124:127]
	v_mfma_f32_16x16x32_bf16 v[120:123], v[156:159], v[182:185], v[120:123]
	v_mfma_f32_16x16x32_bf16 v[108:111], v[138:141], v[190:193], v[108:111]
	v_mfma_f32_16x16x32_bf16 v[104:107], v[156:159], v[190:193], v[104:107]
	v_mfma_f32_16x16x32_bf16 v[92:95], v[138:141], v[206:209], v[92:95]
	v_mfma_f32_16x16x32_bf16 v[88:91], v[156:159], v[206:209], v[88:91]
	v_mfma_f32_16x16x32_bf16 v[76:79], v[138:141], v[214:217], v[76:79]
	v_mfma_f32_16x16x32_bf16 v[72:75], v[156:159], v[214:217], v[72:75]
	v_mfma_f32_16x16x32_bf16 v[124:127], v[152:155], v[186:189], v[124:127]
	v_mfma_f32_16x16x32_bf16 v[120:123], v[160:163], v[186:189], v[120:123]
	v_mfma_f32_16x16x32_bf16 v[108:111], v[152:155], v[194:197], v[108:111]
	v_mfma_f32_16x16x32_bf16 v[104:107], v[160:163], v[194:197], v[104:107]
	v_mfma_f32_16x16x32_bf16 v[92:95], v[152:155], v[210:213], v[92:95]
	v_mfma_f32_16x16x32_bf16 v[88:91], v[160:163], v[210:213], v[88:91]
	v_mfma_f32_16x16x32_bf16 v[76:79], v[152:155], v[218:221], v[76:79]
	v_mfma_f32_16x16x32_bf16 v[72:75], v[160:163], v[218:221], v[72:75]
	v_mfma_f32_16x16x32_bf16 v[116:119], v[164:167], v[182:185], v[116:119]
	v_mfma_f32_16x16x32_bf16 v[112:115], v[172:175], v[182:185], v[112:115]
	v_mfma_f32_16x16x32_bf16 v[100:103], v[164:167], v[190:193], v[100:103]
	v_mfma_f32_16x16x32_bf16 v[96:99], v[172:175], v[190:193], v[96:99]
	v_mfma_f32_16x16x32_bf16 v[84:87], v[164:167], v[206:209], v[84:87]
	v_mfma_f32_16x16x32_bf16 v[80:83], v[172:175], v[206:209], v[80:83]
	v_mfma_f32_16x16x32_bf16 v[68:71], v[164:167], v[214:217], v[68:71]
	v_mfma_f32_16x16x32_bf16 v[64:67], v[172:175], v[214:217], v[64:67]
	v_mfma_f32_16x16x32_bf16 v[116:119], v[168:171], v[186:189], v[116:119]
	v_mfma_f32_16x16x32_bf16 v[112:115], v[178:181], v[186:189], v[112:115]
	v_mfma_f32_16x16x32_bf16 v[100:103], v[168:171], v[194:197], v[100:103]
	v_mfma_f32_16x16x32_bf16 v[96:99], v[178:181], v[194:197], v[96:99]
	v_mfma_f32_16x16x32_bf16 v[84:87], v[168:171], v[210:213], v[84:87]
	v_mfma_f32_16x16x32_bf16 v[80:83], v[178:181], v[210:213], v[80:83]
	v_mfma_f32_16x16x32_bf16 v[68:71], v[168:171], v[218:221], v[68:71]
	v_mfma_f32_16x16x32_bf16 v[64:67], v[178:181], v[218:221], v[64:67]
	s_setprio 0
	s_barrier
	s_mov_b32 m0, s39
	v_lshl_add_u64 v[142:143], s[56:57], 0, v[132:133]
	ds_read_b128 v[182:185], v149 offset:16384
	ds_read_b128 v[186:189], v149 offset:17408
	ds_read_b128 v[190:193], v149 offset:18432
	ds_read_b128 v[194:197], v149 offset:19456
	ds_read_b128 v[206:209], v149 offset:20480
	ds_read_b128 v[210:213], v149 offset:21504
	ds_read_b128 v[214:217], v149 offset:22528
	ds_read_b128 v[218:221], v149 offset:23552
	global_load_lds_dwordx4 v[142:143], off
	v_lshl_add_u64 v[198:199], s[56:57], 0, v[128:129]
	s_mov_b32 m0, s50
	v_lshl_add_u64 v[202:203], s[58:59], 0, v[132:133]
	global_load_lds_dwordx4 v[198:199], off
	s_mov_b32 m0, s38
	v_lshl_add_u64 v[222:223], s[54:55], 0, v[130:131]
	global_load_lds_dwordx4 v[202:203], off
	v_lshl_add_u64 v[202:203], s[58:59], 0, v[128:129]
	s_mov_b32 m0, s51
	s_nop 0
	global_load_lds_dwordx4 v[202:203], off
	v_lshl_add_u64 v[202:203], s[54:55], 0, v[134:135]
	s_mov_b32 m0, s63
	s_nop 0
	global_load_lds_dwordx4 v[202:203], off
	s_mov_b32 m0, s64
	s_nop 0
	global_load_lds_dwordx4 v[222:223], off
	s_waitcnt vmcnt(8)
	s_waitcnt lgkmcnt(0)
	s_barrier
	s_setprio 1
	v_mfma_f32_16x16x32_bf16 v[60:63], v[138:141], v[182:185], v[60:63]
	v_mfma_f32_16x16x32_bf16 v[56:59], v[156:159], v[182:185], v[56:59]
	v_mfma_f32_16x16x32_bf16 v[44:47], v[138:141], v[190:193], v[44:47]
	v_mfma_f32_16x16x32_bf16 v[40:43], v[156:159], v[190:193], v[40:43]
	v_mfma_f32_16x16x32_bf16 v[28:31], v[138:141], v[206:209], v[28:31]
	v_mfma_f32_16x16x32_bf16 v[24:27], v[156:159], v[206:209], v[24:27]
	v_mfma_f32_16x16x32_bf16 v[12:15], v[138:141], v[214:217], v[12:15]
	v_mfma_f32_16x16x32_bf16 v[8:11], v[156:159], v[214:217], v[8:11]
	v_mfma_f32_16x16x32_bf16 v[60:63], v[152:155], v[186:189], v[60:63]
	v_mfma_f32_16x16x32_bf16 v[56:59], v[160:163], v[186:189], v[56:59]
	v_mfma_f32_16x16x32_bf16 v[44:47], v[152:155], v[194:197], v[44:47]
	v_mfma_f32_16x16x32_bf16 v[40:43], v[160:163], v[194:197], v[40:43]
	v_mfma_f32_16x16x32_bf16 v[28:31], v[152:155], v[210:213], v[28:31]
	v_mfma_f32_16x16x32_bf16 v[24:27], v[160:163], v[210:213], v[24:27]
	v_mfma_f32_16x16x32_bf16 v[12:15], v[152:155], v[218:221], v[12:15]
	v_mfma_f32_16x16x32_bf16 v[8:11], v[160:163], v[218:221], v[8:11]
	v_mfma_f32_16x16x32_bf16 v[52:55], v[164:167], v[182:185], v[52:55]
	v_mfma_f32_16x16x32_bf16 v[48:51], v[172:175], v[182:185], v[48:51]
	v_mfma_f32_16x16x32_bf16 v[36:39], v[164:167], v[190:193], v[36:39]
	v_mfma_f32_16x16x32_bf16 v[32:35], v[172:175], v[190:193], v[32:35]
	v_mfma_f32_16x16x32_bf16 v[20:23], v[164:167], v[206:209], v[20:23]
	v_mfma_f32_16x16x32_bf16 v[16:19], v[172:175], v[206:209], v[16:19]
	v_mfma_f32_16x16x32_bf16 v[4:7], v[164:167], v[214:217], v[4:7]
	v_mfma_f32_16x16x32_bf16 v[0:3], v[172:175], v[214:217], v[0:3]
	v_mfma_f32_16x16x32_bf16 v[52:55], v[168:171], v[186:189], v[52:55]
	v_mfma_f32_16x16x32_bf16 v[48:51], v[178:181], v[186:189], v[48:51]
	v_mfma_f32_16x16x32_bf16 v[36:39], v[168:171], v[194:197], v[36:39]
	v_mfma_f32_16x16x32_bf16 v[32:35], v[178:181], v[194:197], v[32:35]
	v_mfma_f32_16x16x32_bf16 v[20:23], v[168:171], v[210:213], v[20:23]
	v_mfma_f32_16x16x32_bf16 v[16:19], v[178:181], v[210:213], v[16:19]
	v_mfma_f32_16x16x32_bf16 v[4:7], v[168:171], v[218:221], v[4:7]
	v_mfma_f32_16x16x32_bf16 v[0:3], v[178:181], v[218:221], v[0:3]
	s_setprio 0
	s_barrier
	v_add_u32_e32 v137, s76, v146
	ds_read_b128 v[138:141], v137
	ds_read_b128 v[152:155], v137 offset:1024
	ds_read_b128 v[156:159], v137 offset:2048
	ds_read_b128 v[160:163], v137 offset:3072
	v_add_u32_e32 v137, s0, v146
	ds_read_b128 v[164:167], v137
	ds_read_b128 v[168:171], v137 offset:1024
	ds_read_b128 v[172:175], v137 offset:2048
	ds_read_b128 v[178:181], v137 offset:3072
	s_mov_b32 m0, s65
	v_lshl_add_u64 v[224:225], s[52:53], 0, v[134:135]
	ds_read_b128 v[182:185], v149 offset:32768
	ds_read_b128 v[186:189], v149 offset:33792
	ds_read_b128 v[190:193], v149 offset:34816
	ds_read_b128 v[194:197], v149 offset:35840
	ds_read_b128 v[206:209], v149 offset:36864
	ds_read_b128 v[210:213], v149 offset:37888
	ds_read_b128 v[214:217], v149 offset:38912
	ds_read_b128 v[218:221], v149 offset:39936
	global_load_lds_dwordx4 v[224:225], off
	v_lshl_add_u64 v[224:225], s[52:53], 0, v[130:131]
	s_mov_b32 m0, s66
	s_nop 0
	global_load_lds_dwordx4 v[224:225], off
	s_waitcnt vmcnt(8)
	s_waitcnt lgkmcnt(0)
	s_barrier
	s_setprio 1
	v_mfma_f32_16x16x32_bf16 v[124:127], v[138:141], v[182:185], v[124:127]
	v_mfma_f32_16x16x32_bf16 v[120:123], v[156:159], v[182:185], v[120:123]
	v_mfma_f32_16x16x32_bf16 v[108:111], v[138:141], v[190:193], v[108:111]
	v_mfma_f32_16x16x32_bf16 v[104:107], v[156:159], v[190:193], v[104:107]
	v_mfma_f32_16x16x32_bf16 v[92:95], v[138:141], v[206:209], v[92:95]
	v_mfma_f32_16x16x32_bf16 v[88:91], v[156:159], v[206:209], v[88:91]
	v_mfma_f32_16x16x32_bf16 v[76:79], v[138:141], v[214:217], v[76:79]
	v_mfma_f32_16x16x32_bf16 v[72:75], v[156:159], v[214:217], v[72:75]
	v_mfma_f32_16x16x32_bf16 v[124:127], v[152:155], v[186:189], v[124:127]
	v_mfma_f32_16x16x32_bf16 v[120:123], v[160:163], v[186:189], v[120:123]
	v_mfma_f32_16x16x32_bf16 v[108:111], v[152:155], v[194:197], v[108:111]
	v_mfma_f32_16x16x32_bf16 v[104:107], v[160:163], v[194:197], v[104:107]
	v_mfma_f32_16x16x32_bf16 v[92:95], v[152:155], v[210:213], v[92:95]
	v_mfma_f32_16x16x32_bf16 v[88:91], v[160:163], v[210:213], v[88:91]
	v_mfma_f32_16x16x32_bf16 v[76:79], v[152:155], v[218:221], v[76:79]
	v_mfma_f32_16x16x32_bf16 v[72:75], v[160:163], v[218:221], v[72:75]
	v_mfma_f32_16x16x32_bf16 v[116:119], v[164:167], v[182:185], v[116:119]
	v_mfma_f32_16x16x32_bf16 v[112:115], v[172:175], v[182:185], v[112:115]
	v_mfma_f32_16x16x32_bf16 v[100:103], v[164:167], v[190:193], v[100:103]
	v_mfma_f32_16x16x32_bf16 v[96:99], v[172:175], v[190:193], v[96:99]
	v_mfma_f32_16x16x32_bf16 v[84:87], v[164:167], v[206:209], v[84:87]
	v_mfma_f32_16x16x32_bf16 v[80:83], v[172:175], v[206:209], v[80:83]
	v_mfma_f32_16x16x32_bf16 v[68:71], v[164:167], v[214:217], v[68:71]
	v_mfma_f32_16x16x32_bf16 v[64:67], v[172:175], v[214:217], v[64:67]
	v_mfma_f32_16x16x32_bf16 v[116:119], v[168:171], v[186:189], v[116:119]
	v_mfma_f32_16x16x32_bf16 v[112:115], v[178:181], v[186:189], v[112:115]
	v_mfma_f32_16x16x32_bf16 v[100:103], v[168:171], v[194:197], v[100:103]
	v_mfma_f32_16x16x32_bf16 v[96:99], v[178:181], v[194:197], v[96:99]
	v_mfma_f32_16x16x32_bf16 v[84:87], v[168:171], v[210:213], v[84:87]
	v_mfma_f32_16x16x32_bf16 v[80:83], v[178:181], v[210:213], v[80:83]
	v_mfma_f32_16x16x32_bf16 v[68:71], v[168:171], v[218:221], v[68:71]
	v_mfma_f32_16x16x32_bf16 v[64:67], v[178:181], v[218:221], v[64:67]
	s_setprio 0
	s_barrier
	s_mov_b32 m0, s3
	v_lshl_add_u64 v[142:143], v[142:143], 0, s[14:15]
	ds_read_b128 v[182:185], v149 offset:49152
	ds_read_b128 v[186:189], v149 offset:50176
	ds_read_b128 v[190:193], v149 offset:51200
	ds_read_b128 v[194:197], v149 offset:52224
	ds_read_b128 v[206:209], v149 offset:53248
	ds_read_b128 v[210:213], v149 offset:54272
	ds_read_b128 v[214:217], v149 offset:55296
	ds_read_b128 v[218:221], v149 offset:56320
	global_load_lds_dwordx4 v[142:143], off
	v_lshl_add_u64 v[142:143], v[198:199], 0, s[14:15]
	s_mov_b32 m0, s1
	s_nop 0
	global_load_lds_dwordx4 v[142:143], off
	v_lshl_add_u64 v[142:143], s[34:35], 0, v[132:133]
	s_mov_b32 m0, s2
	s_nop 0
	global_load_lds_dwordx4 v[142:143], off
	v_lshl_add_u64 v[142:143], s[34:35], 0, v[128:129]
	s_mov_b32 m0, s9
	s_nop 0
	global_load_lds_dwordx4 v[142:143], off
	v_lshl_add_u64 v[142:143], v[202:203], 0, s[14:15]
	s_mov_b32 m0, s77
	s_nop 0
	global_load_lds_dwordx4 v[142:143], off
	v_lshl_add_u64 v[142:143], v[222:223], 0, s[14:15]
	s_mov_b32 m0, s78
	s_nop 0
	global_load_lds_dwordx4 v[142:143], off
	s_waitcnt vmcnt(8)
	s_waitcnt lgkmcnt(0)
	s_barrier
	s_setprio 1
	v_mfma_f32_16x16x32_bf16 v[60:63], v[138:141], v[182:185], v[60:63]
	v_mfma_f32_16x16x32_bf16 v[56:59], v[156:159], v[182:185], v[56:59]
	v_mfma_f32_16x16x32_bf16 v[44:47], v[138:141], v[190:193], v[44:47]
	v_mfma_f32_16x16x32_bf16 v[40:43], v[156:159], v[190:193], v[40:43]
	v_mfma_f32_16x16x32_bf16 v[28:31], v[138:141], v[206:209], v[28:31]
	v_mfma_f32_16x16x32_bf16 v[24:27], v[156:159], v[206:209], v[24:27]
	v_mfma_f32_16x16x32_bf16 v[12:15], v[138:141], v[214:217], v[12:15]
	v_mfma_f32_16x16x32_bf16 v[8:11], v[156:159], v[214:217], v[8:11]
	v_mfma_f32_16x16x32_bf16 v[60:63], v[152:155], v[186:189], v[60:63]
	v_mfma_f32_16x16x32_bf16 v[56:59], v[160:163], v[186:189], v[56:59]
	v_mfma_f32_16x16x32_bf16 v[44:47], v[152:155], v[194:197], v[44:47]
	v_mfma_f32_16x16x32_bf16 v[40:43], v[160:163], v[194:197], v[40:43]
	v_mfma_f32_16x16x32_bf16 v[28:31], v[152:155], v[210:213], v[28:31]
	v_mfma_f32_16x16x32_bf16 v[24:27], v[160:163], v[210:213], v[24:27]
	v_mfma_f32_16x16x32_bf16 v[12:15], v[152:155], v[218:221], v[12:15]
	v_mfma_f32_16x16x32_bf16 v[8:11], v[160:163], v[218:221], v[8:11]
	v_mfma_f32_16x16x32_bf16 v[52:55], v[164:167], v[182:185], v[52:55]
	v_mfma_f32_16x16x32_bf16 v[48:51], v[172:175], v[182:185], v[48:51]
	v_mfma_f32_16x16x32_bf16 v[36:39], v[164:167], v[190:193], v[36:39]
	v_mfma_f32_16x16x32_bf16 v[32:35], v[172:175], v[190:193], v[32:35]
	v_mfma_f32_16x16x32_bf16 v[20:23], v[164:167], v[206:209], v[20:23]
	v_mfma_f32_16x16x32_bf16 v[16:19], v[172:175], v[206:209], v[16:19]
	v_mfma_f32_16x16x32_bf16 v[4:7], v[164:167], v[214:217], v[4:7]
	v_mfma_f32_16x16x32_bf16 v[0:3], v[172:175], v[214:217], v[0:3]
	v_mfma_f32_16x16x32_bf16 v[52:55], v[168:171], v[186:189], v[52:55]
	v_mfma_f32_16x16x32_bf16 v[48:51], v[178:181], v[186:189], v[48:51]
	v_mfma_f32_16x16x32_bf16 v[36:39], v[168:171], v[194:197], v[36:39]
	v_mfma_f32_16x16x32_bf16 v[32:35], v[178:181], v[194:197], v[32:35]
	v_mfma_f32_16x16x32_bf16 v[20:23], v[168:171], v[210:213], v[20:23]
	v_mfma_f32_16x16x32_bf16 v[16:19], v[178:181], v[210:213], v[16:19]
	v_mfma_f32_16x16x32_bf16 v[4:7], v[168:171], v[218:221], v[4:7]
	v_mfma_f32_16x16x32_bf16 v[0:3], v[178:181], v[218:221], v[0:3]
	s_setprio 0
	s_barrier
	s_mov_b64 s[54:55], 0
	s_mov_b64 s[34:35], -1
	s_mov_b64 s[52:53], 0x100
	s_cbranch_vccz .LBB0_849
	s_and_b64 vcc, exec, s[16:17]
	s_cbranch_vccz .LBB0_852
	s_barrier

.LBB0_877:
	s_add_u32 s2, s54, s64
	s_addc_u32 s3, s55, s65
	s_add_u32 s8, s2, 0x100
	s_addc_u32 s9, s3, 0
	s_and_b64 s[0:1], s[62:63], exec
	v_cndmask_b32_e64 v138, 0, 1, s[66:67]
	s_cselect_b32 s67, s21, s9
	s_cselect_b32 s66, s23, s8
	s_add_u32 s0, s30, s64
	s_addc_u32 s1, s31, s65
	s_add_u32 s8, s0, 0x100
	s_addc_u32 s9, s1, 0
	s_and_b64 s[0:1], s[62:63], exec
	s_cselect_b32 s69, s95, s9
	s_cselect_b32 s68, s96, s8
	s_add_u32 s72, s2, 0x10080
	v_cmp_ne_u32_e32 vcc, 1, v138
	ds_read_b128 v[138:141], v135
	ds_read_b128 v[142:145], v135 offset:1024
	ds_read_b128 v[146:149], v135 offset:2048
	ds_read_b128 v[150:153], v135 offset:3072
	ds_read_b128 v[154:157], v136
	ds_read_b128 v[158:161], v136 offset:1024
	ds_read_b128 v[162:165], v136 offset:2048
	ds_read_b128 v[166:169], v136 offset:3072
	s_addc_u32 s73, s3, 0
	s_add_i32 s19, s91, s77
	s_add_i32 m0, s80, 0xc000
	s_add_i32 s38, s80, 0xe000
	s_add_i32 s0, s19, 0x2000
	s_add_u32 s70, s68, 0x10000
	s_addc_u32 s71, s69, 0
	s_add_i32 s76, s92, s77
	s_add_i32 s18, s76, 0x2000
	s_add_i32 s3, 0, 0x18000
	s_add_i32 s2, 0, 0x1c000
	s_add_u32 s64, s66, 0x10000
	s_addc_u32 s65, s67, 0
	s_add_i32 s1, s3, s77
	s_add_i32 s9, s1, 0x2000
	s_add_u32 s62, s68, 0x10080
	s_addc_u32 s63, s69, 0
	s_add_i32 s97, s2, s77
	s_add_i32 s8, s97, 0x2000
	v_lshl_add_u64 v[174:175], s[72:73], 0, v[128:129]
	ds_read_b128 v[170:173], v137
	ds_read_b128 v[178:181], v137 offset:1024
	ds_read_b128 v[182:185], v137 offset:2048
	ds_read_b128 v[186:189], v137 offset:3072
	ds_read_b128 v[190:193], v137 offset:4096
	ds_read_b128 v[194:197], v137 offset:5120
	ds_read_b128 v[206:209], v137 offset:6144
	ds_read_b128 v[210:213], v137 offset:7168
	global_load_lds_dwordx4 v[174:175], off
	v_lshl_add_u64 v[174:175], s[72:73], 0, v[130:131]
	s_mov_b32 m0, s38
	s_nop 0
	global_load_lds_dwordx4 v[174:175], off
	s_waitcnt vmcnt(8)
	s_waitcnt lgkmcnt(0)
	s_barrier
	s_setprio 1
	v_mfma_f32_16x16x32_bf16 v[124:127], v[138:141], v[170:173], v[124:127]
	v_mfma_f32_16x16x32_bf16 v[120:123], v[146:149], v[170:173], v[120:123]
	v_mfma_f32_16x16x32_bf16 v[116:119], v[138:141], v[182:185], v[116:119]
	v_mfma_f32_16x16x32_bf16 v[112:115], v[146:149], v[182:185], v[112:115]
	v_mfma_f32_16x16x32_bf16 v[104:107], v[138:141], v[190:193], v[104:107]
	v_mfma_f32_16x16x32_bf16 v[96:99], v[146:149], v[190:193], v[96:99]
	v_mfma_f32_16x16x32_bf16 v[88:91], v[138:141], v[206:209], v[88:91]
	v_mfma_f32_16x16x32_bf16 v[80:83], v[146:149], v[206:209], v[80:83]
	v_mfma_f32_16x16x32_bf16 v[124:127], v[142:145], v[178:181], v[124:127]
	v_mfma_f32_16x16x32_bf16 v[120:123], v[150:153], v[178:181], v[120:123]
	v_mfma_f32_16x16x32_bf16 v[116:119], v[142:145], v[186:189], v[116:119]
	v_mfma_f32_16x16x32_bf16 v[112:115], v[150:153], v[186:189], v[112:115]
	v_mfma_f32_16x16x32_bf16 v[104:107], v[142:145], v[194:197], v[104:107]
	v_mfma_f32_16x16x32_bf16 v[96:99], v[150:153], v[194:197], v[96:99]
	v_mfma_f32_16x16x32_bf16 v[88:91], v[142:145], v[210:213], v[88:91]
	v_mfma_f32_16x16x32_bf16 v[80:83], v[150:153], v[210:213], v[80:83]
	v_mfma_f32_16x16x32_bf16 v[108:111], v[154:157], v[170:173], v[108:111]
	v_mfma_f32_16x16x32_bf16 v[100:103], v[162:165], v[170:173], v[100:103]
	v_mfma_f32_16x16x32_bf16 v[92:95], v[154:157], v[182:185], v[92:95]
	v_mfma_f32_16x16x32_bf16 v[84:87], v[162:165], v[182:185], v[84:87]
	v_mfma_f32_16x16x32_bf16 v[76:79], v[154:157], v[190:193], v[76:79]
	v_mfma_f32_16x16x32_bf16 v[72:75], v[162:165], v[190:193], v[72:75]
	v_mfma_f32_16x16x32_bf16 v[68:71], v[154:157], v[206:209], v[68:71]
	v_mfma_f32_16x16x32_bf16 v[64:67], v[162:165], v[206:209], v[64:67]
	v_mfma_f32_16x16x32_bf16 v[108:111], v[158:161], v[178:181], v[108:111]
	v_mfma_f32_16x16x32_bf16 v[100:103], v[166:169], v[178:181], v[100:103]
	v_mfma_f32_16x16x32_bf16 v[92:95], v[158:161], v[186:189], v[92:95]
	v_mfma_f32_16x16x32_bf16 v[84:87], v[166:169], v[186:189], v[84:87]
	v_mfma_f32_16x16x32_bf16 v[76:79], v[158:161], v[194:197], v[76:79]
	v_mfma_f32_16x16x32_bf16 v[72:75], v[166:169], v[194:197], v[72:75]
	v_mfma_f32_16x16x32_bf16 v[68:71], v[158:161], v[210:213], v[68:71]
	v_mfma_f32_16x16x32_bf16 v[64:67], v[166:169], v[210:213], v[64:67]
	s_setprio 0
	s_barrier
	s_mov_b32 m0, s19
	v_lshl_add_u64 v[174:175], s[68:69], 0, v[128:129]
	ds_read_b128 v[170:173], v137 offset:16384
	ds_read_b128 v[178:181], v137 offset:17408
	ds_read_b128 v[182:185], v137 offset:18432
	ds_read_b128 v[186:189], v137 offset:19456
	ds_read_b128 v[190:193], v137 offset:20480
	ds_read_b128 v[194:197], v137 offset:21504
	ds_read_b128 v[206:209], v137 offset:22528
	ds_read_b128 v[210:213], v137 offset:23552
	global_load_lds_dwordx4 v[174:175], off
	v_lshl_add_u64 v[198:199], s[68:69], 0, v[130:131]
	s_mov_b32 m0, s0
	v_lshl_add_u64 v[202:203], s[70:71], 0, v[128:129]
	global_load_lds_dwordx4 v[198:199], off
	s_mov_b32 m0, s76
	v_lshl_add_u64 v[214:215], s[66:67], 0, v[130:131]
	global_load_lds_dwordx4 v[202:203], off
	v_lshl_add_u64 v[202:203], s[70:71], 0, v[130:131]
	s_mov_b32 m0, s18
	s_nop 0
	global_load_lds_dwordx4 v[202:203], off
	v_lshl_add_u64 v[202:203], s[66:67], 0, v[128:129]
	s_mov_b32 m0, s80
	s_nop 0
	global_load_lds_dwordx4 v[202:203], off
	s_mov_b32 m0, s81
	s_nop 0
	global_load_lds_dwordx4 v[214:215], off
	s_waitcnt vmcnt(8)
	s_waitcnt lgkmcnt(0)
	s_barrier
	s_setprio 1
	v_mfma_f32_16x16x32_bf16 v[60:63], v[138:141], v[170:173], v[60:63]
	v_mfma_f32_16x16x32_bf16 v[56:59], v[146:149], v[170:173], v[56:59]
	v_mfma_f32_16x16x32_bf16 v[52:55], v[138:141], v[182:185], v[52:55]
	v_mfma_f32_16x16x32_bf16 v[48:51], v[146:149], v[182:185], v[48:51]
	v_mfma_f32_16x16x32_bf16 v[40:43], v[138:141], v[190:193], v[40:43]
	v_mfma_f32_16x16x32_bf16 v[32:35], v[146:149], v[190:193], v[32:35]
	v_mfma_f32_16x16x32_bf16 v[24:27], v[138:141], v[206:209], v[24:27]
	v_mfma_f32_16x16x32_bf16 v[16:19], v[146:149], v[206:209], v[16:19]
	v_mfma_f32_16x16x32_bf16 v[60:63], v[142:145], v[178:181], v[60:63]
	v_mfma_f32_16x16x32_bf16 v[56:59], v[150:153], v[178:181], v[56:59]
	v_mfma_f32_16x16x32_bf16 v[52:55], v[142:145], v[186:189], v[52:55]
	v_mfma_f32_16x16x32_bf16 v[48:51], v[150:153], v[186:189], v[48:51]
	v_mfma_f32_16x16x32_bf16 v[40:43], v[142:145], v[194:197], v[40:43]
	v_mfma_f32_16x16x32_bf16 v[32:35], v[150:153], v[194:197], v[32:35]
	v_mfma_f32_16x16x32_bf16 v[24:27], v[142:145], v[210:213], v[24:27]
	v_mfma_f32_16x16x32_bf16 v[16:19], v[150:153], v[210:213], v[16:19]
	v_mfma_f32_16x16x32_bf16 v[44:47], v[154:157], v[170:173], v[44:47]
	v_mfma_f32_16x16x32_bf16 v[36:39], v[162:165], v[170:173], v[36:39]
	v_mfma_f32_16x16x32_bf16 v[28:31], v[154:157], v[182:185], v[28:31]
	v_mfma_f32_16x16x32_bf16 v[20:23], v[162:165], v[182:185], v[20:23]
	v_mfma_f32_16x16x32_bf16 v[12:15], v[154:157], v[190:193], v[12:15]
	v_mfma_f32_16x16x32_bf16 v[8:11], v[162:165], v[190:193], v[8:11]
	v_mfma_f32_16x16x32_bf16 v[4:7], v[154:157], v[206:209], v[4:7]
	v_mfma_f32_16x16x32_bf16 v[0:3], v[162:165], v[206:209], v[0:3]
	v_mfma_f32_16x16x32_bf16 v[44:47], v[158:161], v[178:181], v[44:47]
	v_mfma_f32_16x16x32_bf16 v[36:39], v[166:169], v[178:181], v[36:39]
	v_mfma_f32_16x16x32_bf16 v[28:31], v[158:161], v[186:189], v[28:31]
	v_mfma_f32_16x16x32_bf16 v[20:23], v[166:169], v[186:189], v[20:23]
	v_mfma_f32_16x16x32_bf16 v[12:15], v[158:161], v[194:197], v[12:15]
	v_mfma_f32_16x16x32_bf16 v[8:11], v[166:169], v[194:197], v[8:11]
	v_mfma_f32_16x16x32_bf16 v[4:7], v[158:161], v[210:213], v[4:7]
	v_mfma_f32_16x16x32_bf16 v[0:3], v[166:169], v[210:213], v[0:3]
	s_setprio 0
	s_barrier
	v_add_u32_e32 v150, s3, v134
	v_add_u32_e32 v166, s2, v134
	ds_read_b128 v[138:141], v150
	ds_read_b128 v[142:145], v150 offset:1024
	ds_read_b128 v[146:149], v150 offset:2048
	ds_read_b128 v[150:153], v150 offset:3072
	ds_read_b128 v[154:157], v166
	ds_read_b128 v[158:161], v166 offset:1024
	ds_read_b128 v[162:165], v166 offset:2048
	ds_read_b128 v[166:169], v166 offset:3072
	s_mov_b32 m0, s82
	v_lshl_add_u64 v[216:217], s[64:65], 0, v[128:129]
	ds_read_b128 v[170:173], v137 offset:32768
	ds_read_b128 v[178:181], v137 offset:33792
	ds_read_b128 v[182:185], v137 offset:34816
	ds_read_b128 v[186:189], v137 offset:35840
	ds_read_b128 v[190:193], v137 offset:36864
	ds_read_b128 v[194:197], v137 offset:37888
	ds_read_b128 v[206:209], v137 offset:38912
	ds_read_b128 v[210:213], v137 offset:39936
	global_load_lds_dwordx4 v[216:217], off
	v_lshl_add_u64 v[216:217], s[64:65], 0, v[130:131]
	s_mov_b32 m0, s83
	s_nop 0
	global_load_lds_dwordx4 v[216:217], off
	s_waitcnt vmcnt(8)
	s_waitcnt lgkmcnt(0)
	s_barrier
	s_setprio 1
	v_mfma_f32_16x16x32_bf16 v[124:127], v[138:141], v[170:173], v[124:127]
	v_mfma_f32_16x16x32_bf16 v[120:123], v[146:149], v[170:173], v[120:123]
	v_mfma_f32_16x16x32_bf16 v[116:119], v[138:141], v[182:185], v[116:119]
	v_mfma_f32_16x16x32_bf16 v[112:115], v[146:149], v[182:185], v[112:115]
	v_mfma_f32_16x16x32_bf16 v[104:107], v[138:141], v[190:193], v[104:107]
	v_mfma_f32_16x16x32_bf16 v[96:99], v[146:149], v[190:193], v[96:99]
	v_mfma_f32_16x16x32_bf16 v[88:91], v[138:141], v[206:209], v[88:91]
	v_mfma_f32_16x16x32_bf16 v[80:83], v[146:149], v[206:209], v[80:83]
	v_mfma_f32_16x16x32_bf16 v[124:127], v[142:145], v[178:181], v[124:127]
	v_mfma_f32_16x16x32_bf16 v[120:123], v[150:153], v[178:181], v[120:123]
	v_mfma_f32_16x16x32_bf16 v[116:119], v[142:145], v[186:189], v[116:119]
	v_mfma_f32_16x16x32_bf16 v[112:115], v[150:153], v[186:189], v[112:115]
	v_mfma_f32_16x16x32_bf16 v[104:107], v[142:145], v[194:197], v[104:107]
	v_mfma_f32_16x16x32_bf16 v[96:99], v[150:153], v[194:197], v[96:99]
	v_mfma_f32_16x16x32_bf16 v[88:91], v[142:145], v[210:213], v[88:91]
	v_mfma_f32_16x16x32_bf16 v[80:83], v[150:153], v[210:213], v[80:83]
	v_mfma_f32_16x16x32_bf16 v[108:111], v[154:157], v[170:173], v[108:111]
	v_mfma_f32_16x16x32_bf16 v[100:103], v[162:165], v[170:173], v[100:103]
	v_mfma_f32_16x16x32_bf16 v[92:95], v[154:157], v[182:185], v[92:95]
	v_mfma_f32_16x16x32_bf16 v[84:87], v[162:165], v[182:185], v[84:87]
	v_mfma_f32_16x16x32_bf16 v[76:79], v[154:157], v[190:193], v[76:79]
	v_mfma_f32_16x16x32_bf16 v[72:75], v[162:165], v[190:193], v[72:75]
	v_mfma_f32_16x16x32_bf16 v[68:71], v[154:157], v[206:209], v[68:71]
	v_mfma_f32_16x16x32_bf16 v[64:67], v[162:165], v[206:209], v[64:67]
	v_mfma_f32_16x16x32_bf16 v[108:111], v[158:161], v[178:181], v[108:111]
	v_mfma_f32_16x16x32_bf16 v[100:103], v[166:169], v[178:181], v[100:103]
	v_mfma_f32_16x16x32_bf16 v[92:95], v[158:161], v[186:189], v[92:95]
	v_mfma_f32_16x16x32_bf16 v[84:87], v[166:169], v[186:189], v[84:87]
	v_mfma_f32_16x16x32_bf16 v[76:79], v[158:161], v[194:197], v[76:79]
	v_mfma_f32_16x16x32_bf16 v[72:75], v[166:169], v[194:197], v[72:75]
	v_mfma_f32_16x16x32_bf16 v[68:71], v[158:161], v[210:213], v[68:71]
	v_mfma_f32_16x16x32_bf16 v[64:67], v[166:169], v[210:213], v[64:67]
	s_setprio 0
	s_barrier
	s_mov_b32 m0, s1
	v_lshl_add_u64 v[174:175], v[174:175], 0, s[26:27]
	ds_read_b128 v[170:173], v137 offset:49152
	ds_read_b128 v[178:181], v137 offset:50176
	ds_read_b128 v[182:185], v137 offset:51200
	ds_read_b128 v[186:189], v137 offset:52224
	ds_read_b128 v[190:193], v137 offset:53248
	ds_read_b128 v[194:197], v137 offset:54272
	ds_read_b128 v[206:209], v137 offset:55296
	ds_read_b128 v[210:213], v137 offset:56320
	global_load_lds_dwordx4 v[174:175], off
	v_lshl_add_u64 v[174:175], v[198:199], 0, s[26:27]
	s_mov_b32 m0, s9
	s_nop 0
	global_load_lds_dwordx4 v[174:175], off
	v_lshl_add_u64 v[174:175], s[62:63], 0, v[128:129]
	s_mov_b32 m0, s97
	s_nop 0
	global_load_lds_dwordx4 v[174:175], off
	v_lshl_add_u64 v[174:175], s[62:63], 0, v[130:131]
	s_mov_b32 m0, s8
	s_nop 0
	global_load_lds_dwordx4 v[174:175], off
	v_lshl_add_u64 v[174:175], v[202:203], 0, s[26:27]
	s_mov_b32 m0, s89
	s_nop 0
	global_load_lds_dwordx4 v[174:175], off
	v_lshl_add_u64 v[174:175], v[214:215], 0, s[26:27]
	s_mov_b32 m0, s90
	s_nop 0
	global_load_lds_dwordx4 v[174:175], off
	s_waitcnt vmcnt(8)
	s_waitcnt lgkmcnt(0)
	s_barrier
	s_setprio 1
	v_mfma_f32_16x16x32_bf16 v[60:63], v[138:141], v[170:173], v[60:63]
	v_mfma_f32_16x16x32_bf16 v[56:59], v[146:149], v[170:173], v[56:59]
	v_mfma_f32_16x16x32_bf16 v[52:55], v[138:141], v[182:185], v[52:55]
	v_mfma_f32_16x16x32_bf16 v[48:51], v[146:149], v[182:185], v[48:51]
	v_mfma_f32_16x16x32_bf16 v[40:43], v[138:141], v[190:193], v[40:43]
	v_mfma_f32_16x16x32_bf16 v[32:35], v[146:149], v[190:193], v[32:35]
	v_mfma_f32_16x16x32_bf16 v[24:27], v[138:141], v[206:209], v[24:27]
	v_mfma_f32_16x16x32_bf16 v[16:19], v[146:149], v[206:209], v[16:19]
	v_mfma_f32_16x16x32_bf16 v[60:63], v[142:145], v[178:181], v[60:63]
	v_mfma_f32_16x16x32_bf16 v[56:59], v[150:153], v[178:181], v[56:59]
	v_mfma_f32_16x16x32_bf16 v[52:55], v[142:145], v[186:189], v[52:55]
	v_mfma_f32_16x16x32_bf16 v[48:51], v[150:153], v[186:189], v[48:51]
	v_mfma_f32_16x16x32_bf16 v[40:43], v[142:145], v[194:197], v[40:43]
	v_mfma_f32_16x16x32_bf16 v[32:35], v[150:153], v[194:197], v[32:35]
	v_mfma_f32_16x16x32_bf16 v[24:27], v[142:145], v[210:213], v[24:27]
	v_mfma_f32_16x16x32_bf16 v[16:19], v[150:153], v[210:213], v[16:19]
	v_mfma_f32_16x16x32_bf16 v[44:47], v[154:157], v[170:173], v[44:47]
	v_mfma_f32_16x16x32_bf16 v[36:39], v[162:165], v[170:173], v[36:39]
	v_mfma_f32_16x16x32_bf16 v[28:31], v[154:157], v[182:185], v[28:31]
	v_mfma_f32_16x16x32_bf16 v[20:23], v[162:165], v[182:185], v[20:23]
	v_mfma_f32_16x16x32_bf16 v[12:15], v[154:157], v[190:193], v[12:15]
	v_mfma_f32_16x16x32_bf16 v[8:11], v[162:165], v[190:193], v[8:11]
	v_mfma_f32_16x16x32_bf16 v[4:7], v[154:157], v[206:209], v[4:7]
	v_mfma_f32_16x16x32_bf16 v[0:3], v[162:165], v[206:209], v[0:3]
	v_mfma_f32_16x16x32_bf16 v[44:47], v[158:161], v[178:181], v[44:47]
	v_mfma_f32_16x16x32_bf16 v[36:39], v[166:169], v[178:181], v[36:39]
	v_mfma_f32_16x16x32_bf16 v[28:31], v[158:161], v[186:189], v[28:31]
	v_mfma_f32_16x16x32_bf16 v[20:23], v[166:169], v[186:189], v[20:23]
	v_mfma_f32_16x16x32_bf16 v[12:15], v[158:161], v[194:197], v[12:15]
	v_mfma_f32_16x16x32_bf16 v[8:11], v[166:169], v[194:197], v[8:11]
	v_mfma_f32_16x16x32_bf16 v[4:7], v[158:161], v[210:213], v[4:7]
	v_mfma_f32_16x16x32_bf16 v[0:3], v[166:169], v[210:213], v[0:3]
	s_setprio 0
	s_barrier
	s_mov_b64 s[66:67], 0
	s_mov_b64 s[62:63], -1
	s_mov_b64 s[64:65], 0x100
	s_cbranch_vccz .LBB0_877
	s_and_b64 vcc, exec, s[28:29]
	s_cbranch_vccz .LBB0_880
	s_barrier

.LBB0_904:
	s_add_u32 s2, s28, s56
	s_addc_u32 s3, s29, s57
	s_add_u32 s8, s2, 0x100
	s_addc_u32 s9, s3, 0
	s_and_b64 s[0:1], s[54:55], exec
	v_cndmask_b32_e64 v138, 0, 1, s[58:59]
	s_cselect_b32 s59, s13, s9
	s_cselect_b32 s58, s15, s8
	s_add_u32 s0, s22, s56
	s_addc_u32 s1, s23, s57
	s_add_u32 s8, s0, 0x100
	s_addc_u32 s9, s1, 0
	s_and_b64 s[0:1], s[54:55], exec
	s_cselect_b32 s61, s87, s9
	s_cselect_b32 s60, s88, s8
	s_add_u32 s64, s2, 0x10080
	v_cmp_ne_u32_e32 vcc, 1, v138
	ds_read_b128 v[138:141], v135
	ds_read_b128 v[142:145], v135 offset:1024
	ds_read_b128 v[146:149], v135 offset:2048
	ds_read_b128 v[150:153], v135 offset:3072
	ds_read_b128 v[154:157], v136
	ds_read_b128 v[158:161], v136 offset:1024
	ds_read_b128 v[162:165], v136 offset:2048
	ds_read_b128 v[166:169], v136 offset:3072
	s_addc_u32 s65, s3, 0
	s_add_i32 s38, s83, s66
	s_add_i32 m0, s69, 0xc000
	s_add_i32 s39, s69, 0xe000
	s_add_i32 s0, s38, 0x2000
	s_add_u32 s62, s60, 0x10000
	s_addc_u32 s63, s61, 0
	s_add_i32 s90, s84, s66
	s_add_i32 s76, s90, 0x2000
	s_add_i32 s3, 0, 0x18000
	s_add_i32 s2, 0, 0x1c000
	s_add_u32 s56, s58, 0x10000
	s_addc_u32 s57, s59, 0
	s_add_i32 s1, s3, s66
	s_add_i32 s9, s1, 0x2000
	s_add_u32 s54, s60, 0x10080
	s_addc_u32 s55, s61, 0
	s_add_i32 s89, s2, s66
	s_add_i32 s8, s89, 0x2000
	v_lshl_add_u64 v[174:175], s[64:65], 0, v[128:129]
	ds_read_b128 v[170:173], v137
	ds_read_b128 v[178:181], v137 offset:1024
	ds_read_b128 v[182:185], v137 offset:2048
	ds_read_b128 v[186:189], v137 offset:3072
	ds_read_b128 v[190:193], v137 offset:4096
	ds_read_b128 v[194:197], v137 offset:5120
	ds_read_b128 v[206:209], v137 offset:6144
	ds_read_b128 v[210:213], v137 offset:7168
	global_load_lds_dwordx4 v[174:175], off
	v_lshl_add_u64 v[174:175], s[64:65], 0, v[130:131]
	s_mov_b32 m0, s39
	s_nop 0
	global_load_lds_dwordx4 v[174:175], off
	s_waitcnt vmcnt(8)
	s_waitcnt lgkmcnt(0)
	s_barrier
	s_setprio 1
	v_mfma_f32_16x16x32_bf16 v[124:127], v[138:141], v[170:173], v[124:127]
	v_mfma_f32_16x16x32_bf16 v[120:123], v[146:149], v[170:173], v[120:123]
	v_mfma_f32_16x16x32_bf16 v[116:119], v[138:141], v[182:185], v[116:119]
	v_mfma_f32_16x16x32_bf16 v[112:115], v[146:149], v[182:185], v[112:115]
	v_mfma_f32_16x16x32_bf16 v[104:107], v[138:141], v[190:193], v[104:107]
	v_mfma_f32_16x16x32_bf16 v[96:99], v[146:149], v[190:193], v[96:99]
	v_mfma_f32_16x16x32_bf16 v[88:91], v[138:141], v[206:209], v[88:91]
	v_mfma_f32_16x16x32_bf16 v[80:83], v[146:149], v[206:209], v[80:83]
	v_mfma_f32_16x16x32_bf16 v[124:127], v[142:145], v[178:181], v[124:127]
	v_mfma_f32_16x16x32_bf16 v[120:123], v[150:153], v[178:181], v[120:123]
	v_mfma_f32_16x16x32_bf16 v[116:119], v[142:145], v[186:189], v[116:119]
	v_mfma_f32_16x16x32_bf16 v[112:115], v[150:153], v[186:189], v[112:115]
	v_mfma_f32_16x16x32_bf16 v[104:107], v[142:145], v[194:197], v[104:107]
	v_mfma_f32_16x16x32_bf16 v[96:99], v[150:153], v[194:197], v[96:99]
	v_mfma_f32_16x16x32_bf16 v[88:91], v[142:145], v[210:213], v[88:91]
	v_mfma_f32_16x16x32_bf16 v[80:83], v[150:153], v[210:213], v[80:83]
	v_mfma_f32_16x16x32_bf16 v[108:111], v[154:157], v[170:173], v[108:111]
	v_mfma_f32_16x16x32_bf16 v[100:103], v[162:165], v[170:173], v[100:103]
	v_mfma_f32_16x16x32_bf16 v[92:95], v[154:157], v[182:185], v[92:95]
	v_mfma_f32_16x16x32_bf16 v[84:87], v[162:165], v[182:185], v[84:87]
	v_mfma_f32_16x16x32_bf16 v[76:79], v[154:157], v[190:193], v[76:79]
	v_mfma_f32_16x16x32_bf16 v[72:75], v[162:165], v[190:193], v[72:75]
	v_mfma_f32_16x16x32_bf16 v[68:71], v[154:157], v[206:209], v[68:71]
	v_mfma_f32_16x16x32_bf16 v[64:67], v[162:165], v[206:209], v[64:67]
	v_mfma_f32_16x16x32_bf16 v[108:111], v[158:161], v[178:181], v[108:111]
	v_mfma_f32_16x16x32_bf16 v[100:103], v[166:169], v[178:181], v[100:103]
	v_mfma_f32_16x16x32_bf16 v[92:95], v[158:161], v[186:189], v[92:95]
	v_mfma_f32_16x16x32_bf16 v[84:87], v[166:169], v[186:189], v[84:87]
	v_mfma_f32_16x16x32_bf16 v[76:79], v[158:161], v[194:197], v[76:79]
	v_mfma_f32_16x16x32_bf16 v[72:75], v[166:169], v[194:197], v[72:75]
	v_mfma_f32_16x16x32_bf16 v[68:71], v[158:161], v[210:213], v[68:71]
	v_mfma_f32_16x16x32_bf16 v[64:67], v[166:169], v[210:213], v[64:67]
	s_setprio 0
	s_barrier
	s_mov_b32 m0, s38
	v_lshl_add_u64 v[174:175], s[60:61], 0, v[128:129]
	ds_read_b128 v[170:173], v137 offset:16384
	ds_read_b128 v[178:181], v137 offset:17408
	ds_read_b128 v[182:185], v137 offset:18432
	ds_read_b128 v[186:189], v137 offset:19456
	ds_read_b128 v[190:193], v137 offset:20480
	ds_read_b128 v[194:197], v137 offset:21504
	ds_read_b128 v[206:209], v137 offset:22528
	ds_read_b128 v[210:213], v137 offset:23552
	global_load_lds_dwordx4 v[174:175], off
	v_lshl_add_u64 v[198:199], s[60:61], 0, v[130:131]
	s_mov_b32 m0, s0
	v_lshl_add_u64 v[202:203], s[62:63], 0, v[128:129]
	global_load_lds_dwordx4 v[198:199], off
	s_mov_b32 m0, s90
	v_lshl_add_u64 v[214:215], s[58:59], 0, v[130:131]
	global_load_lds_dwordx4 v[202:203], off
	v_lshl_add_u64 v[202:203], s[62:63], 0, v[130:131]
	s_mov_b32 m0, s76
	s_nop 0
	global_load_lds_dwordx4 v[202:203], off
	v_lshl_add_u64 v[202:203], s[58:59], 0, v[128:129]
	s_mov_b32 m0, s69
	s_nop 0
	global_load_lds_dwordx4 v[202:203], off
	s_mov_b32 m0, s70
	s_nop 0
	global_load_lds_dwordx4 v[214:215], off
	s_waitcnt vmcnt(8)
	s_waitcnt lgkmcnt(0)
	s_barrier
	s_setprio 1
	v_mfma_f32_16x16x32_bf16 v[60:63], v[138:141], v[170:173], v[60:63]
	v_mfma_f32_16x16x32_bf16 v[56:59], v[146:149], v[170:173], v[56:59]
	v_mfma_f32_16x16x32_bf16 v[52:55], v[138:141], v[182:185], v[52:55]
	v_mfma_f32_16x16x32_bf16 v[48:51], v[146:149], v[182:185], v[48:51]
	v_mfma_f32_16x16x32_bf16 v[40:43], v[138:141], v[190:193], v[40:43]
	v_mfma_f32_16x16x32_bf16 v[32:35], v[146:149], v[190:193], v[32:35]
	v_mfma_f32_16x16x32_bf16 v[24:27], v[138:141], v[206:209], v[24:27]
	v_mfma_f32_16x16x32_bf16 v[16:19], v[146:149], v[206:209], v[16:19]
	v_mfma_f32_16x16x32_bf16 v[60:63], v[142:145], v[178:181], v[60:63]
	v_mfma_f32_16x16x32_bf16 v[56:59], v[150:153], v[178:181], v[56:59]
	v_mfma_f32_16x16x32_bf16 v[52:55], v[142:145], v[186:189], v[52:55]
	v_mfma_f32_16x16x32_bf16 v[48:51], v[150:153], v[186:189], v[48:51]
	v_mfma_f32_16x16x32_bf16 v[40:43], v[142:145], v[194:197], v[40:43]
	v_mfma_f32_16x16x32_bf16 v[32:35], v[150:153], v[194:197], v[32:35]
	v_mfma_f32_16x16x32_bf16 v[24:27], v[142:145], v[210:213], v[24:27]
	v_mfma_f32_16x16x32_bf16 v[16:19], v[150:153], v[210:213], v[16:19]
	v_mfma_f32_16x16x32_bf16 v[44:47], v[154:157], v[170:173], v[44:47]
	v_mfma_f32_16x16x32_bf16 v[36:39], v[162:165], v[170:173], v[36:39]
	v_mfma_f32_16x16x32_bf16 v[28:31], v[154:157], v[182:185], v[28:31]
	v_mfma_f32_16x16x32_bf16 v[20:23], v[162:165], v[182:185], v[20:23]
	v_mfma_f32_16x16x32_bf16 v[12:15], v[154:157], v[190:193], v[12:15]
	v_mfma_f32_16x16x32_bf16 v[8:11], v[162:165], v[190:193], v[8:11]
	v_mfma_f32_16x16x32_bf16 v[4:7], v[154:157], v[206:209], v[4:7]
	v_mfma_f32_16x16x32_bf16 v[0:3], v[162:165], v[206:209], v[0:3]
	v_mfma_f32_16x16x32_bf16 v[44:47], v[158:161], v[178:181], v[44:47]
	v_mfma_f32_16x16x32_bf16 v[36:39], v[166:169], v[178:181], v[36:39]
	v_mfma_f32_16x16x32_bf16 v[28:31], v[158:161], v[186:189], v[28:31]
	v_mfma_f32_16x16x32_bf16 v[20:23], v[166:169], v[186:189], v[20:23]
	v_mfma_f32_16x16x32_bf16 v[12:15], v[158:161], v[194:197], v[12:15]
	v_mfma_f32_16x16x32_bf16 v[8:11], v[166:169], v[194:197], v[8:11]
	v_mfma_f32_16x16x32_bf16 v[4:7], v[158:161], v[210:213], v[4:7]
	v_mfma_f32_16x16x32_bf16 v[0:3], v[166:169], v[210:213], v[0:3]
	s_setprio 0
	s_barrier
	v_add_u32_e32 v150, s3, v134
	v_add_u32_e32 v166, s2, v134
	ds_read_b128 v[138:141], v150
	ds_read_b128 v[142:145], v150 offset:1024
	ds_read_b128 v[146:149], v150 offset:2048
	ds_read_b128 v[150:153], v150 offset:3072
	ds_read_b128 v[154:157], v166
	ds_read_b128 v[158:161], v166 offset:1024
	ds_read_b128 v[162:165], v166 offset:2048
	ds_read_b128 v[166:169], v166 offset:3072
	s_mov_b32 m0, s71
	v_lshl_add_u64 v[216:217], s[56:57], 0, v[128:129]
	ds_read_b128 v[170:173], v137 offset:32768
	ds_read_b128 v[178:181], v137 offset:33792
	ds_read_b128 v[182:185], v137 offset:34816
	ds_read_b128 v[186:189], v137 offset:35840
	ds_read_b128 v[190:193], v137 offset:36864
	ds_read_b128 v[194:197], v137 offset:37888
	ds_read_b128 v[206:209], v137 offset:38912
	ds_read_b128 v[210:213], v137 offset:39936
	global_load_lds_dwordx4 v[216:217], off
	v_lshl_add_u64 v[216:217], s[56:57], 0, v[130:131]
	s_mov_b32 m0, s72
	s_nop 0
	global_load_lds_dwordx4 v[216:217], off
	s_waitcnt vmcnt(8)
	s_waitcnt lgkmcnt(0)
	s_barrier
	s_setprio 1
	v_mfma_f32_16x16x32_bf16 v[124:127], v[138:141], v[170:173], v[124:127]
	v_mfma_f32_16x16x32_bf16 v[120:123], v[146:149], v[170:173], v[120:123]
	v_mfma_f32_16x16x32_bf16 v[116:119], v[138:141], v[182:185], v[116:119]
	v_mfma_f32_16x16x32_bf16 v[112:115], v[146:149], v[182:185], v[112:115]
	v_mfma_f32_16x16x32_bf16 v[104:107], v[138:141], v[190:193], v[104:107]
	v_mfma_f32_16x16x32_bf16 v[96:99], v[146:149], v[190:193], v[96:99]
	v_mfma_f32_16x16x32_bf16 v[88:91], v[138:141], v[206:209], v[88:91]
	v_mfma_f32_16x16x32_bf16 v[80:83], v[146:149], v[206:209], v[80:83]
	v_mfma_f32_16x16x32_bf16 v[124:127], v[142:145], v[178:181], v[124:127]
	v_mfma_f32_16x16x32_bf16 v[120:123], v[150:153], v[178:181], v[120:123]
	v_mfma_f32_16x16x32_bf16 v[116:119], v[142:145], v[186:189], v[116:119]
	v_mfma_f32_16x16x32_bf16 v[112:115], v[150:153], v[186:189], v[112:115]
	v_mfma_f32_16x16x32_bf16 v[104:107], v[142:145], v[194:197], v[104:107]
	v_mfma_f32_16x16x32_bf16 v[96:99], v[150:153], v[194:197], v[96:99]
	v_mfma_f32_16x16x32_bf16 v[88:91], v[142:145], v[210:213], v[88:91]
	v_mfma_f32_16x16x32_bf16 v[80:83], v[150:153], v[210:213], v[80:83]
	v_mfma_f32_16x16x32_bf16 v[108:111], v[154:157], v[170:173], v[108:111]
	v_mfma_f32_16x16x32_bf16 v[100:103], v[162:165], v[170:173], v[100:103]
	v_mfma_f32_16x16x32_bf16 v[92:95], v[154:157], v[182:185], v[92:95]
	v_mfma_f32_16x16x32_bf16 v[84:87], v[162:165], v[182:185], v[84:87]
	v_mfma_f32_16x16x32_bf16 v[76:79], v[154:157], v[190:193], v[76:79]
	v_mfma_f32_16x16x32_bf16 v[72:75], v[162:165], v[190:193], v[72:75]
	v_mfma_f32_16x16x32_bf16 v[68:71], v[154:157], v[206:209], v[68:71]
	v_mfma_f32_16x16x32_bf16 v[64:67], v[162:165], v[206:209], v[64:67]
	v_mfma_f32_16x16x32_bf16 v[108:111], v[158:161], v[178:181], v[108:111]
	v_mfma_f32_16x16x32_bf16 v[100:103], v[166:169], v[178:181], v[100:103]
	v_mfma_f32_16x16x32_bf16 v[92:95], v[158:161], v[186:189], v[92:95]
	v_mfma_f32_16x16x32_bf16 v[84:87], v[166:169], v[186:189], v[84:87]
	v_mfma_f32_16x16x32_bf16 v[76:79], v[158:161], v[194:197], v[76:79]
	v_mfma_f32_16x16x32_bf16 v[72:75], v[166:169], v[194:197], v[72:75]
	v_mfma_f32_16x16x32_bf16 v[68:71], v[158:161], v[210:213], v[68:71]
	v_mfma_f32_16x16x32_bf16 v[64:67], v[166:169], v[210:213], v[64:67]
	s_setprio 0
	s_barrier
	s_mov_b32 m0, s1
	v_lshl_add_u64 v[174:175], v[174:175], 0, s[18:19]
	ds_read_b128 v[170:173], v137 offset:49152
	ds_read_b128 v[178:181], v137 offset:50176
	ds_read_b128 v[182:185], v137 offset:51200
	ds_read_b128 v[186:189], v137 offset:52224
	ds_read_b128 v[190:193], v137 offset:53248
	ds_read_b128 v[194:197], v137 offset:54272
	ds_read_b128 v[206:209], v137 offset:55296
	ds_read_b128 v[210:213], v137 offset:56320
	global_load_lds_dwordx4 v[174:175], off
	v_lshl_add_u64 v[174:175], v[198:199], 0, s[18:19]
	s_mov_b32 m0, s9
	s_nop 0
	global_load_lds_dwordx4 v[174:175], off
	v_lshl_add_u64 v[174:175], s[54:55], 0, v[128:129]
	s_mov_b32 m0, s89
	s_nop 0
	global_load_lds_dwordx4 v[174:175], off
	v_lshl_add_u64 v[174:175], s[54:55], 0, v[130:131]
	s_mov_b32 m0, s8
	s_nop 0
	global_load_lds_dwordx4 v[174:175], off
	v_lshl_add_u64 v[174:175], v[202:203], 0, s[18:19]
	s_mov_b32 m0, s81
	s_nop 0
	global_load_lds_dwordx4 v[174:175], off
	v_lshl_add_u64 v[174:175], v[214:215], 0, s[18:19]
	s_mov_b32 m0, s82
	s_nop 0
	global_load_lds_dwordx4 v[174:175], off
	s_waitcnt vmcnt(8)
	s_waitcnt lgkmcnt(0)
	s_barrier
	s_setprio 1
	v_mfma_f32_16x16x32_bf16 v[60:63], v[138:141], v[170:173], v[60:63]
	v_mfma_f32_16x16x32_bf16 v[56:59], v[146:149], v[170:173], v[56:59]
	v_mfma_f32_16x16x32_bf16 v[52:55], v[138:141], v[182:185], v[52:55]
	v_mfma_f32_16x16x32_bf16 v[48:51], v[146:149], v[182:185], v[48:51]
	v_mfma_f32_16x16x32_bf16 v[40:43], v[138:141], v[190:193], v[40:43]
	v_mfma_f32_16x16x32_bf16 v[32:35], v[146:149], v[190:193], v[32:35]
	v_mfma_f32_16x16x32_bf16 v[24:27], v[138:141], v[206:209], v[24:27]
	v_mfma_f32_16x16x32_bf16 v[16:19], v[146:149], v[206:209], v[16:19]
	v_mfma_f32_16x16x32_bf16 v[60:63], v[142:145], v[178:181], v[60:63]
	v_mfma_f32_16x16x32_bf16 v[56:59], v[150:153], v[178:181], v[56:59]
	v_mfma_f32_16x16x32_bf16 v[52:55], v[142:145], v[186:189], v[52:55]
	v_mfma_f32_16x16x32_bf16 v[48:51], v[150:153], v[186:189], v[48:51]
	v_mfma_f32_16x16x32_bf16 v[40:43], v[142:145], v[194:197], v[40:43]
	v_mfma_f32_16x16x32_bf16 v[32:35], v[150:153], v[194:197], v[32:35]
	v_mfma_f32_16x16x32_bf16 v[24:27], v[142:145], v[210:213], v[24:27]
	v_mfma_f32_16x16x32_bf16 v[16:19], v[150:153], v[210:213], v[16:19]
	v_mfma_f32_16x16x32_bf16 v[44:47], v[154:157], v[170:173], v[44:47]
	v_mfma_f32_16x16x32_bf16 v[36:39], v[162:165], v[170:173], v[36:39]
	v_mfma_f32_16x16x32_bf16 v[28:31], v[154:157], v[182:185], v[28:31]
	v_mfma_f32_16x16x32_bf16 v[20:23], v[162:165], v[182:185], v[20:23]
	v_mfma_f32_16x16x32_bf16 v[12:15], v[154:157], v[190:193], v[12:15]
	v_mfma_f32_16x16x32_bf16 v[8:11], v[162:165], v[190:193], v[8:11]
	v_mfma_f32_16x16x32_bf16 v[4:7], v[154:157], v[206:209], v[4:7]
	v_mfma_f32_16x16x32_bf16 v[0:3], v[162:165], v[206:209], v[0:3]
	v_mfma_f32_16x16x32_bf16 v[44:47], v[158:161], v[178:181], v[44:47]
	v_mfma_f32_16x16x32_bf16 v[36:39], v[166:169], v[178:181], v[36:39]
	v_mfma_f32_16x16x32_bf16 v[28:31], v[158:161], v[186:189], v[28:31]
	v_mfma_f32_16x16x32_bf16 v[20:23], v[166:169], v[186:189], v[20:23]
	v_mfma_f32_16x16x32_bf16 v[12:15], v[158:161], v[194:197], v[12:15]
	v_mfma_f32_16x16x32_bf16 v[8:11], v[166:169], v[194:197], v[8:11]
	v_mfma_f32_16x16x32_bf16 v[4:7], v[158:161], v[210:213], v[4:7]
	v_mfma_f32_16x16x32_bf16 v[0:3], v[166:169], v[210:213], v[0:3]
	s_setprio 0
	s_barrier
	s_mov_b64 s[58:59], 0
	s_mov_b64 s[54:55], -1
	s_mov_b64 s[56:57], 0x100
	s_cbranch_vccz .LBB0_904
	s_and_b64 vcc, exec, s[20:21]
	s_cbranch_vccz .LBB0_907
	s_barrier

.LBB0_953:
	ds_read_b128 v[148:151], v145
	ds_read_b128 v[152:155], v145 offset:1024
	ds_read_b128 v[156:159], v145 offset:2048
	ds_read_b128 v[160:163], v145 offset:3072
	ds_read_b128 v[164:167], v146
	ds_read_b128 v[168:171], v146 offset:1024
	ds_read_b128 v[172:175], v146 offset:2048
	ds_read_b128 v[178:181], v146 offset:3072
	s_add_u32 s56, s54, 0x100
	s_addc_u32 s57, s55, 0
	s_cmp_eq_u32 vcc_hi, 20
	s_cselect_b32 s61, s93, s57
	s_cselect_b32 s60, s94, s56
	s_cselect_b32 s59, s95, vcc_lo
	s_cselect_b32 s58, s96, s97
	v_lshl_add_u64 v[140:141], s[54:55], 0, v[136:137]
	s_add_i32 m0, s67, 0xc000
	ds_read_b128 v[182:185], v147
	ds_read_b128 v[186:189], v147 offset:1024
	ds_read_b128 v[190:193], v147 offset:2048
	ds_read_b128 v[194:197], v147 offset:3072
	ds_read_b128 v[206:209], v147 offset:4096
	ds_read_b128 v[210:213], v147 offset:5120
	ds_read_b128 v[214:217], v147 offset:6144
	ds_read_b128 v[218:221], v147 offset:7168
	global_load_lds_dwordx4 v[140:141], off
	v_lshl_add_u64 v[140:141], s[54:55], 0, v[138:139]
	s_add_i32 m0, s67, 0xe000
	s_nop 0
	global_load_lds_dwordx4 v[140:141], off
	s_waitcnt vmcnt(8)
	s_waitcnt lgkmcnt(0)
	s_barrier
	s_setprio 1
	v_mfma_f32_16x16x32_bf16 v[124:127], v[148:151], v[182:185], v[124:127]
	v_mfma_f32_16x16x32_bf16 v[120:123], v[156:159], v[182:185], v[120:123]
	v_mfma_f32_16x16x32_bf16 v[116:119], v[148:151], v[190:193], v[116:119]
	v_mfma_f32_16x16x32_bf16 v[108:111], v[156:159], v[190:193], v[108:111]
	v_mfma_f32_16x16x32_bf16 v[100:103], v[148:151], v[206:209], v[100:103]
	v_mfma_f32_16x16x32_bf16 v[92:95], v[156:159], v[206:209], v[92:95]
	v_mfma_f32_16x16x32_bf16 v[84:87], v[148:151], v[214:217], v[84:87]
	v_mfma_f32_16x16x32_bf16 v[76:79], v[156:159], v[214:217], v[76:79]
	v_mfma_f32_16x16x32_bf16 v[124:127], v[152:155], v[186:189], v[124:127]
	v_mfma_f32_16x16x32_bf16 v[120:123], v[160:163], v[186:189], v[120:123]
	v_mfma_f32_16x16x32_bf16 v[116:119], v[152:155], v[194:197], v[116:119]
	v_mfma_f32_16x16x32_bf16 v[108:111], v[160:163], v[194:197], v[108:111]
	v_mfma_f32_16x16x32_bf16 v[100:103], v[152:155], v[210:213], v[100:103]
	v_mfma_f32_16x16x32_bf16 v[92:95], v[160:163], v[210:213], v[92:95]
	v_mfma_f32_16x16x32_bf16 v[84:87], v[152:155], v[218:221], v[84:87]
	v_mfma_f32_16x16x32_bf16 v[76:79], v[160:163], v[218:221], v[76:79]
	v_mfma_f32_16x16x32_bf16 v[112:115], v[164:167], v[182:185], v[112:115]
	v_mfma_f32_16x16x32_bf16 v[104:107], v[172:175], v[182:185], v[104:107]
	v_mfma_f32_16x16x32_bf16 v[96:99], v[164:167], v[190:193], v[96:99]
	v_mfma_f32_16x16x32_bf16 v[88:91], v[172:175], v[190:193], v[88:91]
	v_mfma_f32_16x16x32_bf16 v[80:83], v[164:167], v[206:209], v[80:83]
	v_mfma_f32_16x16x32_bf16 v[72:75], v[172:175], v[206:209], v[72:75]
	v_mfma_f32_16x16x32_bf16 v[68:71], v[164:167], v[214:217], v[68:71]
	v_mfma_f32_16x16x32_bf16 v[64:67], v[172:175], v[214:217], v[64:67]
	v_mfma_f32_16x16x32_bf16 v[112:115], v[168:171], v[186:189], v[112:115]
	v_mfma_f32_16x16x32_bf16 v[104:107], v[178:181], v[186:189], v[104:107]
	v_mfma_f32_16x16x32_bf16 v[96:99], v[168:171], v[194:197], v[96:99]
	v_mfma_f32_16x16x32_bf16 v[88:91], v[178:181], v[194:197], v[88:91]
	v_mfma_f32_16x16x32_bf16 v[80:83], v[168:171], v[210:213], v[80:83]
	v_mfma_f32_16x16x32_bf16 v[72:75], v[178:181], v[210:213], v[72:75]
	v_mfma_f32_16x16x32_bf16 v[68:71], v[168:171], v[218:221], v[68:71]
	v_mfma_f32_16x16x32_bf16 v[64:67], v[178:181], v[218:221], v[64:67]
	s_setprio 0
	s_barrier
	s_add_i32 s0, s79, s66
	v_lshl_add_u64 v[140:141], s[58:59], 0, v[130:131]
	s_mov_b32 m0, s0
	ds_read_b128 v[182:185], v147 offset:16384
	ds_read_b128 v[186:189], v147 offset:17408
	ds_read_b128 v[190:193], v147 offset:18432
	ds_read_b128 v[194:197], v147 offset:19456
	ds_read_b128 v[206:209], v147 offset:20480
	ds_read_b128 v[210:213], v147 offset:21504
	ds_read_b128 v[214:217], v147 offset:22528
	ds_read_b128 v[218:221], v147 offset:23552
	global_load_lds_dwordx4 v[140:141], off
	s_add_i32 m0, s0, 0x2000
	s_add_u32 s0, s58, 0x60000
	v_lshl_add_u64 v[198:199], s[58:59], 0, v[134:135]
	s_addc_u32 s1, s59, 0
	s_add_i32 s2, s80, s66
	global_load_lds_dwordx4 v[198:199], off
	v_lshl_add_u64 v[202:203], s[0:1], 0, v[130:131]
	s_mov_b32 m0, s2
	v_lshl_add_u64 v[222:223], s[60:61], 0, v[132:133]
	global_load_lds_dwordx4 v[202:203], off
	v_lshl_add_u64 v[202:203], s[0:1], 0, v[134:135]
	s_add_i32 m0, s2, 0x2000
	s_nop 0
	global_load_lds_dwordx4 v[202:203], off
	v_lshl_add_u64 v[202:203], s[60:61], 0, v[128:129]
	s_mov_b32 m0, s67
	s_nop 0
	global_load_lds_dwordx4 v[202:203], off
	s_mov_b32 m0, s68
	s_nop 0
	global_load_lds_dwordx4 v[222:223], off
	s_waitcnt vmcnt(8)
	s_waitcnt lgkmcnt(0)
	s_barrier
	s_setprio 1
	v_mfma_f32_16x16x32_bf16 v[60:63], v[148:151], v[182:185], v[60:63]
	v_mfma_f32_16x16x32_bf16 v[56:59], v[156:159], v[182:185], v[56:59]
	v_mfma_f32_16x16x32_bf16 v[52:55], v[148:151], v[190:193], v[52:55]
	v_mfma_f32_16x16x32_bf16 v[44:47], v[156:159], v[190:193], v[44:47]
	v_mfma_f32_16x16x32_bf16 v[36:39], v[148:151], v[206:209], v[36:39]
	v_mfma_f32_16x16x32_bf16 v[28:31], v[156:159], v[206:209], v[28:31]
	v_mfma_f32_16x16x32_bf16 v[20:23], v[148:151], v[214:217], v[20:23]
	v_mfma_f32_16x16x32_bf16 v[12:15], v[156:159], v[214:217], v[12:15]
	v_mfma_f32_16x16x32_bf16 v[60:63], v[152:155], v[186:189], v[60:63]
	v_mfma_f32_16x16x32_bf16 v[56:59], v[160:163], v[186:189], v[56:59]
	v_mfma_f32_16x16x32_bf16 v[52:55], v[152:155], v[194:197], v[52:55]
	v_mfma_f32_16x16x32_bf16 v[44:47], v[160:163], v[194:197], v[44:47]
	v_mfma_f32_16x16x32_bf16 v[36:39], v[152:155], v[210:213], v[36:39]
	v_mfma_f32_16x16x32_bf16 v[28:31], v[160:163], v[210:213], v[28:31]
	v_mfma_f32_16x16x32_bf16 v[20:23], v[152:155], v[218:221], v[20:23]
	v_mfma_f32_16x16x32_bf16 v[12:15], v[160:163], v[218:221], v[12:15]
	v_mfma_f32_16x16x32_bf16 v[48:51], v[164:167], v[182:185], v[48:51]
	v_mfma_f32_16x16x32_bf16 v[40:43], v[172:175], v[182:185], v[40:43]
	v_mfma_f32_16x16x32_bf16 v[32:35], v[164:167], v[190:193], v[32:35]
	v_mfma_f32_16x16x32_bf16 v[24:27], v[172:175], v[190:193], v[24:27]
	v_mfma_f32_16x16x32_bf16 v[16:19], v[164:167], v[206:209], v[16:19]
	v_mfma_f32_16x16x32_bf16 v[8:11], v[172:175], v[206:209], v[8:11]
	v_mfma_f32_16x16x32_bf16 v[4:7], v[164:167], v[214:217], v[4:7]
	v_mfma_f32_16x16x32_bf16 v[0:3], v[172:175], v[214:217], v[0:3]
	v_mfma_f32_16x16x32_bf16 v[48:51], v[168:171], v[186:189], v[48:51]
	v_mfma_f32_16x16x32_bf16 v[40:43], v[178:181], v[186:189], v[40:43]
	v_mfma_f32_16x16x32_bf16 v[32:35], v[168:171], v[194:197], v[32:35]
	v_mfma_f32_16x16x32_bf16 v[24:27], v[178:181], v[194:197], v[24:27]
	v_mfma_f32_16x16x32_bf16 v[16:19], v[168:171], v[210:213], v[16:19]
	v_mfma_f32_16x16x32_bf16 v[8:11], v[178:181], v[210:213], v[8:11]
	v_mfma_f32_16x16x32_bf16 v[4:7], v[168:171], v[218:221], v[4:7]
	v_mfma_f32_16x16x32_bf16 v[0:3], v[178:181], v[218:221], v[0:3]
	s_setprio 0
	s_barrier
	s_add_i32 s2, 0, 0x18000
	s_add_i32 s3, 0, 0x1c000
	v_add_u32_e32 v160, s2, v144
	v_add_u32_e32 v177, s3, v144
	ds_read_b128 v[148:151], v160
	ds_read_b128 v[152:155], v160 offset:1024
	ds_read_b128 v[156:159], v160 offset:2048
	ds_read_b128 v[160:163], v160 offset:3072
	ds_read_b128 v[164:167], v177
	ds_read_b128 v[168:171], v177 offset:1024
	ds_read_b128 v[172:175], v177 offset:2048
	ds_read_b128 v[178:181], v177 offset:3072
	s_add_u32 s0, s60, 0x60000
	s_addc_u32 s1, s61, 0
	s_mov_b32 m0, s69
	v_lshl_add_u64 v[224:225], s[0:1], 0, v[128:129]
	ds_read_b128 v[182:185], v147 offset:32768
	ds_read_b128 v[186:189], v147 offset:33792
	ds_read_b128 v[190:193], v147 offset:34816
	ds_read_b128 v[194:197], v147 offset:35840
	ds_read_b128 v[206:209], v147 offset:36864
	ds_read_b128 v[210:213], v147 offset:37888
	ds_read_b128 v[214:217], v147 offset:38912
	ds_read_b128 v[218:221], v147 offset:39936
	global_load_lds_dwordx4 v[224:225], off
	v_lshl_add_u64 v[224:225], s[0:1], 0, v[132:133]
	s_mov_b32 m0, s70
	s_nop 0
	global_load_lds_dwordx4 v[224:225], off
	s_waitcnt vmcnt(8)
	s_waitcnt lgkmcnt(0)
	s_barrier
	s_setprio 1
	v_mfma_f32_16x16x32_bf16 v[124:127], v[148:151], v[182:185], v[124:127]
	v_mfma_f32_16x16x32_bf16 v[120:123], v[156:159], v[182:185], v[120:123]
	v_mfma_f32_16x16x32_bf16 v[116:119], v[148:151], v[190:193], v[116:119]
	v_mfma_f32_16x16x32_bf16 v[108:111], v[156:159], v[190:193], v[108:111]
	v_mfma_f32_16x16x32_bf16 v[100:103], v[148:151], v[206:209], v[100:103]
	v_mfma_f32_16x16x32_bf16 v[92:95], v[156:159], v[206:209], v[92:95]
	v_mfma_f32_16x16x32_bf16 v[84:87], v[148:151], v[214:217], v[84:87]
	v_mfma_f32_16x16x32_bf16 v[76:79], v[156:159], v[214:217], v[76:79]
	v_mfma_f32_16x16x32_bf16 v[124:127], v[152:155], v[186:189], v[124:127]
	v_mfma_f32_16x16x32_bf16 v[120:123], v[160:163], v[186:189], v[120:123]
	v_mfma_f32_16x16x32_bf16 v[116:119], v[152:155], v[194:197], v[116:119]
	v_mfma_f32_16x16x32_bf16 v[108:111], v[160:163], v[194:197], v[108:111]
	v_mfma_f32_16x16x32_bf16 v[100:103], v[152:155], v[210:213], v[100:103]
	v_mfma_f32_16x16x32_bf16 v[92:95], v[160:163], v[210:213], v[92:95]
	v_mfma_f32_16x16x32_bf16 v[84:87], v[152:155], v[218:221], v[84:87]
	v_mfma_f32_16x16x32_bf16 v[76:79], v[160:163], v[218:221], v[76:79]
	v_mfma_f32_16x16x32_bf16 v[112:115], v[164:167], v[182:185], v[112:115]
	v_mfma_f32_16x16x32_bf16 v[104:107], v[172:175], v[182:185], v[104:107]
	v_mfma_f32_16x16x32_bf16 v[96:99], v[164:167], v[190:193], v[96:99]
	v_mfma_f32_16x16x32_bf16 v[88:91], v[172:175], v[190:193], v[88:91]
	v_mfma_f32_16x16x32_bf16 v[80:83], v[164:167], v[206:209], v[80:83]
	v_mfma_f32_16x16x32_bf16 v[72:75], v[172:175], v[206:209], v[72:75]
	v_mfma_f32_16x16x32_bf16 v[68:71], v[164:167], v[214:217], v[68:71]
	v_mfma_f32_16x16x32_bf16 v[64:67], v[172:175], v[214:217], v[64:67]
	v_mfma_f32_16x16x32_bf16 v[112:115], v[168:171], v[186:189], v[112:115]
	v_mfma_f32_16x16x32_bf16 v[104:107], v[178:181], v[186:189], v[104:107]
	v_mfma_f32_16x16x32_bf16 v[96:99], v[168:171], v[194:197], v[96:99]
	v_mfma_f32_16x16x32_bf16 v[88:91], v[178:181], v[194:197], v[88:91]
	v_mfma_f32_16x16x32_bf16 v[80:83], v[168:171], v[210:213], v[80:83]
	v_mfma_f32_16x16x32_bf16 v[72:75], v[178:181], v[210:213], v[72:75]
	v_mfma_f32_16x16x32_bf16 v[68:71], v[168:171], v[218:221], v[68:71]
	v_mfma_f32_16x16x32_bf16 v[64:67], v[178:181], v[218:221], v[64:67]
	s_setprio 0
	s_barrier
	s_add_i32 s0, s2, s66
	v_lshl_add_u64 v[140:141], v[140:141], 0, s[12:13]
	s_mov_b32 m0, s0
	ds_read_b128 v[182:185], v147 offset:49152
	ds_read_b128 v[186:189], v147 offset:50176
	ds_read_b128 v[190:193], v147 offset:51200
	ds_read_b128 v[194:197], v147 offset:52224
	ds_read_b128 v[206:209], v147 offset:53248
	ds_read_b128 v[210:213], v147 offset:54272
	ds_read_b128 v[214:217], v147 offset:55296
	ds_read_b128 v[218:221], v147 offset:56320
	global_load_lds_dwordx4 v[140:141], off
	s_add_i32 m0, s0, 0x2000
	s_add_u32 s0, s58, 0x60080
	v_lshl_add_u64 v[140:141], v[198:199], 0, s[12:13]
	s_addc_u32 s1, s59, 0
	s_add_i32 s2, s3, s66
	global_load_lds_dwordx4 v[140:141], off
	v_lshl_add_u64 v[140:141], s[0:1], 0, v[130:131]
	s_mov_b32 m0, s2
	s_nop 0
	global_load_lds_dwordx4 v[140:141], off
	v_lshl_add_u64 v[140:141], s[0:1], 0, v[134:135]
	s_add_i32 m0, s2, 0x2000
	s_nop 0
	global_load_lds_dwordx4 v[140:141], off
	v_lshl_add_u64 v[140:141], v[202:203], 0, s[12:13]
	s_mov_b32 m0, s77
	s_nop 0
	global_load_lds_dwordx4 v[140:141], off
	v_lshl_add_u64 v[140:141], v[222:223], 0, s[12:13]
	s_mov_b32 m0, s78
	s_nop 0
	global_load_lds_dwordx4 v[140:141], off
	s_waitcnt vmcnt(8)
	s_waitcnt lgkmcnt(0)
	s_barrier
	s_setprio 1
	v_mfma_f32_16x16x32_bf16 v[60:63], v[148:151], v[182:185], v[60:63]
	v_mfma_f32_16x16x32_bf16 v[56:59], v[156:159], v[182:185], v[56:59]
	v_mfma_f32_16x16x32_bf16 v[52:55], v[148:151], v[190:193], v[52:55]
	v_mfma_f32_16x16x32_bf16 v[44:47], v[156:159], v[190:193], v[44:47]
	v_mfma_f32_16x16x32_bf16 v[36:39], v[148:151], v[206:209], v[36:39]
	v_mfma_f32_16x16x32_bf16 v[28:31], v[156:159], v[206:209], v[28:31]
	v_mfma_f32_16x16x32_bf16 v[20:23], v[148:151], v[214:217], v[20:23]
	v_mfma_f32_16x16x32_bf16 v[12:15], v[156:159], v[214:217], v[12:15]
	v_mfma_f32_16x16x32_bf16 v[60:63], v[152:155], v[186:189], v[60:63]
	v_mfma_f32_16x16x32_bf16 v[56:59], v[160:163], v[186:189], v[56:59]
	v_mfma_f32_16x16x32_bf16 v[52:55], v[152:155], v[194:197], v[52:55]
	v_mfma_f32_16x16x32_bf16 v[44:47], v[160:163], v[194:197], v[44:47]
	v_mfma_f32_16x16x32_bf16 v[36:39], v[152:155], v[210:213], v[36:39]
	v_mfma_f32_16x16x32_bf16 v[28:31], v[160:163], v[210:213], v[28:31]
	v_mfma_f32_16x16x32_bf16 v[20:23], v[152:155], v[218:221], v[20:23]
	v_mfma_f32_16x16x32_bf16 v[12:15], v[160:163], v[218:221], v[12:15]
	v_mfma_f32_16x16x32_bf16 v[48:51], v[164:167], v[182:185], v[48:51]
	v_mfma_f32_16x16x32_bf16 v[40:43], v[172:175], v[182:185], v[40:43]
	v_mfma_f32_16x16x32_bf16 v[32:35], v[164:167], v[190:193], v[32:35]
	v_mfma_f32_16x16x32_bf16 v[24:27], v[172:175], v[190:193], v[24:27]
	v_mfma_f32_16x16x32_bf16 v[16:19], v[164:167], v[206:209], v[16:19]
	v_mfma_f32_16x16x32_bf16 v[8:11], v[172:175], v[206:209], v[8:11]
	v_mfma_f32_16x16x32_bf16 v[4:7], v[164:167], v[214:217], v[4:7]
	v_mfma_f32_16x16x32_bf16 v[0:3], v[172:175], v[214:217], v[0:3]
	v_mfma_f32_16x16x32_bf16 v[48:51], v[168:171], v[186:189], v[48:51]
	v_mfma_f32_16x16x32_bf16 v[40:43], v[178:181], v[186:189], v[40:43]
	v_mfma_f32_16x16x32_bf16 v[32:35], v[168:171], v[194:197], v[32:35]
	v_mfma_f32_16x16x32_bf16 v[24:27], v[178:181], v[194:197], v[24:27]
	v_mfma_f32_16x16x32_bf16 v[16:19], v[168:171], v[210:213], v[16:19]
	v_mfma_f32_16x16x32_bf16 v[8:11], v[178:181], v[210:213], v[8:11]
	v_mfma_f32_16x16x32_bf16 v[4:7], v[168:171], v[218:221], v[4:7]
	v_mfma_f32_16x16x32_bf16 v[0:3], v[178:181], v[218:221], v[0:3]
	s_setprio 0
	s_barrier
	s_add_i32 vcc_hi, vcc_hi, 2
	s_add_u32 s97, s97, 0x100
	s_addc_u32 vcc_lo, vcc_lo, 0
	s_cmp_gt_u32 vcc_hi, 21
	s_mov_b64 s[54:55], s[56:57]
	s_cbranch_scc0 .LBB0_953
	s_and_b64 vcc, exec, s[14:15]
	s_cbranch_vccz .LBB0_956
	s_barrier

.LBB0_979:
	s_add_u32 s2, s46, s58
	s_addc_u32 s3, s47, 0
	s_add_u32 s38, s2, 0x100
	s_addc_u32 s39, s3, 0
	s_and_b64 s[0:1], s[52:53], exec
	s_cselect_b32 s57, s23, s39
	s_cselect_b32 s56, s85, s38
	s_add_u32 s0, s34, s58
	s_addc_u32 s1, s35, 0
	s_add_u32 s38, s0, 0x100
	s_addc_u32 s39, s1, 0
	s_and_b64 s[0:1], s[52:53], exec
	s_cselect_b32 s59, s86, s39
	s_cselect_b32 s58, s87, s38
	s_add_u32 s62, s2, 0x10080
	ds_read_b128 v[144:147], v141
	ds_read_b128 v[148:151], v141 offset:1024
	ds_read_b128 v[152:155], v141 offset:2048
	ds_read_b128 v[156:159], v141 offset:3072
	ds_read_b128 v[160:163], v142
	ds_read_b128 v[164:167], v142 offset:1024
	ds_read_b128 v[168:171], v142 offset:2048
	ds_read_b128 v[172:175], v142 offset:3072
	s_addc_u32 s63, s3, 0
	s_add_i32 s38, s78, s66
	s_add_i32 m0, s25, 0xc000
	s_add_i32 s39, s25, 0xe000
	s_add_i32 s0, s38, 0x2000
	s_add_u32 s60, s58, 0x10000
	s_addc_u32 s61, s59, 0
	s_add_i32 s91, s79, s66
	s_add_i32 s76, s91, 0x2000
	s_add_i32 s3, 0, 0x18000
	s_add_i32 s2, 0, 0x1c000
	v_cndmask_b32_e64 v136, 0, 1, s[54:55]
	s_add_u32 s54, s56, 0x10000
	s_addc_u32 s55, s57, 0
	s_add_i32 s1, s3, s66
	s_add_i32 s89, s1, 0x2000
	s_add_u32 s52, s58, 0x10080
	s_addc_u32 s53, s59, 0
	s_add_i32 s90, s2, s66
	s_add_i32 s88, s90, 0x2000
	v_cmp_ne_u32_e32 vcc, 1, v136
	v_lshl_add_u64 v[136:137], s[62:63], 0, v[128:129]
	ds_read_b128 v[178:181], v143
	ds_read_b128 v[182:185], v143 offset:1024
	ds_read_b128 v[186:189], v143 offset:2048
	ds_read_b128 v[190:193], v143 offset:3072
	ds_read_b128 v[194:197], v143 offset:4096
	ds_read_b128 v[206:209], v143 offset:5120
	ds_read_b128 v[210:213], v143 offset:6144
	ds_read_b128 v[214:217], v143 offset:7168
	global_load_lds_dwordx4 v[136:137], off
	v_lshl_add_u64 v[136:137], s[62:63], 0, v[132:133]
	s_mov_b32 m0, s39
	s_nop 0
	global_load_lds_dwordx4 v[136:137], off
	s_waitcnt vmcnt(8)
	s_waitcnt lgkmcnt(0)
	s_barrier
	s_setprio 1
	v_mfma_f32_16x16x32_bf16 v[124:127], v[144:147], v[178:181], v[124:127]
	v_mfma_f32_16x16x32_bf16 v[120:123], v[152:155], v[178:181], v[120:123]
	v_mfma_f32_16x16x32_bf16 v[116:119], v[144:147], v[186:189], v[116:119]
	v_mfma_f32_16x16x32_bf16 v[108:111], v[152:155], v[186:189], v[108:111]
	v_mfma_f32_16x16x32_bf16 v[100:103], v[144:147], v[194:197], v[100:103]
	v_mfma_f32_16x16x32_bf16 v[92:95], v[152:155], v[194:197], v[92:95]
	v_mfma_f32_16x16x32_bf16 v[84:87], v[144:147], v[210:213], v[84:87]
	v_mfma_f32_16x16x32_bf16 v[76:79], v[152:155], v[210:213], v[76:79]
	v_mfma_f32_16x16x32_bf16 v[124:127], v[148:151], v[182:185], v[124:127]
	v_mfma_f32_16x16x32_bf16 v[120:123], v[156:159], v[182:185], v[120:123]
	v_mfma_f32_16x16x32_bf16 v[116:119], v[148:151], v[190:193], v[116:119]
	v_mfma_f32_16x16x32_bf16 v[108:111], v[156:159], v[190:193], v[108:111]
	v_mfma_f32_16x16x32_bf16 v[100:103], v[148:151], v[206:209], v[100:103]
	v_mfma_f32_16x16x32_bf16 v[92:95], v[156:159], v[206:209], v[92:95]
	v_mfma_f32_16x16x32_bf16 v[84:87], v[148:151], v[214:217], v[84:87]
	v_mfma_f32_16x16x32_bf16 v[76:79], v[156:159], v[214:217], v[76:79]
	v_mfma_f32_16x16x32_bf16 v[112:115], v[160:163], v[178:181], v[112:115]
	v_mfma_f32_16x16x32_bf16 v[104:107], v[168:171], v[178:181], v[104:107]
	v_mfma_f32_16x16x32_bf16 v[96:99], v[160:163], v[186:189], v[96:99]
	v_mfma_f32_16x16x32_bf16 v[88:91], v[168:171], v[186:189], v[88:91]
	v_mfma_f32_16x16x32_bf16 v[80:83], v[160:163], v[194:197], v[80:83]
	v_mfma_f32_16x16x32_bf16 v[72:75], v[168:171], v[194:197], v[72:75]
	v_mfma_f32_16x16x32_bf16 v[68:71], v[160:163], v[210:213], v[68:71]
	v_mfma_f32_16x16x32_bf16 v[64:67], v[168:171], v[210:213], v[64:67]
	v_mfma_f32_16x16x32_bf16 v[112:115], v[164:167], v[182:185], v[112:115]
	v_mfma_f32_16x16x32_bf16 v[104:107], v[172:175], v[182:185], v[104:107]
	v_mfma_f32_16x16x32_bf16 v[96:99], v[164:167], v[190:193], v[96:99]
	v_mfma_f32_16x16x32_bf16 v[88:91], v[172:175], v[190:193], v[88:91]
	v_mfma_f32_16x16x32_bf16 v[80:83], v[164:167], v[206:209], v[80:83]
	v_mfma_f32_16x16x32_bf16 v[72:75], v[172:175], v[206:209], v[72:75]
	v_mfma_f32_16x16x32_bf16 v[68:71], v[164:167], v[214:217], v[68:71]
	v_mfma_f32_16x16x32_bf16 v[64:67], v[172:175], v[214:217], v[64:67]
	s_setprio 0
	s_barrier
	s_mov_b32 m0, s38
	v_lshl_add_u64 v[136:137], s[58:59], 0, v[130:131]
	ds_read_b128 v[178:181], v143 offset:16384
	ds_read_b128 v[182:185], v143 offset:17408
	ds_read_b128 v[186:189], v143 offset:18432
	ds_read_b128 v[190:193], v143 offset:19456
	ds_read_b128 v[194:197], v143 offset:20480
	ds_read_b128 v[206:209], v143 offset:21504
	ds_read_b128 v[210:213], v143 offset:22528
	ds_read_b128 v[214:217], v143 offset:23552
	global_load_lds_dwordx4 v[136:137], off
	v_lshl_add_u64 v[198:199], s[58:59], 0, v[134:135]
	s_mov_b32 m0, s0
	v_lshl_add_u64 v[202:203], s[60:61], 0, v[130:131]
	global_load_lds_dwordx4 v[198:199], off
	s_mov_b32 m0, s91
	v_lshl_add_u64 v[218:219], s[56:57], 0, v[132:133]
	global_load_lds_dwordx4 v[202:203], off
	v_lshl_add_u64 v[202:203], s[60:61], 0, v[134:135]
	s_mov_b32 m0, s76
	s_nop 0
	global_load_lds_dwordx4 v[202:203], off
	v_lshl_add_u64 v[202:203], s[56:57], 0, v[128:129]
	s_mov_b32 m0, s25
	s_nop 0
	global_load_lds_dwordx4 v[202:203], off
	s_mov_b32 m0, s69
	s_nop 0
	global_load_lds_dwordx4 v[218:219], off
	s_waitcnt vmcnt(8)
	s_waitcnt lgkmcnt(0)
	s_barrier
	s_setprio 1
	v_mfma_f32_16x16x32_bf16 v[60:63], v[144:147], v[178:181], v[60:63]
	v_mfma_f32_16x16x32_bf16 v[56:59], v[152:155], v[178:181], v[56:59]
	v_mfma_f32_16x16x32_bf16 v[52:55], v[144:147], v[186:189], v[52:55]
	v_mfma_f32_16x16x32_bf16 v[44:47], v[152:155], v[186:189], v[44:47]
	v_mfma_f32_16x16x32_bf16 v[36:39], v[144:147], v[194:197], v[36:39]
	v_mfma_f32_16x16x32_bf16 v[28:31], v[152:155], v[194:197], v[28:31]
	v_mfma_f32_16x16x32_bf16 v[20:23], v[144:147], v[210:213], v[20:23]
	v_mfma_f32_16x16x32_bf16 v[12:15], v[152:155], v[210:213], v[12:15]
	v_mfma_f32_16x16x32_bf16 v[60:63], v[148:151], v[182:185], v[60:63]
	v_mfma_f32_16x16x32_bf16 v[56:59], v[156:159], v[182:185], v[56:59]
	v_mfma_f32_16x16x32_bf16 v[52:55], v[148:151], v[190:193], v[52:55]
	v_mfma_f32_16x16x32_bf16 v[44:47], v[156:159], v[190:193], v[44:47]
	v_mfma_f32_16x16x32_bf16 v[36:39], v[148:151], v[206:209], v[36:39]
	v_mfma_f32_16x16x32_bf16 v[28:31], v[156:159], v[206:209], v[28:31]
	v_mfma_f32_16x16x32_bf16 v[20:23], v[148:151], v[214:217], v[20:23]
	v_mfma_f32_16x16x32_bf16 v[12:15], v[156:159], v[214:217], v[12:15]
	v_mfma_f32_16x16x32_bf16 v[48:51], v[160:163], v[178:181], v[48:51]
	v_mfma_f32_16x16x32_bf16 v[40:43], v[168:171], v[178:181], v[40:43]
	v_mfma_f32_16x16x32_bf16 v[32:35], v[160:163], v[186:189], v[32:35]
	v_mfma_f32_16x16x32_bf16 v[24:27], v[168:171], v[186:189], v[24:27]
	v_mfma_f32_16x16x32_bf16 v[16:19], v[160:163], v[194:197], v[16:19]
	v_mfma_f32_16x16x32_bf16 v[8:11], v[168:171], v[194:197], v[8:11]
	v_mfma_f32_16x16x32_bf16 v[4:7], v[160:163], v[210:213], v[4:7]
	v_mfma_f32_16x16x32_bf16 v[0:3], v[168:171], v[210:213], v[0:3]
	v_mfma_f32_16x16x32_bf16 v[48:51], v[164:167], v[182:185], v[48:51]
	v_mfma_f32_16x16x32_bf16 v[40:43], v[172:175], v[182:185], v[40:43]
	v_mfma_f32_16x16x32_bf16 v[32:35], v[164:167], v[190:193], v[32:35]
	v_mfma_f32_16x16x32_bf16 v[24:27], v[172:175], v[190:193], v[24:27]
	v_mfma_f32_16x16x32_bf16 v[16:19], v[164:167], v[206:209], v[16:19]
	v_mfma_f32_16x16x32_bf16 v[8:11], v[172:175], v[206:209], v[8:11]
	v_mfma_f32_16x16x32_bf16 v[4:7], v[164:167], v[214:217], v[4:7]
	v_mfma_f32_16x16x32_bf16 v[0:3], v[172:175], v[214:217], v[0:3]
	s_setprio 0
	s_barrier
	v_add_u32_e32 v156, s3, v140
	v_add_u32_e32 v172, s2, v140
	ds_read_b128 v[144:147], v156
	ds_read_b128 v[148:151], v156 offset:1024
	ds_read_b128 v[152:155], v156 offset:2048
	ds_read_b128 v[156:159], v156 offset:3072
	ds_read_b128 v[160:163], v172
	ds_read_b128 v[164:167], v172 offset:1024
	ds_read_b128 v[168:171], v172 offset:2048
	ds_read_b128 v[172:175], v172 offset:3072
	s_mov_b32 m0, s70
	v_lshl_add_u64 v[220:221], s[54:55], 0, v[128:129]
	ds_read_b128 v[178:181], v143 offset:32768
	ds_read_b128 v[182:185], v143 offset:33792
	ds_read_b128 v[186:189], v143 offset:34816
	ds_read_b128 v[190:193], v143 offset:35840
	ds_read_b128 v[194:197], v143 offset:36864
	ds_read_b128 v[206:209], v143 offset:37888
	ds_read_b128 v[210:213], v143 offset:38912
	ds_read_b128 v[214:217], v143 offset:39936
	global_load_lds_dwordx4 v[220:221], off
	v_lshl_add_u64 v[220:221], s[54:55], 0, v[132:133]
	s_mov_b32 m0, s71
	s_nop 0
	global_load_lds_dwordx4 v[220:221], off
	s_waitcnt vmcnt(8)
	s_waitcnt lgkmcnt(0)
	s_barrier
	s_setprio 1
	v_mfma_f32_16x16x32_bf16 v[124:127], v[144:147], v[178:181], v[124:127]
	v_mfma_f32_16x16x32_bf16 v[120:123], v[152:155], v[178:181], v[120:123]
	v_mfma_f32_16x16x32_bf16 v[116:119], v[144:147], v[186:189], v[116:119]
	v_mfma_f32_16x16x32_bf16 v[108:111], v[152:155], v[186:189], v[108:111]
	v_mfma_f32_16x16x32_bf16 v[100:103], v[144:147], v[194:197], v[100:103]
	v_mfma_f32_16x16x32_bf16 v[92:95], v[152:155], v[194:197], v[92:95]
	v_mfma_f32_16x16x32_bf16 v[84:87], v[144:147], v[210:213], v[84:87]
	v_mfma_f32_16x16x32_bf16 v[76:79], v[152:155], v[210:213], v[76:79]
	v_mfma_f32_16x16x32_bf16 v[124:127], v[148:151], v[182:185], v[124:127]
	v_mfma_f32_16x16x32_bf16 v[120:123], v[156:159], v[182:185], v[120:123]
	v_mfma_f32_16x16x32_bf16 v[116:119], v[148:151], v[190:193], v[116:119]
	v_mfma_f32_16x16x32_bf16 v[108:111], v[156:159], v[190:193], v[108:111]
	v_mfma_f32_16x16x32_bf16 v[100:103], v[148:151], v[206:209], v[100:103]
	v_mfma_f32_16x16x32_bf16 v[92:95], v[156:159], v[206:209], v[92:95]
	v_mfma_f32_16x16x32_bf16 v[84:87], v[148:151], v[214:217], v[84:87]
	v_mfma_f32_16x16x32_bf16 v[76:79], v[156:159], v[214:217], v[76:79]
	v_mfma_f32_16x16x32_bf16 v[112:115], v[160:163], v[178:181], v[112:115]
	v_mfma_f32_16x16x32_bf16 v[104:107], v[168:171], v[178:181], v[104:107]
	v_mfma_f32_16x16x32_bf16 v[96:99], v[160:163], v[186:189], v[96:99]
	v_mfma_f32_16x16x32_bf16 v[88:91], v[168:171], v[186:189], v[88:91]
	v_mfma_f32_16x16x32_bf16 v[80:83], v[160:163], v[194:197], v[80:83]
	v_mfma_f32_16x16x32_bf16 v[72:75], v[168:171], v[194:197], v[72:75]
	v_mfma_f32_16x16x32_bf16 v[68:71], v[160:163], v[210:213], v[68:71]
	v_mfma_f32_16x16x32_bf16 v[64:67], v[168:171], v[210:213], v[64:67]
	v_mfma_f32_16x16x32_bf16 v[112:115], v[164:167], v[182:185], v[112:115]
	v_mfma_f32_16x16x32_bf16 v[104:107], v[172:175], v[182:185], v[104:107]
	v_mfma_f32_16x16x32_bf16 v[96:99], v[164:167], v[190:193], v[96:99]
	v_mfma_f32_16x16x32_bf16 v[88:91], v[172:175], v[190:193], v[88:91]
	v_mfma_f32_16x16x32_bf16 v[80:83], v[164:167], v[206:209], v[80:83]
	v_mfma_f32_16x16x32_bf16 v[72:75], v[172:175], v[206:209], v[72:75]
	v_mfma_f32_16x16x32_bf16 v[68:71], v[164:167], v[214:217], v[68:71]
	v_mfma_f32_16x16x32_bf16 v[64:67], v[172:175], v[214:217], v[64:67]
	s_setprio 0
	s_barrier
	s_mov_b32 m0, s1
	v_lshl_add_u64 v[136:137], v[136:137], 0, s[10:11]
	ds_read_b128 v[178:181], v143 offset:49152
	ds_read_b128 v[182:185], v143 offset:50176
	ds_read_b128 v[186:189], v143 offset:51200
	ds_read_b128 v[190:193], v143 offset:52224
	ds_read_b128 v[194:197], v143 offset:53248
	ds_read_b128 v[206:209], v143 offset:54272
	ds_read_b128 v[210:213], v143 offset:55296
	ds_read_b128 v[214:217], v143 offset:56320
	global_load_lds_dwordx4 v[136:137], off
	v_lshl_add_u64 v[136:137], v[198:199], 0, s[10:11]
	s_mov_b32 m0, s89
	s_nop 0
	global_load_lds_dwordx4 v[136:137], off
	v_lshl_add_u64 v[136:137], s[52:53], 0, v[130:131]
	s_mov_b32 m0, s90
	s_nop 0
	global_load_lds_dwordx4 v[136:137], off
	v_lshl_add_u64 v[136:137], s[52:53], 0, v[134:135]
	s_mov_b32 m0, s88
	s_nop 0
	global_load_lds_dwordx4 v[136:137], off
	v_lshl_add_u64 v[136:137], v[202:203], 0, s[10:11]
	s_mov_b32 m0, s75
	s_nop 0
	global_load_lds_dwordx4 v[136:137], off
	v_lshl_add_u64 v[136:137], v[218:219], 0, s[10:11]
	s_mov_b32 m0, s77
	s_nop 0
	global_load_lds_dwordx4 v[136:137], off
	s_waitcnt vmcnt(8)
	s_waitcnt lgkmcnt(0)
	s_barrier
	s_setprio 1
	v_mfma_f32_16x16x32_bf16 v[60:63], v[144:147], v[178:181], v[60:63]
	v_mfma_f32_16x16x32_bf16 v[56:59], v[152:155], v[178:181], v[56:59]
	v_mfma_f32_16x16x32_bf16 v[52:55], v[144:147], v[186:189], v[52:55]
	v_mfma_f32_16x16x32_bf16 v[44:47], v[152:155], v[186:189], v[44:47]
	v_mfma_f32_16x16x32_bf16 v[36:39], v[144:147], v[194:197], v[36:39]
	v_mfma_f32_16x16x32_bf16 v[28:31], v[152:155], v[194:197], v[28:31]
	v_mfma_f32_16x16x32_bf16 v[20:23], v[144:147], v[210:213], v[20:23]
	v_mfma_f32_16x16x32_bf16 v[12:15], v[152:155], v[210:213], v[12:15]
	v_mfma_f32_16x16x32_bf16 v[60:63], v[148:151], v[182:185], v[60:63]
	v_mfma_f32_16x16x32_bf16 v[56:59], v[156:159], v[182:185], v[56:59]
	v_mfma_f32_16x16x32_bf16 v[52:55], v[148:151], v[190:193], v[52:55]
	v_mfma_f32_16x16x32_bf16 v[44:47], v[156:159], v[190:193], v[44:47]
	v_mfma_f32_16x16x32_bf16 v[36:39], v[148:151], v[206:209], v[36:39]
	v_mfma_f32_16x16x32_bf16 v[28:31], v[156:159], v[206:209], v[28:31]
	v_mfma_f32_16x16x32_bf16 v[20:23], v[148:151], v[214:217], v[20:23]
	v_mfma_f32_16x16x32_bf16 v[12:15], v[156:159], v[214:217], v[12:15]
	v_mfma_f32_16x16x32_bf16 v[48:51], v[160:163], v[178:181], v[48:51]
	v_mfma_f32_16x16x32_bf16 v[40:43], v[168:171], v[178:181], v[40:43]
	v_mfma_f32_16x16x32_bf16 v[32:35], v[160:163], v[186:189], v[32:35]
	v_mfma_f32_16x16x32_bf16 v[24:27], v[168:171], v[186:189], v[24:27]
	v_mfma_f32_16x16x32_bf16 v[16:19], v[160:163], v[194:197], v[16:19]
	v_mfma_f32_16x16x32_bf16 v[8:11], v[168:171], v[194:197], v[8:11]
	v_mfma_f32_16x16x32_bf16 v[4:7], v[160:163], v[210:213], v[4:7]
	v_mfma_f32_16x16x32_bf16 v[0:3], v[168:171], v[210:213], v[0:3]
	v_mfma_f32_16x16x32_bf16 v[48:51], v[164:167], v[182:185], v[48:51]
	v_mfma_f32_16x16x32_bf16 v[40:43], v[172:175], v[182:185], v[40:43]
	v_mfma_f32_16x16x32_bf16 v[32:35], v[164:167], v[190:193], v[32:35]
	v_mfma_f32_16x16x32_bf16 v[24:27], v[172:175], v[190:193], v[24:27]
	v_mfma_f32_16x16x32_bf16 v[16:19], v[164:167], v[206:209], v[16:19]
	v_mfma_f32_16x16x32_bf16 v[8:11], v[172:175], v[206:209], v[8:11]
	v_mfma_f32_16x16x32_bf16 v[4:7], v[164:167], v[214:217], v[4:7]
	v_mfma_f32_16x16x32_bf16 v[0:3], v[172:175], v[214:217], v[0:3]
	s_setprio 0
	s_barrier
	s_movk_i32 s58, 0x100
	s_mov_b64 s[54:55], 0
	s_mov_b64 s[52:53], -1
	s_cbranch_vccz .LBB0_979
	s_and_b64 vcc, exec, s[12:13]
	s_cbranch_vccz .LBB0_982
	s_barrier

.LBB0_1037:
	ds_read_b128 v[128:131], v157
	ds_read_b128 v[132:135], v157 offset:1024
	ds_read_b128 v[136:139], v157 offset:2048
	ds_read_b128 v[140:143], v157 offset:3072
	ds_read_b128 v[160:163], v158
	ds_read_b128 v[164:167], v158 offset:1024
	ds_read_b128 v[168:171], v158 offset:2048
	ds_read_b128 v[172:175], v158 offset:3072
	s_add_u32 s0, s58, 0xfff00080
	s_addc_u32 s1, s59, -1
	s_cmp_eq_u32 s87, 60
	s_cselect_b32 s63, s12, s1
	s_cselect_b32 s62, s29, s0
	s_cselect_b32 s61, s57, s86
	s_cselect_b32 s60, s64, s65
	v_lshl_add_u64 v[152:153], s[58:59], 0, v[148:149]
	s_add_i32 m0, s68, 0xc000
	ds_read_b128 v[178:181], v159
	ds_read_b128 v[182:185], v159 offset:1024
	ds_read_b128 v[186:189], v159 offset:2048
	ds_read_b128 v[190:193], v159 offset:3072
	ds_read_b128 v[194:197], v159 offset:4096
	ds_read_b128 v[206:209], v159 offset:5120
	ds_read_b128 v[210:213], v159 offset:6144
	ds_read_b128 v[214:217], v159 offset:7168
	global_load_lds_dwordx4 v[152:153], off
	v_lshl_add_u64 v[152:153], s[58:59], 0, v[150:151]
	s_add_i32 m0, s68, 0xe000
	s_nop 0
	global_load_lds_dwordx4 v[152:153], off
	s_waitcnt vmcnt(8)
	s_waitcnt lgkmcnt(0)
	s_barrier
	s_setprio 1
	v_mfma_f32_16x16x32_bf16 v[124:127], v[128:131], v[178:181], v[124:127]
	v_mfma_f32_16x16x32_bf16 v[120:123], v[136:139], v[178:181], v[120:123]
	v_mfma_f32_16x16x32_bf16 v[112:115], v[128:131], v[186:189], v[112:115]
	v_mfma_f32_16x16x32_bf16 v[108:111], v[136:139], v[186:189], v[108:111]
	v_mfma_f32_16x16x32_bf16 v[96:99], v[128:131], v[194:197], v[96:99]
	v_mfma_f32_16x16x32_bf16 v[92:95], v[136:139], v[194:197], v[92:95]
	v_mfma_f32_16x16x32_bf16 v[80:83], v[128:131], v[210:213], v[80:83]
	v_mfma_f32_16x16x32_bf16 v[76:79], v[136:139], v[210:213], v[76:79]
	v_mfma_f32_16x16x32_bf16 v[124:127], v[132:135], v[182:185], v[124:127]
	v_mfma_f32_16x16x32_bf16 v[120:123], v[140:143], v[182:185], v[120:123]
	v_mfma_f32_16x16x32_bf16 v[112:115], v[132:135], v[190:193], v[112:115]
	v_mfma_f32_16x16x32_bf16 v[108:111], v[140:143], v[190:193], v[108:111]
	v_mfma_f32_16x16x32_bf16 v[96:99], v[132:135], v[206:209], v[96:99]
	v_mfma_f32_16x16x32_bf16 v[92:95], v[140:143], v[206:209], v[92:95]
	v_mfma_f32_16x16x32_bf16 v[80:83], v[132:135], v[214:217], v[80:83]
	v_mfma_f32_16x16x32_bf16 v[76:79], v[140:143], v[214:217], v[76:79]
	v_mfma_f32_16x16x32_bf16 v[116:119], v[160:163], v[178:181], v[116:119]
	v_mfma_f32_16x16x32_bf16 v[104:107], v[168:171], v[178:181], v[104:107]
	v_mfma_f32_16x16x32_bf16 v[100:103], v[160:163], v[186:189], v[100:103]
	v_mfma_f32_16x16x32_bf16 v[88:91], v[168:171], v[186:189], v[88:91]
	v_mfma_f32_16x16x32_bf16 v[84:87], v[160:163], v[194:197], v[84:87]
	v_mfma_f32_16x16x32_bf16 v[72:75], v[168:171], v[194:197], v[72:75]
	v_mfma_f32_16x16x32_bf16 v[68:71], v[160:163], v[210:213], v[68:71]
	v_mfma_f32_16x16x32_bf16 v[64:67], v[168:171], v[210:213], v[64:67]
	v_mfma_f32_16x16x32_bf16 v[116:119], v[164:167], v[182:185], v[116:119]
	v_mfma_f32_16x16x32_bf16 v[104:107], v[172:175], v[182:185], v[104:107]
	v_mfma_f32_16x16x32_bf16 v[100:103], v[164:167], v[190:193], v[100:103]
	v_mfma_f32_16x16x32_bf16 v[88:91], v[172:175], v[190:193], v[88:91]
	v_mfma_f32_16x16x32_bf16 v[84:87], v[164:167], v[206:209], v[84:87]
	v_mfma_f32_16x16x32_bf16 v[72:75], v[172:175], v[206:209], v[72:75]
	v_mfma_f32_16x16x32_bf16 v[68:71], v[164:167], v[214:217], v[68:71]
	v_mfma_f32_16x16x32_bf16 v[64:67], v[172:175], v[214:217], v[64:67]
	s_setprio 0
	s_barrier
	s_add_i32 s0, s81, s67
	v_lshl_add_u64 v[152:153], s[60:61], 0, v[146:147]
	s_mov_b32 m0, s0
	ds_read_b128 v[178:181], v159 offset:16384
	ds_read_b128 v[182:185], v159 offset:17408
	ds_read_b128 v[186:189], v159 offset:18432
	ds_read_b128 v[190:193], v159 offset:19456
	ds_read_b128 v[194:197], v159 offset:20480
	ds_read_b128 v[206:209], v159 offset:21504
	ds_read_b128 v[210:213], v159 offset:22528
	ds_read_b128 v[214:217], v159 offset:23552
	global_load_lds_dwordx4 v[152:153], off
	s_add_i32 m0, s0, 0x2000
	s_add_u32 s0, s60, 0x100000
	v_lshl_add_u64 v[198:199], s[60:61], 0, v[144:145]
	s_addc_u32 s1, s61, 0
	s_add_i32 s2, s82, s67
	global_load_lds_dwordx4 v[198:199], off
	v_lshl_add_u64 v[202:203], s[0:1], 0, v[146:147]
	s_mov_b32 m0, s2
	v_lshl_add_u64 v[218:219], s[62:63], 0, v[144:145]
	global_load_lds_dwordx4 v[202:203], off
	v_lshl_add_u64 v[202:203], s[0:1], 0, v[144:145]
	s_add_i32 m0, s2, 0x2000
	s_nop 0
	global_load_lds_dwordx4 v[202:203], off
	v_lshl_add_u64 v[202:203], s[62:63], 0, v[146:147]
	s_mov_b32 m0, s68
	s_nop 0
	global_load_lds_dwordx4 v[202:203], off
	s_mov_b32 m0, s69
	s_nop 0
	global_load_lds_dwordx4 v[218:219], off
	s_waitcnt vmcnt(8)
	s_waitcnt lgkmcnt(0)
	s_barrier
	s_setprio 1
	v_mfma_f32_16x16x32_bf16 v[60:63], v[128:131], v[178:181], v[60:63]
	v_mfma_f32_16x16x32_bf16 v[56:59], v[136:139], v[178:181], v[56:59]
	v_mfma_f32_16x16x32_bf16 v[48:51], v[128:131], v[186:189], v[48:51]
	v_mfma_f32_16x16x32_bf16 v[44:47], v[136:139], v[186:189], v[44:47]
	v_mfma_f32_16x16x32_bf16 v[32:35], v[128:131], v[194:197], v[32:35]
	v_mfma_f32_16x16x32_bf16 v[28:31], v[136:139], v[194:197], v[28:31]
	v_mfma_f32_16x16x32_bf16 v[16:19], v[128:131], v[210:213], v[16:19]
	v_mfma_f32_16x16x32_bf16 v[12:15], v[136:139], v[210:213], v[12:15]
	v_mfma_f32_16x16x32_bf16 v[60:63], v[132:135], v[182:185], v[60:63]
	v_mfma_f32_16x16x32_bf16 v[56:59], v[140:143], v[182:185], v[56:59]
	v_mfma_f32_16x16x32_bf16 v[48:51], v[132:135], v[190:193], v[48:51]
	v_mfma_f32_16x16x32_bf16 v[44:47], v[140:143], v[190:193], v[44:47]
	v_mfma_f32_16x16x32_bf16 v[32:35], v[132:135], v[206:209], v[32:35]
	v_mfma_f32_16x16x32_bf16 v[28:31], v[140:143], v[206:209], v[28:31]
	v_mfma_f32_16x16x32_bf16 v[16:19], v[132:135], v[214:217], v[16:19]
	v_mfma_f32_16x16x32_bf16 v[12:15], v[140:143], v[214:217], v[12:15]
	v_mfma_f32_16x16x32_bf16 v[52:55], v[160:163], v[178:181], v[52:55]
	v_mfma_f32_16x16x32_bf16 v[40:43], v[168:171], v[178:181], v[40:43]
	v_mfma_f32_16x16x32_bf16 v[36:39], v[160:163], v[186:189], v[36:39]
	v_mfma_f32_16x16x32_bf16 v[24:27], v[168:171], v[186:189], v[24:27]
	v_mfma_f32_16x16x32_bf16 v[20:23], v[160:163], v[194:197], v[20:23]
	v_mfma_f32_16x16x32_bf16 v[8:11], v[168:171], v[194:197], v[8:11]
	v_mfma_f32_16x16x32_bf16 v[4:7], v[160:163], v[210:213], v[4:7]
	v_mfma_f32_16x16x32_bf16 v[0:3], v[168:171], v[210:213], v[0:3]
	v_mfma_f32_16x16x32_bf16 v[52:55], v[164:167], v[182:185], v[52:55]
	v_mfma_f32_16x16x32_bf16 v[40:43], v[172:175], v[182:185], v[40:43]
	v_mfma_f32_16x16x32_bf16 v[36:39], v[164:167], v[190:193], v[36:39]
	v_mfma_f32_16x16x32_bf16 v[24:27], v[172:175], v[190:193], v[24:27]
	v_mfma_f32_16x16x32_bf16 v[20:23], v[164:167], v[206:209], v[20:23]
	v_mfma_f32_16x16x32_bf16 v[8:11], v[172:175], v[206:209], v[8:11]
	v_mfma_f32_16x16x32_bf16 v[4:7], v[164:167], v[214:217], v[4:7]
	v_mfma_f32_16x16x32_bf16 v[0:3], v[172:175], v[214:217], v[0:3]
	s_setprio 0
	s_barrier
	s_add_i32 s2, 0, 0x18000
	s_add_i32 s3, 0, 0x1c000
	v_add_u32_e32 v140, s2, v156
	v_add_u32_e32 v172, s3, v156
	ds_read_b128 v[128:131], v140
	ds_read_b128 v[132:135], v140 offset:1024
	ds_read_b128 v[136:139], v140 offset:2048
	ds_read_b128 v[140:143], v140 offset:3072
	ds_read_b128 v[160:163], v172
	ds_read_b128 v[164:167], v172 offset:1024
	ds_read_b128 v[168:171], v172 offset:2048
	ds_read_b128 v[172:175], v172 offset:3072
	s_add_u32 s0, s62, 0x100000
	s_addc_u32 s1, s63, 0
	s_mov_b32 m0, s70
	v_lshl_add_u64 v[220:221], s[0:1], 0, v[146:147]
	ds_read_b128 v[178:181], v159 offset:32768
	ds_read_b128 v[182:185], v159 offset:33792
	ds_read_b128 v[186:189], v159 offset:34816
	ds_read_b128 v[190:193], v159 offset:35840
	ds_read_b128 v[194:197], v159 offset:36864
	ds_read_b128 v[206:209], v159 offset:37888
	ds_read_b128 v[210:213], v159 offset:38912
	ds_read_b128 v[214:217], v159 offset:39936
	global_load_lds_dwordx4 v[220:221], off
	v_lshl_add_u64 v[220:221], s[0:1], 0, v[144:145]
	s_mov_b32 m0, s71
	s_nop 0
	global_load_lds_dwordx4 v[220:221], off
	s_waitcnt vmcnt(8)
	s_waitcnt lgkmcnt(0)
	s_barrier
	s_setprio 1
	v_mfma_f32_16x16x32_bf16 v[124:127], v[128:131], v[178:181], v[124:127]
	v_mfma_f32_16x16x32_bf16 v[120:123], v[136:139], v[178:181], v[120:123]
	v_mfma_f32_16x16x32_bf16 v[112:115], v[128:131], v[186:189], v[112:115]
	v_mfma_f32_16x16x32_bf16 v[108:111], v[136:139], v[186:189], v[108:111]
	v_mfma_f32_16x16x32_bf16 v[96:99], v[128:131], v[194:197], v[96:99]
	v_mfma_f32_16x16x32_bf16 v[92:95], v[136:139], v[194:197], v[92:95]
	v_mfma_f32_16x16x32_bf16 v[80:83], v[128:131], v[210:213], v[80:83]
	v_mfma_f32_16x16x32_bf16 v[76:79], v[136:139], v[210:213], v[76:79]
	v_mfma_f32_16x16x32_bf16 v[124:127], v[132:135], v[182:185], v[124:127]
	v_mfma_f32_16x16x32_bf16 v[120:123], v[140:143], v[182:185], v[120:123]
	v_mfma_f32_16x16x32_bf16 v[112:115], v[132:135], v[190:193], v[112:115]
	v_mfma_f32_16x16x32_bf16 v[108:111], v[140:143], v[190:193], v[108:111]
	v_mfma_f32_16x16x32_bf16 v[96:99], v[132:135], v[206:209], v[96:99]
	v_mfma_f32_16x16x32_bf16 v[92:95], v[140:143], v[206:209], v[92:95]
	v_mfma_f32_16x16x32_bf16 v[80:83], v[132:135], v[214:217], v[80:83]
	v_mfma_f32_16x16x32_bf16 v[76:79], v[140:143], v[214:217], v[76:79]
	v_mfma_f32_16x16x32_bf16 v[116:119], v[160:163], v[178:181], v[116:119]
	v_mfma_f32_16x16x32_bf16 v[104:107], v[168:171], v[178:181], v[104:107]
	v_mfma_f32_16x16x32_bf16 v[100:103], v[160:163], v[186:189], v[100:103]
	v_mfma_f32_16x16x32_bf16 v[88:91], v[168:171], v[186:189], v[88:91]
	v_mfma_f32_16x16x32_bf16 v[84:87], v[160:163], v[194:197], v[84:87]
	v_mfma_f32_16x16x32_bf16 v[72:75], v[168:171], v[194:197], v[72:75]
	v_mfma_f32_16x16x32_bf16 v[68:71], v[160:163], v[210:213], v[68:71]
	v_mfma_f32_16x16x32_bf16 v[64:67], v[168:171], v[210:213], v[64:67]
	v_mfma_f32_16x16x32_bf16 v[116:119], v[164:167], v[182:185], v[116:119]
	v_mfma_f32_16x16x32_bf16 v[104:107], v[172:175], v[182:185], v[104:107]
	v_mfma_f32_16x16x32_bf16 v[100:103], v[164:167], v[190:193], v[100:103]
	v_mfma_f32_16x16x32_bf16 v[88:91], v[172:175], v[190:193], v[88:91]
	v_mfma_f32_16x16x32_bf16 v[84:87], v[164:167], v[206:209], v[84:87]
	v_mfma_f32_16x16x32_bf16 v[72:75], v[172:175], v[206:209], v[72:75]
	v_mfma_f32_16x16x32_bf16 v[68:71], v[164:167], v[214:217], v[68:71]
	v_mfma_f32_16x16x32_bf16 v[64:67], v[172:175], v[214:217], v[64:67]
	s_setprio 0
	s_barrier
	s_add_i32 s0, s2, s67
	v_lshl_add_u64 v[152:153], v[152:153], 0, s[10:11]
	s_mov_b32 m0, s0
	ds_read_b128 v[178:181], v159 offset:49152
	ds_read_b128 v[182:185], v159 offset:50176
	ds_read_b128 v[186:189], v159 offset:51200
	ds_read_b128 v[190:193], v159 offset:52224
	ds_read_b128 v[194:197], v159 offset:53248
	ds_read_b128 v[206:209], v159 offset:54272
	ds_read_b128 v[210:213], v159 offset:55296
	ds_read_b128 v[214:217], v159 offset:56320
	global_load_lds_dwordx4 v[152:153], off
	s_add_i32 m0, s0, 0x2000
	s_add_u32 s0, s60, 0x100080
	v_lshl_add_u64 v[152:153], v[198:199], 0, s[10:11]
	s_addc_u32 s1, s61, 0
	s_add_i32 s2, s3, s67
	global_load_lds_dwordx4 v[152:153], off
	v_lshl_add_u64 v[152:153], s[0:1], 0, v[146:147]
	s_mov_b32 m0, s2
	s_nop 0
	global_load_lds_dwordx4 v[152:153], off
	v_lshl_add_u64 v[152:153], s[0:1], 0, v[144:145]
	s_add_i32 m0, s2, 0x2000
	s_nop 0
	global_load_lds_dwordx4 v[152:153], off
	v_lshl_add_u64 v[152:153], v[202:203], 0, s[10:11]
	s_mov_b32 m0, s79
	s_nop 0
	global_load_lds_dwordx4 v[152:153], off
	v_lshl_add_u64 v[152:153], v[218:219], 0, s[10:11]
	s_mov_b32 m0, s80
	s_nop 0
	global_load_lds_dwordx4 v[152:153], off
	s_waitcnt vmcnt(8)
	s_waitcnt lgkmcnt(0)
	s_barrier
	s_setprio 1
	v_mfma_f32_16x16x32_bf16 v[60:63], v[128:131], v[178:181], v[60:63]
	v_mfma_f32_16x16x32_bf16 v[56:59], v[136:139], v[178:181], v[56:59]
	v_mfma_f32_16x16x32_bf16 v[48:51], v[128:131], v[186:189], v[48:51]
	v_mfma_f32_16x16x32_bf16 v[44:47], v[136:139], v[186:189], v[44:47]
	v_mfma_f32_16x16x32_bf16 v[32:35], v[128:131], v[194:197], v[32:35]
	v_mfma_f32_16x16x32_bf16 v[28:31], v[136:139], v[194:197], v[28:31]
	v_mfma_f32_16x16x32_bf16 v[16:19], v[128:131], v[210:213], v[16:19]
	v_mfma_f32_16x16x32_bf16 v[12:15], v[136:139], v[210:213], v[12:15]
	v_mfma_f32_16x16x32_bf16 v[60:63], v[132:135], v[182:185], v[60:63]
	v_mfma_f32_16x16x32_bf16 v[56:59], v[140:143], v[182:185], v[56:59]
	v_mfma_f32_16x16x32_bf16 v[48:51], v[132:135], v[190:193], v[48:51]
	v_mfma_f32_16x16x32_bf16 v[44:47], v[140:143], v[190:193], v[44:47]
	v_mfma_f32_16x16x32_bf16 v[32:35], v[132:135], v[206:209], v[32:35]
	v_mfma_f32_16x16x32_bf16 v[28:31], v[140:143], v[206:209], v[28:31]
	v_mfma_f32_16x16x32_bf16 v[16:19], v[132:135], v[214:217], v[16:19]
	v_mfma_f32_16x16x32_bf16 v[12:15], v[140:143], v[214:217], v[12:15]
	v_mfma_f32_16x16x32_bf16 v[52:55], v[160:163], v[178:181], v[52:55]
	v_mfma_f32_16x16x32_bf16 v[40:43], v[168:171], v[178:181], v[40:43]
	v_mfma_f32_16x16x32_bf16 v[36:39], v[160:163], v[186:189], v[36:39]
	v_mfma_f32_16x16x32_bf16 v[24:27], v[168:171], v[186:189], v[24:27]
	v_mfma_f32_16x16x32_bf16 v[20:23], v[160:163], v[194:197], v[20:23]
	v_mfma_f32_16x16x32_bf16 v[8:11], v[168:171], v[194:197], v[8:11]
	v_mfma_f32_16x16x32_bf16 v[4:7], v[160:163], v[210:213], v[4:7]
	v_mfma_f32_16x16x32_bf16 v[0:3], v[168:171], v[210:213], v[0:3]
	v_mfma_f32_16x16x32_bf16 v[52:55], v[164:167], v[182:185], v[52:55]
	v_mfma_f32_16x16x32_bf16 v[40:43], v[172:175], v[182:185], v[40:43]
	v_mfma_f32_16x16x32_bf16 v[36:39], v[164:167], v[190:193], v[36:39]
	v_mfma_f32_16x16x32_bf16 v[24:27], v[172:175], v[190:193], v[24:27]
	v_mfma_f32_16x16x32_bf16 v[20:23], v[164:167], v[206:209], v[20:23]
	v_mfma_f32_16x16x32_bf16 v[8:11], v[172:175], v[206:209], v[8:11]
	v_mfma_f32_16x16x32_bf16 v[4:7], v[164:167], v[214:217], v[4:7]
	v_mfma_f32_16x16x32_bf16 v[0:3], v[172:175], v[214:217], v[0:3]
	s_setprio 0
	s_barrier
	s_add_i32 s87, s87, 2
	s_add_u32 s58, s58, 0x100
	s_addc_u32 s59, s59, 0
	s_add_u32 s65, s65, 0x100
	s_addc_u32 s86, s86, 0
	s_cmp_gt_u32 s87, 61
	s_cbranch_scc0 .LBB0_1037
	s_and_b64 vcc, exec, s[14:15]
	s_cbranch_vccz .LBB0_1040
	s_barrier

.LBB0_1107:
	ds_read_b128 v[128:131], v203
	ds_read_b128 v[132:135], v203 offset:1024
	ds_read_b128 v[136:139], v203 offset:2048
	ds_read_b128 v[140:143], v203 offset:3072
	ds_read_b128 v[144:147], v204
	ds_read_b128 v[148:151], v204 offset:1024
	ds_read_b128 v[152:155], v204 offset:2048
	ds_read_b128 v[156:159], v204 offset:3072
	s_add_u32 s0, s4, 0xfff80080
	s_addc_u32 s1, s5, -1
	s_cmp_eq_u32 s96, 28
	s_cselect_b32 s9, s13, s1
	s_cselect_b32 s8, s15, s0
	s_cselect_b32 s7, s37, s11
	s_cselect_b32 s6, s63, s10
	v_lshl_add_u64 v[198:199], s[4:5], 0, v[186:187]
	s_add_i32 m0, s77, 0xc000
	ds_read_b128 v[160:163], v205
	ds_read_b128 v[164:167], v205 offset:1024
	ds_read_b128 v[168:171], v205 offset:2048
	ds_read_b128 v[172:175], v205 offset:3072
	ds_read_b128 v[190:193], v205 offset:4096
	ds_read_b128 v[194:197], v205 offset:5120
	ds_read_b128 v[206:209], v205 offset:6144
	ds_read_b128 v[210:213], v205 offset:7168
	global_load_lds_dwordx4 v[198:199], off
	v_lshl_add_u64 v[198:199], s[4:5], 0, v[188:189]
	s_add_i32 m0, s77, 0xe000
	s_nop 0
	global_load_lds_dwordx4 v[198:199], off
	s_waitcnt vmcnt(8)
	s_waitcnt lgkmcnt(0)
	s_barrier
	s_setprio 1
	v_mfma_f32_16x16x32_bf16 v[124:127], v[128:131], v[160:163], v[124:127]
	v_mfma_f32_16x16x32_bf16 v[56:59], v[136:139], v[160:163], v[56:59]
	v_mfma_f32_16x16x32_bf16 v[116:119], v[128:131], v[168:171], v[116:119]
	v_mfma_f32_16x16x32_bf16 v[52:55], v[136:139], v[168:171], v[52:55]
	v_mfma_f32_16x16x32_bf16 v[108:111], v[128:131], v[190:193], v[108:111]
	v_mfma_f32_16x16x32_bf16 v[44:47], v[136:139], v[190:193], v[44:47]
	v_mfma_f32_16x16x32_bf16 v[104:107], v[128:131], v[206:209], v[104:107]
	v_mfma_f32_16x16x32_bf16 v[32:35], v[136:139], v[206:209], v[32:35]
	v_mfma_f32_16x16x32_bf16 v[124:127], v[132:135], v[164:167], v[124:127]
	v_mfma_f32_16x16x32_bf16 v[56:59], v[140:143], v[164:167], v[56:59]
	v_mfma_f32_16x16x32_bf16 v[116:119], v[132:135], v[172:175], v[116:119]
	v_mfma_f32_16x16x32_bf16 v[52:55], v[140:143], v[172:175], v[52:55]
	v_mfma_f32_16x16x32_bf16 v[108:111], v[132:135], v[194:197], v[108:111]
	v_mfma_f32_16x16x32_bf16 v[44:47], v[140:143], v[194:197], v[44:47]
	v_mfma_f32_16x16x32_bf16 v[104:107], v[132:135], v[210:213], v[104:107]
	v_mfma_f32_16x16x32_bf16 v[32:35], v[140:143], v[210:213], v[32:35]
	v_mfma_f32_16x16x32_bf16 v[120:123], v[144:147], v[160:163], v[120:123]
	v_mfma_f32_16x16x32_bf16 v[60:63], v[152:155], v[160:163], v[60:63]
	v_mfma_f32_16x16x32_bf16 v[112:115], v[144:147], v[168:171], v[112:115]
	v_mfma_f32_16x16x32_bf16 v[48:51], v[152:155], v[168:171], v[48:51]
	v_mfma_f32_16x16x32_bf16 v[100:103], v[144:147], v[190:193], v[100:103]
	v_mfma_f32_16x16x32_bf16 v[40:43], v[152:155], v[190:193], v[40:43]
	v_mfma_f32_16x16x32_bf16 v[96:99], v[144:147], v[206:209], v[96:99]
	v_mfma_f32_16x16x32_bf16 v[36:39], v[152:155], v[206:209], v[36:39]
	v_mfma_f32_16x16x32_bf16 v[120:123], v[148:151], v[164:167], v[120:123]
	v_mfma_f32_16x16x32_bf16 v[60:63], v[156:159], v[164:167], v[60:63]
	v_mfma_f32_16x16x32_bf16 v[112:115], v[148:151], v[172:175], v[112:115]
	v_mfma_f32_16x16x32_bf16 v[48:51], v[156:159], v[172:175], v[48:51]
	v_mfma_f32_16x16x32_bf16 v[100:103], v[148:151], v[194:197], v[100:103]
	v_mfma_f32_16x16x32_bf16 v[40:43], v[156:159], v[194:197], v[40:43]
	v_mfma_f32_16x16x32_bf16 v[96:99], v[148:151], v[210:213], v[96:99]
	v_mfma_f32_16x16x32_bf16 v[36:39], v[156:159], v[210:213], v[36:39]
	s_setprio 0
	s_barrier
	s_add_i32 s0, s92, s76
	v_lshl_add_u64 v[198:199], s[6:7], 0, v[180:181]
	s_mov_b32 m0, s0
	ds_read_b128 v[160:163], v205 offset:16384
	ds_read_b128 v[164:167], v205 offset:17408
	ds_read_b128 v[168:171], v205 offset:18432
	ds_read_b128 v[172:175], v205 offset:19456
	ds_read_b128 v[190:193], v205 offset:20480
	ds_read_b128 v[194:197], v205 offset:21504
	ds_read_b128 v[206:209], v205 offset:22528
	ds_read_b128 v[210:213], v205 offset:23552
	global_load_lds_dwordx4 v[198:199], off
	s_add_i32 m0, s0, 0x2000
	s_add_u32 s0, s6, 0x80000
	v_lshl_add_u64 v[214:215], s[6:7], 0, v[184:185]
	s_addc_u32 s1, s7, 0
	s_add_i32 s2, s93, s76
	global_load_lds_dwordx4 v[214:215], off
	v_lshl_add_u64 v[216:217], s[0:1], 0, v[180:181]
	s_mov_b32 m0, s2
	v_lshl_add_u64 v[218:219], s[8:9], 0, v[182:183]
	global_load_lds_dwordx4 v[216:217], off
	v_lshl_add_u64 v[216:217], s[0:1], 0, v[184:185]
	s_add_i32 m0, s2, 0x2000
	s_nop 0
	global_load_lds_dwordx4 v[216:217], off
	v_lshl_add_u64 v[216:217], s[8:9], 0, v[178:179]
	s_mov_b32 m0, s77
	s_nop 0
	global_load_lds_dwordx4 v[216:217], off
	s_mov_b32 m0, s78
	s_nop 0
	global_load_lds_dwordx4 v[218:219], off
	s_waitcnt vmcnt(8)
	s_waitcnt lgkmcnt(0)
	s_barrier
	s_setprio 1
	v_mfma_f32_16x16x32_bf16 v[92:95], v[128:131], v[160:163], v[92:95]
	v_mfma_f32_16x16x32_bf16 v[24:27], v[136:139], v[160:163], v[24:27]
	v_mfma_f32_16x16x32_bf16 v[84:87], v[128:131], v[168:171], v[84:87]
	v_mfma_f32_16x16x32_bf16 v[20:23], v[136:139], v[168:171], v[20:23]
	v_mfma_f32_16x16x32_bf16 v[76:79], v[128:131], v[190:193], v[76:79]
	v_mfma_f32_16x16x32_bf16 v[12:15], v[136:139], v[190:193], v[12:15]
	v_mfma_f32_16x16x32_bf16 v[72:75], v[128:131], v[206:209], v[72:75]
	v_mfma_f32_16x16x32_bf16 v[0:3], v[136:139], v[206:209], v[0:3]
	v_mfma_f32_16x16x32_bf16 v[92:95], v[132:135], v[164:167], v[92:95]
	v_mfma_f32_16x16x32_bf16 v[24:27], v[140:143], v[164:167], v[24:27]
	v_mfma_f32_16x16x32_bf16 v[84:87], v[132:135], v[172:175], v[84:87]
	v_mfma_f32_16x16x32_bf16 v[20:23], v[140:143], v[172:175], v[20:23]
	v_mfma_f32_16x16x32_bf16 v[76:79], v[132:135], v[194:197], v[76:79]
	v_mfma_f32_16x16x32_bf16 v[12:15], v[140:143], v[194:197], v[12:15]
	v_mfma_f32_16x16x32_bf16 v[72:75], v[132:135], v[210:213], v[72:75]
	v_mfma_f32_16x16x32_bf16 v[0:3], v[140:143], v[210:213], v[0:3]
	v_mfma_f32_16x16x32_bf16 v[88:91], v[144:147], v[160:163], v[88:91]
	v_mfma_f32_16x16x32_bf16 v[28:31], v[152:155], v[160:163], v[28:31]
	v_mfma_f32_16x16x32_bf16 v[80:83], v[144:147], v[168:171], v[80:83]
	v_mfma_f32_16x16x32_bf16 v[16:19], v[152:155], v[168:171], v[16:19]
	v_mfma_f32_16x16x32_bf16 v[68:71], v[144:147], v[190:193], v[68:71]
	v_mfma_f32_16x16x32_bf16 v[8:11], v[152:155], v[190:193], v[8:11]
	v_mfma_f32_16x16x32_bf16 v[64:67], v[144:147], v[206:209], v[64:67]
	v_mfma_f32_16x16x32_bf16 v[4:7], v[152:155], v[206:209], v[4:7]
	v_mfma_f32_16x16x32_bf16 v[88:91], v[148:151], v[164:167], v[88:91]
	v_mfma_f32_16x16x32_bf16 v[28:31], v[156:159], v[164:167], v[28:31]
	v_mfma_f32_16x16x32_bf16 v[80:83], v[148:151], v[172:175], v[80:83]
	v_mfma_f32_16x16x32_bf16 v[16:19], v[156:159], v[172:175], v[16:19]
	v_mfma_f32_16x16x32_bf16 v[68:71], v[148:151], v[194:197], v[68:71]
	v_mfma_f32_16x16x32_bf16 v[8:11], v[156:159], v[194:197], v[8:11]
	v_mfma_f32_16x16x32_bf16 v[64:67], v[148:151], v[210:213], v[64:67]
	v_mfma_f32_16x16x32_bf16 v[4:7], v[156:159], v[210:213], v[4:7]
	s_setprio 0
	s_barrier
	s_add_i32 s2, 0, 0x18000
	s_add_i32 s38, 0, 0x1c000
	v_add_u32_e32 v140, s2, v202
	v_add_u32_e32 v156, s38, v202
	ds_read_b128 v[128:131], v140
	ds_read_b128 v[132:135], v140 offset:1024
	ds_read_b128 v[136:139], v140 offset:2048
	ds_read_b128 v[140:143], v140 offset:3072
	ds_read_b128 v[144:147], v156
	ds_read_b128 v[148:151], v156 offset:1024
	ds_read_b128 v[152:155], v156 offset:2048
	ds_read_b128 v[156:159], v156 offset:3072
	s_add_u32 s0, s8, 0x80000
	s_addc_u32 s1, s9, 0
	s_mov_b32 m0, s79
	v_lshl_add_u64 v[220:221], s[0:1], 0, v[178:179]
	ds_read_b128 v[160:163], v205 offset:32768
	ds_read_b128 v[164:167], v205 offset:33792
	ds_read_b128 v[168:171], v205 offset:34816
	ds_read_b128 v[172:175], v205 offset:35840
	ds_read_b128 v[190:193], v205 offset:36864
	ds_read_b128 v[194:197], v205 offset:37888
	ds_read_b128 v[206:209], v205 offset:38912
	ds_read_b128 v[210:213], v205 offset:39936
	global_load_lds_dwordx4 v[220:221], off
	v_lshl_add_u64 v[220:221], s[0:1], 0, v[182:183]
	s_mov_b32 m0, s80
	s_nop 0
	global_load_lds_dwordx4 v[220:221], off
	s_waitcnt vmcnt(8)
	s_waitcnt lgkmcnt(0)
	s_barrier
	s_setprio 1
	v_mfma_f32_16x16x32_bf16 v[124:127], v[128:131], v[160:163], v[124:127]
	v_mfma_f32_16x16x32_bf16 v[56:59], v[136:139], v[160:163], v[56:59]
	v_mfma_f32_16x16x32_bf16 v[116:119], v[128:131], v[168:171], v[116:119]
	v_mfma_f32_16x16x32_bf16 v[52:55], v[136:139], v[168:171], v[52:55]
	v_mfma_f32_16x16x32_bf16 v[108:111], v[128:131], v[190:193], v[108:111]
	v_mfma_f32_16x16x32_bf16 v[44:47], v[136:139], v[190:193], v[44:47]
	v_mfma_f32_16x16x32_bf16 v[104:107], v[128:131], v[206:209], v[104:107]
	v_mfma_f32_16x16x32_bf16 v[32:35], v[136:139], v[206:209], v[32:35]
	v_mfma_f32_16x16x32_bf16 v[124:127], v[132:135], v[164:167], v[124:127]
	v_mfma_f32_16x16x32_bf16 v[56:59], v[140:143], v[164:167], v[56:59]
	v_mfma_f32_16x16x32_bf16 v[116:119], v[132:135], v[172:175], v[116:119]
	v_mfma_f32_16x16x32_bf16 v[52:55], v[140:143], v[172:175], v[52:55]
	v_mfma_f32_16x16x32_bf16 v[108:111], v[132:135], v[194:197], v[108:111]
	v_mfma_f32_16x16x32_bf16 v[44:47], v[140:143], v[194:197], v[44:47]
	v_mfma_f32_16x16x32_bf16 v[104:107], v[132:135], v[210:213], v[104:107]
	v_mfma_f32_16x16x32_bf16 v[32:35], v[140:143], v[210:213], v[32:35]
	v_mfma_f32_16x16x32_bf16 v[120:123], v[144:147], v[160:163], v[120:123]
	v_mfma_f32_16x16x32_bf16 v[60:63], v[152:155], v[160:163], v[60:63]
	v_mfma_f32_16x16x32_bf16 v[112:115], v[144:147], v[168:171], v[112:115]
	v_mfma_f32_16x16x32_bf16 v[48:51], v[152:155], v[168:171], v[48:51]
	v_mfma_f32_16x16x32_bf16 v[100:103], v[144:147], v[190:193], v[100:103]
	v_mfma_f32_16x16x32_bf16 v[40:43], v[152:155], v[190:193], v[40:43]
	v_mfma_f32_16x16x32_bf16 v[96:99], v[144:147], v[206:209], v[96:99]
	v_mfma_f32_16x16x32_bf16 v[36:39], v[152:155], v[206:209], v[36:39]
	v_mfma_f32_16x16x32_bf16 v[120:123], v[148:151], v[164:167], v[120:123]
	v_mfma_f32_16x16x32_bf16 v[60:63], v[156:159], v[164:167], v[60:63]
	v_mfma_f32_16x16x32_bf16 v[112:115], v[148:151], v[172:175], v[112:115]
	v_mfma_f32_16x16x32_bf16 v[48:51], v[156:159], v[172:175], v[48:51]
	v_mfma_f32_16x16x32_bf16 v[100:103], v[148:151], v[194:197], v[100:103]
	v_mfma_f32_16x16x32_bf16 v[40:43], v[156:159], v[194:197], v[40:43]
	v_mfma_f32_16x16x32_bf16 v[96:99], v[148:151], v[210:213], v[96:99]
	v_mfma_f32_16x16x32_bf16 v[36:39], v[156:159], v[210:213], v[36:39]
	s_setprio 0
	s_barrier
	s_add_i32 s0, s2, s76
	v_lshl_add_u64 v[198:199], v[198:199], 0, s[24:25]
	s_mov_b32 m0, s0
	ds_read_b128 v[160:163], v205 offset:49152
	ds_read_b128 v[164:167], v205 offset:50176
	ds_read_b128 v[168:171], v205 offset:51200
	ds_read_b128 v[172:175], v205 offset:52224
	ds_read_b128 v[190:193], v205 offset:53248
	ds_read_b128 v[194:197], v205 offset:54272
	ds_read_b128 v[206:209], v205 offset:55296
	ds_read_b128 v[210:213], v205 offset:56320
	global_load_lds_dwordx4 v[198:199], off
	s_add_i32 m0, s0, 0x2000
	s_add_u32 s0, s6, 0x80080
	v_lshl_add_u64 v[198:199], v[214:215], 0, s[24:25]
	s_addc_u32 s1, s7, 0
	s_add_i32 s2, s38, s76
	global_load_lds_dwordx4 v[198:199], off
	v_lshl_add_u64 v[198:199], s[0:1], 0, v[180:181]
	s_mov_b32 m0, s2
	s_nop 0
	global_load_lds_dwordx4 v[198:199], off
	v_lshl_add_u64 v[198:199], s[0:1], 0, v[184:185]
	s_add_i32 m0, s2, 0x2000
	s_nop 0
	global_load_lds_dwordx4 v[198:199], off
	v_lshl_add_u64 v[198:199], v[216:217], 0, s[24:25]
	s_mov_b32 m0, s86
	s_nop 0
	global_load_lds_dwordx4 v[198:199], off
	v_lshl_add_u64 v[198:199], v[218:219], 0, s[24:25]
	s_mov_b32 m0, s87
	s_nop 0
	global_load_lds_dwordx4 v[198:199], off
	s_waitcnt vmcnt(8)
	s_waitcnt lgkmcnt(0)
	s_barrier
	s_setprio 1
	v_mfma_f32_16x16x32_bf16 v[92:95], v[128:131], v[160:163], v[92:95]
	v_mfma_f32_16x16x32_bf16 v[24:27], v[136:139], v[160:163], v[24:27]
	v_mfma_f32_16x16x32_bf16 v[84:87], v[128:131], v[168:171], v[84:87]
	v_mfma_f32_16x16x32_bf16 v[20:23], v[136:139], v[168:171], v[20:23]
	v_mfma_f32_16x16x32_bf16 v[76:79], v[128:131], v[190:193], v[76:79]
	v_mfma_f32_16x16x32_bf16 v[12:15], v[136:139], v[190:193], v[12:15]
	v_mfma_f32_16x16x32_bf16 v[72:75], v[128:131], v[206:209], v[72:75]
	v_mfma_f32_16x16x32_bf16 v[0:3], v[136:139], v[206:209], v[0:3]
	v_mfma_f32_16x16x32_bf16 v[92:95], v[132:135], v[164:167], v[92:95]
	v_mfma_f32_16x16x32_bf16 v[24:27], v[140:143], v[164:167], v[24:27]
	v_mfma_f32_16x16x32_bf16 v[84:87], v[132:135], v[172:175], v[84:87]
	v_mfma_f32_16x16x32_bf16 v[20:23], v[140:143], v[172:175], v[20:23]
	v_mfma_f32_16x16x32_bf16 v[76:79], v[132:135], v[194:197], v[76:79]
	v_mfma_f32_16x16x32_bf16 v[12:15], v[140:143], v[194:197], v[12:15]
	v_mfma_f32_16x16x32_bf16 v[72:75], v[132:135], v[210:213], v[72:75]
	v_mfma_f32_16x16x32_bf16 v[0:3], v[140:143], v[210:213], v[0:3]
	v_mfma_f32_16x16x32_bf16 v[88:91], v[144:147], v[160:163], v[88:91]
	v_mfma_f32_16x16x32_bf16 v[28:31], v[152:155], v[160:163], v[28:31]
	v_mfma_f32_16x16x32_bf16 v[80:83], v[144:147], v[168:171], v[80:83]
	v_mfma_f32_16x16x32_bf16 v[16:19], v[152:155], v[168:171], v[16:19]
	v_mfma_f32_16x16x32_bf16 v[68:71], v[144:147], v[190:193], v[68:71]
	v_mfma_f32_16x16x32_bf16 v[8:11], v[152:155], v[190:193], v[8:11]
	v_mfma_f32_16x16x32_bf16 v[64:67], v[144:147], v[206:209], v[64:67]
	v_mfma_f32_16x16x32_bf16 v[4:7], v[152:155], v[206:209], v[4:7]
	v_mfma_f32_16x16x32_bf16 v[88:91], v[148:151], v[164:167], v[88:91]
	v_mfma_f32_16x16x32_bf16 v[28:31], v[156:159], v[164:167], v[28:31]
	v_mfma_f32_16x16x32_bf16 v[80:83], v[148:151], v[172:175], v[80:83]
	v_mfma_f32_16x16x32_bf16 v[16:19], v[156:159], v[172:175], v[16:19]
	v_mfma_f32_16x16x32_bf16 v[68:71], v[148:151], v[194:197], v[68:71]
	v_mfma_f32_16x16x32_bf16 v[8:11], v[156:159], v[194:197], v[8:11]
	v_mfma_f32_16x16x32_bf16 v[64:67], v[148:151], v[210:213], v[64:67]
	v_mfma_f32_16x16x32_bf16 v[4:7], v[156:159], v[210:213], v[4:7]
	s_setprio 0
	s_barrier
	s_add_i32 s96, s96, 2
	s_add_u32 s4, s4, 0x100
	s_addc_u32 s5, s5, 0
	s_add_u32 s10, s10, 0x100
	s_addc_u32 s11, s11, 0
	s_cmp_gt_u32 s96, 29
	s_cbranch_scc0 .LBB0_1107
	s_and_b64 vcc, exec, s[26:27]
	s_cbranch_vccz .LBB0_1110
	s_barrier

.LBB0_1249:
	ds_read_b128 v[128:131], v157
	ds_read_b128 v[132:135], v157 offset:1024
	ds_read_b128 v[136:139], v157 offset:2048
	ds_read_b128 v[140:143], v157 offset:3072
	ds_read_b128 v[160:163], v158
	ds_read_b128 v[164:167], v158 offset:1024
	ds_read_b128 v[168:171], v158 offset:2048
	ds_read_b128 v[172:175], v158 offset:3072
	s_add_u32 s38, s36, 0x100
	s_addc_u32 s39, s37, 0
	s_cmpk_eq_i32 s74, 0x54
	s_cselect_b32 s45, s6, s39
	s_cselect_b32 s44, s35, s38
	s_cselect_b32 s43, s70, s73
	s_cselect_b32 s42, s71, s72
	v_lshl_add_u64 v[152:153], s[36:37], 0, v[148:149]
	s_add_i32 m0, s52, 0xc000
	ds_read_b128 v[176:179], v159
	ds_read_b128 v[180:183], v159 offset:1024
	ds_read_b128 v[184:187], v159 offset:2048
	ds_read_b128 v[188:191], v159 offset:3072
	ds_read_b128 v[192:195], v159 offset:4096
	ds_read_b128 v[196:199], v159 offset:5120
	ds_read_b128 v[200:203], v159 offset:6144
	ds_read_b128 v[204:207], v159 offset:7168
	global_load_lds_dwordx4 v[152:153], off
	v_lshl_add_u64 v[152:153], s[36:37], 0, v[150:151]
	s_add_i32 m0, s52, 0xe000
	s_nop 0
	global_load_lds_dwordx4 v[152:153], off
	s_waitcnt vmcnt(8)
	s_waitcnt lgkmcnt(0)
	s_barrier
	s_setprio 1
	v_mfma_f32_16x16x32_bf16 v[124:127], v[128:131], v[176:179], v[124:127]
	v_mfma_f32_16x16x32_bf16 v[120:123], v[136:139], v[176:179], v[120:123]
	v_mfma_f32_16x16x32_bf16 v[112:115], v[128:131], v[184:187], v[112:115]
	v_mfma_f32_16x16x32_bf16 v[108:111], v[136:139], v[184:187], v[108:111]
	v_mfma_f32_16x16x32_bf16 v[96:99], v[128:131], v[192:195], v[96:99]
	v_mfma_f32_16x16x32_bf16 v[92:95], v[136:139], v[192:195], v[92:95]
	v_mfma_f32_16x16x32_bf16 v[80:83], v[128:131], v[200:203], v[80:83]
	v_mfma_f32_16x16x32_bf16 v[76:79], v[136:139], v[200:203], v[76:79]
	v_mfma_f32_16x16x32_bf16 v[124:127], v[132:135], v[180:183], v[124:127]
	v_mfma_f32_16x16x32_bf16 v[120:123], v[140:143], v[180:183], v[120:123]
	v_mfma_f32_16x16x32_bf16 v[112:115], v[132:135], v[188:191], v[112:115]
	v_mfma_f32_16x16x32_bf16 v[108:111], v[140:143], v[188:191], v[108:111]
	v_mfma_f32_16x16x32_bf16 v[96:99], v[132:135], v[196:199], v[96:99]
	v_mfma_f32_16x16x32_bf16 v[92:95], v[140:143], v[196:199], v[92:95]
	v_mfma_f32_16x16x32_bf16 v[80:83], v[132:135], v[204:207], v[80:83]
	v_mfma_f32_16x16x32_bf16 v[76:79], v[140:143], v[204:207], v[76:79]
	v_mfma_f32_16x16x32_bf16 v[116:119], v[160:163], v[176:179], v[116:119]
	v_mfma_f32_16x16x32_bf16 v[104:107], v[168:171], v[176:179], v[104:107]
	v_mfma_f32_16x16x32_bf16 v[100:103], v[160:163], v[184:187], v[100:103]
	v_mfma_f32_16x16x32_bf16 v[88:91], v[168:171], v[184:187], v[88:91]
	v_mfma_f32_16x16x32_bf16 v[84:87], v[160:163], v[192:195], v[84:87]
	v_mfma_f32_16x16x32_bf16 v[72:75], v[168:171], v[192:195], v[72:75]
	v_mfma_f32_16x16x32_bf16 v[68:71], v[160:163], v[200:203], v[68:71]
	v_mfma_f32_16x16x32_bf16 v[64:67], v[168:171], v[200:203], v[64:67]
	v_mfma_f32_16x16x32_bf16 v[116:119], v[164:167], v[180:183], v[116:119]
	v_mfma_f32_16x16x32_bf16 v[104:107], v[172:175], v[180:183], v[104:107]
	v_mfma_f32_16x16x32_bf16 v[100:103], v[164:167], v[188:191], v[100:103]
	v_mfma_f32_16x16x32_bf16 v[88:91], v[172:175], v[188:191], v[88:91]
	v_mfma_f32_16x16x32_bf16 v[84:87], v[164:167], v[196:199], v[84:87]
	v_mfma_f32_16x16x32_bf16 v[72:75], v[172:175], v[196:199], v[72:75]
	v_mfma_f32_16x16x32_bf16 v[68:71], v[164:167], v[204:207], v[68:71]
	v_mfma_f32_16x16x32_bf16 v[64:67], v[172:175], v[204:207], v[64:67]
	s_setprio 0
	s_barrier
	s_add_i32 s36, s64, s51
	v_lshl_add_u64 v[152:153], s[42:43], 0, v[146:147]
	s_mov_b32 m0, s36
	ds_read_b128 v[176:179], v159 offset:16384
	ds_read_b128 v[180:183], v159 offset:17408
	ds_read_b128 v[184:187], v159 offset:18432
	ds_read_b128 v[188:191], v159 offset:19456
	ds_read_b128 v[192:195], v159 offset:20480
	ds_read_b128 v[196:199], v159 offset:21504
	ds_read_b128 v[200:203], v159 offset:22528
	ds_read_b128 v[204:207], v159 offset:23552
	global_load_lds_dwordx4 v[152:153], off
	s_add_i32 m0, s36, 0x2000
	s_add_u32 s36, s42, 0x160000
	v_lshl_add_u64 v[208:209], s[42:43], 0, v[144:145]
	s_addc_u32 s37, s43, 0
	s_add_i32 s75, s65, s51
	global_load_lds_dwordx4 v[208:209], off
	v_lshl_add_u64 v[210:211], s[36:37], 0, v[146:147]
	s_mov_b32 m0, s75
	v_lshl_add_u64 v[212:213], s[44:45], 0, v[144:145]
	global_load_lds_dwordx4 v[210:211], off
	v_lshl_add_u64 v[210:211], s[36:37], 0, v[144:145]
	s_add_i32 m0, s75, 0x2000
	s_nop 0
	global_load_lds_dwordx4 v[210:211], off
	v_lshl_add_u64 v[210:211], s[44:45], 0, v[146:147]
	s_mov_b32 m0, s52
	s_nop 0
	global_load_lds_dwordx4 v[210:211], off
	s_mov_b32 m0, s53
	s_nop 0
	global_load_lds_dwordx4 v[212:213], off
	s_waitcnt vmcnt(8)
	s_waitcnt lgkmcnt(0)
	s_barrier
	s_setprio 1
	v_mfma_f32_16x16x32_bf16 v[60:63], v[128:131], v[176:179], v[60:63]
	v_mfma_f32_16x16x32_bf16 v[56:59], v[136:139], v[176:179], v[56:59]
	v_mfma_f32_16x16x32_bf16 v[48:51], v[128:131], v[184:187], v[48:51]
	v_mfma_f32_16x16x32_bf16 v[44:47], v[136:139], v[184:187], v[44:47]
	v_mfma_f32_16x16x32_bf16 v[32:35], v[128:131], v[192:195], v[32:35]
	v_mfma_f32_16x16x32_bf16 v[28:31], v[136:139], v[192:195], v[28:31]
	v_mfma_f32_16x16x32_bf16 v[16:19], v[128:131], v[200:203], v[16:19]
	v_mfma_f32_16x16x32_bf16 v[12:15], v[136:139], v[200:203], v[12:15]
	v_mfma_f32_16x16x32_bf16 v[60:63], v[132:135], v[180:183], v[60:63]
	v_mfma_f32_16x16x32_bf16 v[56:59], v[140:143], v[180:183], v[56:59]
	v_mfma_f32_16x16x32_bf16 v[48:51], v[132:135], v[188:191], v[48:51]
	v_mfma_f32_16x16x32_bf16 v[44:47], v[140:143], v[188:191], v[44:47]
	v_mfma_f32_16x16x32_bf16 v[32:35], v[132:135], v[196:199], v[32:35]
	v_mfma_f32_16x16x32_bf16 v[28:31], v[140:143], v[196:199], v[28:31]
	v_mfma_f32_16x16x32_bf16 v[16:19], v[132:135], v[204:207], v[16:19]
	v_mfma_f32_16x16x32_bf16 v[12:15], v[140:143], v[204:207], v[12:15]
	v_mfma_f32_16x16x32_bf16 v[52:55], v[160:163], v[176:179], v[52:55]
	v_mfma_f32_16x16x32_bf16 v[40:43], v[168:171], v[176:179], v[40:43]
	v_mfma_f32_16x16x32_bf16 v[36:39], v[160:163], v[184:187], v[36:39]
	v_mfma_f32_16x16x32_bf16 v[24:27], v[168:171], v[184:187], v[24:27]
	v_mfma_f32_16x16x32_bf16 v[20:23], v[160:163], v[192:195], v[20:23]
	v_mfma_f32_16x16x32_bf16 v[8:11], v[168:171], v[192:195], v[8:11]
	v_mfma_f32_16x16x32_bf16 v[4:7], v[160:163], v[200:203], v[4:7]
	v_mfma_f32_16x16x32_bf16 v[0:3], v[168:171], v[200:203], v[0:3]
	v_mfma_f32_16x16x32_bf16 v[52:55], v[164:167], v[180:183], v[52:55]
	v_mfma_f32_16x16x32_bf16 v[40:43], v[172:175], v[180:183], v[40:43]
	v_mfma_f32_16x16x32_bf16 v[36:39], v[164:167], v[188:191], v[36:39]
	v_mfma_f32_16x16x32_bf16 v[24:27], v[172:175], v[188:191], v[24:27]
	v_mfma_f32_16x16x32_bf16 v[20:23], v[164:167], v[196:199], v[20:23]
	v_mfma_f32_16x16x32_bf16 v[8:11], v[172:175], v[196:199], v[8:11]
	v_mfma_f32_16x16x32_bf16 v[4:7], v[164:167], v[204:207], v[4:7]
	v_mfma_f32_16x16x32_bf16 v[0:3], v[172:175], v[204:207], v[0:3]
	s_setprio 0
	s_barrier
	s_add_i32 s75, 0, 0x18000
	s_add_i32 s76, 0, 0x1c000
	v_add_u32_e32 v140, s75, v156
	v_add_u32_e32 v172, s76, v156
	ds_read_b128 v[128:131], v140
	ds_read_b128 v[132:135], v140 offset:1024
	ds_read_b128 v[136:139], v140 offset:2048
	ds_read_b128 v[140:143], v140 offset:3072
	ds_read_b128 v[160:163], v172
	ds_read_b128 v[164:167], v172 offset:1024
	ds_read_b128 v[168:171], v172 offset:2048
	ds_read_b128 v[172:175], v172 offset:3072
	s_add_u32 s36, s44, 0x160000
	s_addc_u32 s37, s45, 0
	s_mov_b32 m0, s54
	v_lshl_add_u64 v[214:215], s[36:37], 0, v[146:147]
	ds_read_b128 v[176:179], v159 offset:32768
	ds_read_b128 v[180:183], v159 offset:33792
	ds_read_b128 v[184:187], v159 offset:34816
	ds_read_b128 v[188:191], v159 offset:35840
	ds_read_b128 v[192:195], v159 offset:36864
	ds_read_b128 v[196:199], v159 offset:37888
	ds_read_b128 v[200:203], v159 offset:38912
	ds_read_b128 v[204:207], v159 offset:39936
	global_load_lds_dwordx4 v[214:215], off
	v_lshl_add_u64 v[214:215], s[36:37], 0, v[144:145]
	s_mov_b32 m0, s55
	s_nop 0
	global_load_lds_dwordx4 v[214:215], off
	s_waitcnt vmcnt(8)
	s_waitcnt lgkmcnt(0)
	s_barrier
	s_setprio 1
	v_mfma_f32_16x16x32_bf16 v[124:127], v[128:131], v[176:179], v[124:127]
	v_mfma_f32_16x16x32_bf16 v[120:123], v[136:139], v[176:179], v[120:123]
	v_mfma_f32_16x16x32_bf16 v[112:115], v[128:131], v[184:187], v[112:115]
	v_mfma_f32_16x16x32_bf16 v[108:111], v[136:139], v[184:187], v[108:111]
	v_mfma_f32_16x16x32_bf16 v[96:99], v[128:131], v[192:195], v[96:99]
	v_mfma_f32_16x16x32_bf16 v[92:95], v[136:139], v[192:195], v[92:95]
	v_mfma_f32_16x16x32_bf16 v[80:83], v[128:131], v[200:203], v[80:83]
	v_mfma_f32_16x16x32_bf16 v[76:79], v[136:139], v[200:203], v[76:79]
	v_mfma_f32_16x16x32_bf16 v[124:127], v[132:135], v[180:183], v[124:127]
	v_mfma_f32_16x16x32_bf16 v[120:123], v[140:143], v[180:183], v[120:123]
	v_mfma_f32_16x16x32_bf16 v[112:115], v[132:135], v[188:191], v[112:115]
	v_mfma_f32_16x16x32_bf16 v[108:111], v[140:143], v[188:191], v[108:111]
	v_mfma_f32_16x16x32_bf16 v[96:99], v[132:135], v[196:199], v[96:99]
	v_mfma_f32_16x16x32_bf16 v[92:95], v[140:143], v[196:199], v[92:95]
	v_mfma_f32_16x16x32_bf16 v[80:83], v[132:135], v[204:207], v[80:83]
	v_mfma_f32_16x16x32_bf16 v[76:79], v[140:143], v[204:207], v[76:79]
	v_mfma_f32_16x16x32_bf16 v[116:119], v[160:163], v[176:179], v[116:119]
	v_mfma_f32_16x16x32_bf16 v[104:107], v[168:171], v[176:179], v[104:107]
	v_mfma_f32_16x16x32_bf16 v[100:103], v[160:163], v[184:187], v[100:103]
	v_mfma_f32_16x16x32_bf16 v[88:91], v[168:171], v[184:187], v[88:91]
	v_mfma_f32_16x16x32_bf16 v[84:87], v[160:163], v[192:195], v[84:87]
	v_mfma_f32_16x16x32_bf16 v[72:75], v[168:171], v[192:195], v[72:75]
	v_mfma_f32_16x16x32_bf16 v[68:71], v[160:163], v[200:203], v[68:71]
	v_mfma_f32_16x16x32_bf16 v[64:67], v[168:171], v[200:203], v[64:67]
	v_mfma_f32_16x16x32_bf16 v[116:119], v[164:167], v[180:183], v[116:119]
	v_mfma_f32_16x16x32_bf16 v[104:107], v[172:175], v[180:183], v[104:107]
	v_mfma_f32_16x16x32_bf16 v[100:103], v[164:167], v[188:191], v[100:103]
	v_mfma_f32_16x16x32_bf16 v[88:91], v[172:175], v[188:191], v[88:91]
	v_mfma_f32_16x16x32_bf16 v[84:87], v[164:167], v[196:199], v[84:87]
	v_mfma_f32_16x16x32_bf16 v[72:75], v[172:175], v[196:199], v[72:75]
	v_mfma_f32_16x16x32_bf16 v[68:71], v[164:167], v[204:207], v[68:71]
	v_mfma_f32_16x16x32_bf16 v[64:67], v[172:175], v[204:207], v[64:67]
	s_setprio 0
	s_barrier
	s_add_i32 s36, s75, s51
	v_lshl_add_u64 v[152:153], v[152:153], 0, s[4:5]
	s_mov_b32 m0, s36
	ds_read_b128 v[176:179], v159 offset:49152
	ds_read_b128 v[180:183], v159 offset:50176
	ds_read_b128 v[184:187], v159 offset:51200
	ds_read_b128 v[188:191], v159 offset:52224
	ds_read_b128 v[192:195], v159 offset:53248
	ds_read_b128 v[196:199], v159 offset:54272
	ds_read_b128 v[200:203], v159 offset:55296
	ds_read_b128 v[204:207], v159 offset:56320
	global_load_lds_dwordx4 v[152:153], off
	s_add_i32 m0, s36, 0x2000
	s_add_u32 s36, s42, 0x160080
	v_lshl_add_u64 v[152:153], v[208:209], 0, s[4:5]
	s_addc_u32 s37, s43, 0
	s_add_i32 s42, s76, s51
	global_load_lds_dwordx4 v[152:153], off
	v_lshl_add_u64 v[152:153], s[36:37], 0, v[146:147]
	s_mov_b32 m0, s42
	s_nop 0
	global_load_lds_dwordx4 v[152:153], off
	v_lshl_add_u64 v[152:153], s[36:37], 0, v[144:145]
	s_add_i32 m0, s42, 0x2000
	s_nop 0
	global_load_lds_dwordx4 v[152:153], off
	v_lshl_add_u64 v[152:153], v[210:211], 0, s[4:5]
	s_mov_b32 m0, s62
	s_nop 0
	global_load_lds_dwordx4 v[152:153], off
	v_lshl_add_u64 v[152:153], v[212:213], 0, s[4:5]
	s_mov_b32 m0, s63
	s_nop 0
	global_load_lds_dwordx4 v[152:153], off
	s_waitcnt vmcnt(8)
	s_waitcnt lgkmcnt(0)
	s_barrier
	s_setprio 1
	v_mfma_f32_16x16x32_bf16 v[60:63], v[128:131], v[176:179], v[60:63]
	v_mfma_f32_16x16x32_bf16 v[56:59], v[136:139], v[176:179], v[56:59]
	v_mfma_f32_16x16x32_bf16 v[48:51], v[128:131], v[184:187], v[48:51]
	v_mfma_f32_16x16x32_bf16 v[44:47], v[136:139], v[184:187], v[44:47]
	v_mfma_f32_16x16x32_bf16 v[32:35], v[128:131], v[192:195], v[32:35]
	v_mfma_f32_16x16x32_bf16 v[28:31], v[136:139], v[192:195], v[28:31]
	v_mfma_f32_16x16x32_bf16 v[16:19], v[128:131], v[200:203], v[16:19]
	v_mfma_f32_16x16x32_bf16 v[12:15], v[136:139], v[200:203], v[12:15]
	v_mfma_f32_16x16x32_bf16 v[60:63], v[132:135], v[180:183], v[60:63]
	v_mfma_f32_16x16x32_bf16 v[56:59], v[140:143], v[180:183], v[56:59]
	v_mfma_f32_16x16x32_bf16 v[48:51], v[132:135], v[188:191], v[48:51]
	v_mfma_f32_16x16x32_bf16 v[44:47], v[140:143], v[188:191], v[44:47]
	v_mfma_f32_16x16x32_bf16 v[32:35], v[132:135], v[196:199], v[32:35]
	v_mfma_f32_16x16x32_bf16 v[28:31], v[140:143], v[196:199], v[28:31]
	v_mfma_f32_16x16x32_bf16 v[16:19], v[132:135], v[204:207], v[16:19]
	v_mfma_f32_16x16x32_bf16 v[12:15], v[140:143], v[204:207], v[12:15]
	v_mfma_f32_16x16x32_bf16 v[52:55], v[160:163], v[176:179], v[52:55]
	v_mfma_f32_16x16x32_bf16 v[40:43], v[168:171], v[176:179], v[40:43]
	v_mfma_f32_16x16x32_bf16 v[36:39], v[160:163], v[184:187], v[36:39]
	v_mfma_f32_16x16x32_bf16 v[24:27], v[168:171], v[184:187], v[24:27]
	v_mfma_f32_16x16x32_bf16 v[20:23], v[160:163], v[192:195], v[20:23]
	v_mfma_f32_16x16x32_bf16 v[8:11], v[168:171], v[192:195], v[8:11]
	v_mfma_f32_16x16x32_bf16 v[4:7], v[160:163], v[200:203], v[4:7]
	v_mfma_f32_16x16x32_bf16 v[0:3], v[168:171], v[200:203], v[0:3]
	v_mfma_f32_16x16x32_bf16 v[52:55], v[164:167], v[180:183], v[52:55]
	v_mfma_f32_16x16x32_bf16 v[40:43], v[172:175], v[180:183], v[40:43]
	v_mfma_f32_16x16x32_bf16 v[36:39], v[164:167], v[188:191], v[36:39]
	v_mfma_f32_16x16x32_bf16 v[24:27], v[172:175], v[188:191], v[24:27]
	v_mfma_f32_16x16x32_bf16 v[20:23], v[164:167], v[196:199], v[20:23]
	v_mfma_f32_16x16x32_bf16 v[8:11], v[172:175], v[196:199], v[8:11]
	v_mfma_f32_16x16x32_bf16 v[4:7], v[164:167], v[204:207], v[4:7]
	v_mfma_f32_16x16x32_bf16 v[0:3], v[172:175], v[204:207], v[0:3]
	s_setprio 0
	s_barrier
	s_add_i32 s74, s74, 2
	s_add_u32 s72, s72, 0x100
	s_addc_u32 s73, s73, 0
	s_cmpk_gt_u32 s74, 0x55
	s_mov_b64 s[36:37], s[38:39]
	s_cbranch_scc0 .LBB0_1249
	s_and_b64 vcc, exec, s[8:9]
	s_cbranch_vccz .LBB0_1252
	s_barrier
